# rewrite gated-residual epilogue loops in w_out/ffn_out GEMM tiles: batched xin loads, dwordx4 stores instead of dword stores
# speedup vs baseline: 1.0213x; 1.0213x over previous
; DI int otid() { int t = threadIdx.x; asm volatile("" : "+v"(t)); return t; }
; DI void rope_task(const Params& p, int task) {
;   const int tid = otid(), row = task * 8 + (tid >> 5), i = tid & 31;
;   const int pos = ((const int*)p.in[2])[row];
;   const float inv = 1.0f / powf(10000.0f, (float)(2 * i) / 64.0f);
;   const float ang = (float)pos * inv;
;   ((float*)(p.ws + O_COS))[(size_t)row * 32 + i] = cosf(ang);
;   ((float*)(p.ws + O_SIN))[(size_t)row * 32 + i] = sinf(ang);
; __global__ void __launch_bounds__(256, 2) fwd_megakernel(Params p) {
;     ...
;       for (int task = bid; task < CONV_TASKS + 384 + 2048; task += G) {
;         if (task < CONV_TASKS) conv_task(p, 0, task, smem);
;         else if (task < CONV_TASKS + 384) ada_task(p, task - CONV_TASKS, smem);
;         else rope_task(p, task - CONV_TASKS - 384);
.LBB0_39:
	s_cmpk_gt_i32 s28, 0x3e9
	s_mov_b64 s[0:1], -1
	s_cbranch_scc0 .LBB0_60
	s_cmpk_gt_u32 s28, 0x569
	s_cbranch_scc0 .LBB0_50
	v_mov_b32_e32 v0, v216
	s_lshl_b32 s0, s28, 3
	v_and_b32_e32 v4, 31, v0
	v_lshlrev_b32_e32 v5, 1, v4
	s_addk_i32 s0, 0xd4b0
	v_ashrrev_i32_e32 v2, 5, v0
	v_cvt_f32_ubyte0_e32 v5, v5
	v_add_u32_e32 v2, s0, v2
	v_readlane_b32 s44, v246, 1
	v_mul_f32_e32 v5, 0x3c800000, v5
	v_ashrrev_i32_e32 v3, 31, v2
	v_readlane_b32 s48, v246, 5
	v_readlane_b32 s49, v246, 6
	v_cmp_eq_f32_e32 vcc, 0, v5
	s_mov_b32 s0, 0x3f2aaaab
	v_lshl_add_u64 v[6:7], v[2:3], 2, s[48:49]
	v_cndmask_b32_e64 v16, v225, 1.0, vcc
	global_load_dword v0, v[6:7], off
	v_frexp_mant_f32_e32 v6, v16
	v_cmp_gt_f32_e32 vcc, s0, v6
	s_mov_b32 s1, 0x3f2aaaaa
	s_mov_b32 s24, 0x42b17218
	v_cndmask_b32_e64 v7, 1.0, 2.0, vcc
	v_mul_f32_e32 v6, v6, v7
	v_add_f32_e32 v9, 1.0, v6
	v_rcp_f32_e32 v14, v9
	v_add_f32_e32 v7, -1.0, v9
	v_sub_f32_e32 v11, v6, v7
	v_add_f32_e32 v7, -1.0, v6
	v_mul_f32_e32 v15, v7, v14
	v_mul_f32_e32 v8, v9, v15
	v_fma_f32 v10, v15, v9, -v8
	v_fmac_f32_e32 v10, v15, v11
	v_add_f32_e32 v6, v8, v10
	v_sub_f32_e32 v9, v7, v6
	v_pk_add_f32 v[12:13], v[6:7], v[8:9] neg_lo:[0,1] neg_hi:[0,1]
	v_mov_b32_e32 v11, v6
	v_pk_add_f32 v[6:7], v[12:13], v[10:11] neg_lo:[0,1] neg_hi:[0,1]
	s_mov_b32 s9, 0x7f800000
	v_add_f32_e32 v6, v6, v7
	v_add_f32_e32 v6, v9, v6
	v_mul_f32_e32 v7, v14, v6
	v_add_f32_e32 v6, v15, v7
	v_sub_f32_e32 v8, v6, v15
	v_sub_f32_e32 v17, v7, v8
	v_mul_f32_e32 v7, v6, v6
	v_fma_f32 v9, v6, v6, -v7
	v_add_f32_e32 v8, v17, v17
	v_fmac_f32_e32 v9, v6, v8
	v_add_f32_e32 v8, v7, v9
	v_fmamk_f32 v10, v8, 0x3e76c4e1, v217
	v_fmaak_f32 v10, v8, v10, 0x3ecccdef
	v_sub_f32_e32 v7, v8, v7
	v_sub_f32_e32 v18, v9, v7
	v_mul_f32_e32 v7, v8, v10
	v_fma_f32 v182, v8, v10, -v7
	v_fmac_f32_e32 v182, v18, v10
	v_add_f32_e32 v11, v7, v182
	v_sub_f32_e32 v10, v11, v7
	v_pk_add_f32 v[12:13], v[182:183], v[10:11] neg_lo:[0,1] neg_hi:[0,1]
	v_pk_add_f32 v[14:15], v[10:11], s[0:1]
	s_mov_b32 s0, 0x31739010
	v_mov_b32_e32 v13, v15
	s_mov_b32 s1, 0xbf2aaaaa
	v_pk_add_f32 v[12:13], v[12:13], s[0:1]
	s_mov_b32 s0, 0x3f317218
	v_sub_f32_e32 v9, v11, v13
	v_mov_b32_e32 v7, v12
	v_pk_mul_f32 v[10:11], v[6:7], v[8:9]
	v_pk_add_f32 v[12:13], v[12:13], v[8:9] op_sel_hi:[0,1]
	v_fma_f32 v14, v8, v6, -v10
	v_fmac_f32_e32 v14, v8, v17
	v_mov_b32_e32 v11, v13
	v_fmac_f32_e32 v14, v18, v6
	v_pk_add_f32 v[8:9], v[10:11], v[14:15]
	v_ldexp_f32 v18, v17, 1
	v_sub_f32_e32 v7, v8, v10
	v_sub_f32_e32 v10, v15, v9
	v_sub_f32_e32 v7, v14, v7
	v_add_f32_e32 v14, v13, v10
	v_pk_mul_f32 v[10:11], v[8:9], v[8:9] op_sel:[0,1] op_sel_hi:[1,0]
	v_cvt_f64_f32_e32 v[12:13], v16
	v_frexp_exp_i32_f64_e32 v11, v[12:13]
	v_subbrev_co_u32_e32 v11, vcc, 0, v11, vcc
	v_cvt_f32_i32_e32 v11, v11
	v_fma_f32 v12, v8, v9, -v10
	v_fmac_f32_e32 v12, v8, v14
	v_fmac_f32_e32 v12, v7, v9
	v_mul_f32_e32 v8, 0x3f317218, v11
	v_fma_f32 v14, v11, s0, -v8
	v_fmac_f32_e32 v14, 0xb102e308, v11
	v_ldexp_f32 v15, v6, 1
	v_add_f32_e32 v9, v10, v12
	v_pk_add_f32 v[6:7], v[8:9], v[14:15]
	v_mov_b32_e32 v16, v9
	v_mov_b32_e32 v17, v7
	v_mov_b32_e32 v11, v15
	v_pk_add_f32 v[10:11], v[16:17], v[10:11] neg_lo:[0,1] neg_hi:[0,1]
	v_mov_b32_e32 v13, v9
	v_pk_add_f32 v[10:11], v[12:13], v[10:11] neg_lo:[0,1] neg_hi:[0,1]
	v_mov_b32_e32 v15, v6
	v_add_f32_e32 v9, v18, v10
	v_add_f32_e32 v9, v9, v11
	v_pk_add_f32 v[10:11], v[6:7], v[8:9] neg_lo:[0,1] neg_hi:[0,1]
	v_pk_add_f32 v[12:13], v[6:7], v[8:9]
	v_mov_b32_e32 v8, v9
	v_mov_b32_e32 v11, v13
	v_pk_add_f32 v[16:17], v[14:15], v[10:11] neg_lo:[0,1] neg_hi:[0,1]
	v_pk_add_f32 v[10:11], v[14:15], v[10:11]
	v_mov_b32_e32 v9, v6
	v_pk_add_f32 v[14:15], v[10:11], v[6:7] op_sel:[1,0] op_sel_hi:[0,1] neg_lo:[0,1] neg_hi:[0,1]
	v_pk_add_f32 v[18:19], v[12:13], v[14:15] op_sel_hi:[1,0] neg_lo:[0,1] neg_hi:[0,1]
	v_mov_b32_e32 v12, v13
	v_mov_b32_e32 v13, v11
	v_pk_mov_b32 v[14:15], v[6:7], v[14:15] op_sel:[1,0]
	v_mov_b32_e32 v18, v16
	v_pk_add_f32 v[12:13], v[12:13], v[14:15] neg_lo:[0,1] neg_hi:[0,1]
	v_mov_b32_e32 v17, v11
	v_pk_add_f32 v[6:7], v[8:9], v[12:13] neg_lo:[0,1] neg_hi:[0,1]
	s_movk_i32 s1, 0x204
	v_pk_add_f32 v[8:9], v[18:19], v[6:7]
	s_mov_b32 s0, 0xc2ce8ed0
	v_pk_add_f32 v[12:13], v[8:9], v[8:9] op_sel:[0,1] op_sel_hi:[1,0]
	s_waitcnt vmcnt(0)
	v_cvt_f32_i32_e32 v0, v0
	v_pk_add_f32 v[10:11], v[10:11], v[12:13] op_sel:[1,0] op_sel_hi:[0,1]
	v_mov_b32_e32 v9, v10
	v_pk_add_f32 v[14:15], v[8:9], v[16:17] neg_lo:[0,1] neg_hi:[0,1]
	v_mov_b32_e32 v7, v12
	v_sub_f32_e32 v8, v8, v14
	v_pk_add_f32 v[6:7], v[6:7], v[14:15] neg_lo:[0,1] neg_hi:[0,1]
	v_sub_f32_e32 v8, v16, v8
	v_add_f32_e32 v6, v6, v8
	v_add_f32_e32 v6, v6, v7
	v_add_f32_e32 v7, v10, v6
	v_sub_f32_e32 v8, v7, v10
	v_sub_f32_e32 v6, v6, v8
	v_mul_f32_e32 v8, v5, v7
	v_fma_f32 v7, v5, v7, -v8
	v_fmac_f32_e32 v7, v5, v6
	v_add_f32_e32 v6, v8, v7
	v_cmp_class_f32_e64 vcc, v8, s1
	v_sub_f32_e32 v9, v6, v8
	v_sub_f32_e32 v7, v7, v9
	v_cndmask_b32_e32 v6, v6, v8, vcc
	v_cmp_eq_f32_e32 vcc, s24, v6
	v_readlane_b32 s45, v246, 2
	v_readlane_b32 s46, v246, 3
	v_cndmask_b32_e32 v8, 0, v226, vcc
	v_sub_f32_e32 v9, v6, v8
	v_mul_f32_e32 v10, 0x3fb8aa3b, v9
	v_fma_f32 v11, v9, s18, -v10
	v_rndne_f32_e32 v12, v10
	v_fmac_f32_e32 v11, 0x32a5705f, v9
	v_sub_f32_e32 v10, v10, v12
	v_add_f32_e32 v10, v10, v11
	v_exp_f32_e32 v10, v10
	v_cvt_i32_f32_e32 v11, v12
	v_cmp_neq_f32_e64 vcc, |v6|, s9
	v_readlane_b32 s47, v246, 4
	v_readlane_b32 s50, v246, 7
	v_cndmask_b32_e32 v6, 0, v7, vcc
	v_ldexp_f32 v7, v10, v11
	v_cmp_ngt_f32_e32 vcc, s0, v9
	v_add_f32_e32 v6, v8, v6
	v_readlane_b32 s51, v246, 8
	v_cndmask_b32_e32 v7, 0, v7, vcc
	v_cmp_nlt_f32_e32 vcc, s24, v9
	v_readlane_b32 s52, v246, 9
	v_readlane_b32 s53, v246, 10
	v_cndmask_b32_e32 v7, v227, v7, vcc
	v_fma_f32 v6, v7, v6, v7
	v_cmp_class_f32_e64 vcc, v7, s1
	v_readlane_b32 s54, v246, 11
	v_readlane_b32 s55, v246, 12
	v_cndmask_b32_e32 v6, v6, v7, vcc
	v_and_b32_e32 v7, 0x7fffffff, v6
	v_div_scale_f32 v8, s[0:1], v7, v7, 1.0
	v_rcp_f32_e32 v9, v8
	v_div_scale_f32 v7, vcc, 1.0, v7, 1.0
	s_brev_b32 s0, 18
	v_fma_f32 v10, -v8, v9, 1.0
	v_fmac_f32_e32 v9, v10, v9
	v_mul_f32_e32 v10, v7, v9
	v_fma_f32 v11, -v8, v10, v7
	v_fmac_f32_e32 v10, v11, v9
	v_fma_f32 v7, -v8, v10, v7
	v_div_fmas_f32 v7, v7, v9, v10
	v_div_fixup_f32 v6, v7, |v6|, 1.0
	v_cmp_neq_f32_e32 vcc, s9, v5
	v_readlane_b32 s56, v246, 13
	v_readlane_b32 s57, v246, 14
	v_cndmask_b32_e32 v5, 0, v6, vcc
	v_mul_f32_e32 v5, v5, v0
	v_and_b32_e32 v6, 0x7fffffff, v5
	v_lshrrev_b32_e32 v0, 23, v6
	v_and_b32_e32 v7, 0x7fffff, v6
	v_cmp_nlt_f32_e64 s[24:25], |v5|, s0
	v_add_u32_e32 v8, 0xffffff88, v0
	v_or_b32_e32 v7, 0x800000, v7
	v_readlane_b32 s58, v246, 15
	v_readlane_b32 s59, v246, 16
	s_and_saveexec_b64 s[0:1], s[24:25]
	s_xor_b64 s[26:27], exec, s[0:1]
	s_cbranch_execz .LBB0_43
; DI void rope_task(const Params& p, int task) {
;     ...
;   const float ang = (float)pos * inv;
;   ((float*)(p.ws + O_COS))[(size_t)row * 32 + i] = cosf(ang);
;   ((float*)(p.ws + O_SIN))[(size_t)row * 32 + i] = sinf(ang);
	v_cmp_lt_u32_e32 vcc, 63, v8
	s_mov_b32 s9, 0xfe5163ab
	v_mad_u64_u32 v[10:11], s[42:43], v7, s9, 0
	v_cndmask_b32_e32 v0, 0, v228, vcc
	v_add_u32_e32 v0, v0, v8
	v_cmp_lt_u32_e64 s[0:1], 31, v0
	s_mov_b32 s9, 0x3c439041
	s_nop 0
	v_cndmask_b32_e64 v9, 0, v229, s[0:1]
	v_add_u32_e32 v0, v9, v0
	v_cmp_lt_u32_e64 s[36:37], 31, v0
	s_nop 1
	v_cndmask_b32_e64 v9, 0, v229, s[36:37]
	v_add_u32_e32 v9, v9, v0
	v_mov_b32_e32 v0, v11
	v_mad_u64_u32 v[12:13], s[42:43], v7, s9, v[0:1]
	v_mov_b32_e32 v0, v13
	s_mov_b32 s9, 0xdb629599
	v_mad_u64_u32 v[14:15], s[42:43], v7, s9, v[0:1]
	v_mov_b32_e32 v0, v15
	s_mov_b32 s9, 0xf534ddc0
	v_mad_u64_u32 v[16:17], s[42:43], v7, s9, v[0:1]
	v_mov_b32_e32 v0, v17
	s_mov_b32 s9, 0xfc2757d1
	v_mad_u64_u32 v[18:19], s[42:43], v7, s9, v[0:1]
	v_mov_b32_e32 v0, v19
	s_mov_b32 s9, 0x4e441529
	v_mad_u64_u32 v[20:21], s[42:43], v7, s9, v[0:1]
	v_mov_b32_e32 v0, v21
	s_mov_b32 s9, 0xa2f9836e
	v_mad_u64_u32 v[22:23], s[42:43], v7, s9, v[0:1]
	v_cndmask_b32_e32 v11, v20, v16, vcc
	v_cndmask_b32_e32 v0, v22, v18, vcc
	v_cndmask_b32_e32 v15, v23, v20, vcc
	v_cndmask_b32_e64 v13, v0, v11, s[0:1]
	v_cndmask_b32_e64 v0, v15, v0, s[0:1]
	v_cndmask_b32_e32 v15, v18, v14, vcc
	v_cndmask_b32_e64 v11, v11, v15, s[0:1]
	v_sub_u32_e32 v17, 32, v9
	v_cmp_eq_u32_e64 s[42:43], 0, v9
	v_cndmask_b32_e32 v9, v16, v12, vcc
	v_cndmask_b32_e64 v0, v0, v13, s[36:37]
	v_cndmask_b32_e64 v13, v13, v11, s[36:37]
	v_cndmask_b32_e64 v12, v15, v9, s[0:1]
	v_alignbit_b32 v18, v0, v13, v17
	v_cndmask_b32_e64 v11, v11, v12, s[36:37]
	v_cndmask_b32_e64 v0, v18, v0, s[42:43]
	v_alignbit_b32 v15, v13, v11, v17
	v_cndmask_b32_e32 v10, v14, v10, vcc
	v_cndmask_b32_e64 v13, v15, v13, s[42:43]
	v_bfe_u32 v18, v0, 29, 1
	v_cndmask_b32_e64 v9, v9, v10, s[0:1]
	v_alignbit_b32 v15, v0, v13, 30
	v_sub_u32_e32 v19, 0, v18
	v_cndmask_b32_e64 v9, v12, v9, s[36:37]
	v_xor_b32_e32 v15, v15, v19
	v_alignbit_b32 v10, v11, v9, v17
	v_cndmask_b32_e64 v10, v10, v11, s[42:43]
	v_ffbh_u32_e32 v12, v15
	v_alignbit_b32 v11, v13, v10, 30
	v_min_u32_e32 v12, 32, v12
	v_alignbit_b32 v9, v10, v9, 30
	v_xor_b32_e32 v11, v11, v19
	v_sub_u32_e32 v13, 31, v12
	v_xor_b32_e32 v9, v9, v19
	v_alignbit_b32 v14, v15, v11, v13
	v_alignbit_b32 v9, v11, v9, v13
	v_alignbit_b32 v10, v14, v9, 9
	v_ffbh_u32_e32 v11, v10
	v_min_u32_e32 v11, 32, v11
	v_lshrrev_b32_e32 v16, 29, v0
	v_not_b32_e32 v13, v11
	v_alignbit_b32 v9, v10, v9, v13
	v_lshlrev_b32_e32 v10, 31, v16
	v_or_b32_e32 v13, 0x33000000, v10
	v_add_lshl_u32 v11, v11, v12, 23
	v_lshrrev_b32_e32 v9, 9, v9
	v_sub_u32_e32 v11, v13, v11
	v_or_b32_e32 v10, 0.5, v10
	v_lshlrev_b32_e32 v12, 23, v12
	v_or_b32_e32 v9, v11, v9
	v_lshrrev_b32_e32 v11, 9, v14
	v_sub_u32_e32 v10, v10, v12
	v_or_b32_e32 v10, v11, v10
	v_mul_f32_e32 v11, 0x3fc90fda, v10
	s_mov_b32 s0, 0x3fc90fda
	v_fma_f32 v12, v10, s0, -v11
	v_fmac_f32_e32 v12, 0x33a22168, v10
	v_fmac_f32_e32 v12, 0x3fc90fda, v9
	v_lshrrev_b32_e32 v0, 30, v0
	v_add_f32_e32 v10, v11, v12
	v_add_u32_e32 v9, v18, v0

; #define MFMA32(a, b, c) __builtin_amdgcn_mfma_f32_32x32x16_bf16((a), (b), (c), 0, 0, 0)
; DI void gemm_mainloop_big(const bf16_t* __restrict__ A, int lda, const bf16_t* __restrict__ Bt, int ldb, int K, int m0, int n0,
;                           f32x16 (&acc)[4][2], char* smem) {
;     ...
;   for (int kt = 0; kt < nk; ++kt) {
;     if (kt + 1 < nk) {
; #pragma unroll
;       for (int i = 0; i < 8; ++i) ra[i] = *(const u32x4*)(ap + (size_t)(32 * i) * lda + (kt + 1) * 64);
; #pragma unroll
;       for (int i = 0; i < 4; ++i) rb[i] = *(const u32x4*)(bp + (size_t)(32 * i) * ldb + (kt + 1) * 64);
;     }
; #pragma unroll
;     for (int ks = 0; ks < 4; ++ks) {
;       bf16x8 af[4], bfr[2];
; #pragma unroll
;       for (int f = 0; f < 4; ++f) af[f] = *(const bf16x8*)&sa[wm * 128 + f * 32 + r][ks * 16 + half * 8];
; #pragma unroll
;       for (int f = 0; f < 2; ++f) bfr[f] = *(const bf16x8*)&sb[wn * 64 + f * 32 + r][ks * 16 + half * 8];
; #pragma unroll
;       for (int mf = 0; mf < 4; ++mf)
; #pragma unroll
;         for (int nf = 0; nf < 2; ++nf) acc[mf][nf] = MFMA32(af[mf], bfr[nf], acc[mf][nf]);
;     }
.LBB0_333:
	ds_read_b128 v[130:133], v0
	ds_read_b128 v[134:137], v139 offset:36864
	ds_read_b128 v[144:147], v0 offset:32
	ds_read_b128 v[148:151], v139 offset:36896
	ds_read_b128 v[152:155], v139 offset:41472
	ds_read_b128 v[156:159], v139 offset:41504
	v_lshl_add_u64 v[172:173], v[142:143], 0, s[26:27]
	s_waitcnt lgkmcnt(4)
	v_mfma_f32_32x32x16_bf16 v[114:129], v[130:133], v[134:137], v[114:129]
	s_waitcnt lgkmcnt(1)
	v_mfma_f32_32x32x16_bf16 v[98:113], v[130:133], v[152:155], v[98:113]
	ds_read_b128 v[130:133], v0 offset:4608
	ds_read_b128 v[160:163], v0 offset:4640
	s_waitcnt lgkmcnt(1)
	v_mfma_f32_32x32x16_bf16 v[82:97], v[130:133], v[134:137], v[82:97]
	v_mfma_f32_32x32x16_bf16 v[66:81], v[130:133], v[152:155], v[66:81]
	ds_read_b128 v[130:133], v0 offset:9216
	ds_read_b128 v[164:167], v0 offset:9248
	s_waitcnt lgkmcnt(1)
	v_mfma_f32_32x32x16_bf16 v[50:65], v[130:133], v[134:137], v[50:65]
	v_mfma_f32_32x32x16_bf16 v[34:49], v[130:133], v[152:155], v[34:49]
	ds_read_b128 v[130:133], v0 offset:13824
	ds_read_b128 v[168:171], v0 offset:13856
	s_waitcnt lgkmcnt(1)
	v_mfma_f32_32x32x16_bf16 v[18:33], v[130:133], v[134:137], v[18:33]
	v_mfma_f32_32x32x16_bf16 v[2:17], v[130:133], v[152:155], v[2:17]
	v_mfma_f32_32x32x16_bf16 v[114:129], v[144:147], v[148:151], v[114:129]
	v_mfma_f32_32x32x16_bf16 v[98:113], v[144:147], v[156:159], v[98:113]
	v_mfma_f32_32x32x16_bf16 v[82:97], v[160:163], v[148:151], v[82:97]
	v_mfma_f32_32x32x16_bf16 v[66:81], v[160:163], v[156:159], v[66:81]
	v_mfma_f32_32x32x16_bf16 v[50:65], v[164:167], v[148:151], v[50:65]
	v_mfma_f32_32x32x16_bf16 v[34:49], v[164:167], v[156:159], v[34:49]
	s_waitcnt lgkmcnt(0)
	v_mfma_f32_32x32x16_bf16 v[18:33], v[168:171], v[148:151], v[18:33]
	ds_read_b128 v[134:137], v0 offset:64
	ds_read_b128 v[144:147], v139 offset:36928
	ds_read_b128 v[148:151], v0 offset:96
	ds_read_b128 v[152:155], v139 offset:36960
	v_mfma_f32_32x32x16_bf16 v[2:17], v[168:171], v[156:159], v[2:17]
	ds_read_b128 v[156:159], v139 offset:41536
	ds_read_b128 v[130:133], v139 offset:41568
	s_waitcnt lgkmcnt(4)
	v_mfma_f32_32x32x16_bf16 v[114:129], v[134:137], v[144:147], v[114:129]
	s_waitcnt lgkmcnt(1)
	v_mfma_f32_32x32x16_bf16 v[98:113], v[134:137], v[156:159], v[98:113]
	ds_read_b128 v[134:137], v0 offset:4672
	ds_read_b128 v[160:163], v0 offset:4704
	s_waitcnt lgkmcnt(1)
	v_mfma_f32_32x32x16_bf16 v[82:97], v[134:137], v[144:147], v[82:97]
	v_mfma_f32_32x32x16_bf16 v[66:81], v[134:137], v[156:159], v[66:81]
	ds_read_b128 v[134:137], v0 offset:9280
	ds_read_b128 v[164:167], v0 offset:9312
	s_waitcnt lgkmcnt(1)
	v_mfma_f32_32x32x16_bf16 v[50:65], v[134:137], v[144:147], v[50:65]
	v_mfma_f32_32x32x16_bf16 v[34:49], v[134:137], v[156:159], v[34:49]
	ds_read_b128 v[168:171], v0 offset:13888
	ds_read_b128 v[134:137], v0 offset:13920
	s_waitcnt lgkmcnt(1)
	v_mfma_f32_32x32x16_bf16 v[18:33], v[168:171], v[144:147], v[18:33]
	v_lshl_add_u64 v[144:145], v[140:141], 0, s[26:27]
	v_add_co_u32_e32 v174, vcc, s87, v144
	s_add_u32 s26, s26, 0x80
	s_nop 0
	v_addc_co_u32_e32 v175, vcc, 0, v145, vcc
	s_addc_u32 s27, s27, 0
	v_mfma_f32_32x32x16_bf16 v[2:17], v[168:171], v[156:159], v[2:17]
	v_add_co_u32_e32 v156, vcc, s2, v144
	s_cmpk_lg_i32 s26, 0x780
	s_nop 0
	v_addc_co_u32_e32 v157, vcc, 0, v145, vcc
	v_add_co_u32_e32 v168, vcc, s3, v144
	v_mfma_f32_32x32x16_bf16 v[114:129], v[148:151], v[152:155], v[114:129]
	s_nop 0
	v_addc_co_u32_e32 v169, vcc, 0, v145, vcc
	v_add_co_u32_e32 v170, vcc, s88, v144
	s_nop 1
	v_addc_co_u32_e32 v171, vcc, 0, v145, vcc
	v_add_co_u32_e32 v176, vcc, s89, v144
	v_mfma_f32_32x32x16_bf16 v[98:113], v[148:151], v[130:133], v[98:113]
	s_nop 0
	v_addc_co_u32_e32 v177, vcc, 0, v145, vcc
	v_add_co_u32_e32 v178, vcc, s4, v144
	s_nop 1
	v_addc_co_u32_e32 v179, vcc, 0, v145, vcc
	v_add_co_u32_e32 v180, vcc, s5, v144
	v_mfma_f32_32x32x16_bf16 v[82:97], v[160:163], v[152:155], v[82:97]
	s_nop 0
	v_addc_co_u32_e32 v181, vcc, 0, v145, vcc
	v_add_co_u32_e32 v186, vcc, s86, v144
	s_nop 1
	v_addc_co_u32_e32 v187, vcc, 0, v145, vcc
	v_add_co_u32_e32 v190, vcc, s34, v172
	global_load_dwordx4 v[144:147], v[172:173], off offset:128
	s_nop 0
	v_addc_co_u32_e32 v191, vcc, 0, v173, vcc
	v_add_co_u32_e32 v194, vcc, s35, v172
	v_mfma_f32_32x32x16_bf16 v[66:81], v[160:163], v[130:133], v[66:81]
	s_nop 0
	v_addc_co_u32_e32 v195, vcc, 0, v173, vcc
	v_add_co_u32_e32 v198, vcc, s17, v172
	global_load_dwordx4 v[148:151], v[174:175], off offset:128
	s_nop 0
	global_load_dwordx4 v[156:159], v[156:157], off offset:128
	s_nop 0
	global_load_dwordx4 v[160:163], v[168:169], off offset:128
	v_addc_co_u32_e32 v199, vcc, 0, v173, vcc
	v_mfma_f32_32x32x16_bf16 v[50:65], v[164:167], v[152:155], v[50:65]
	v_mfma_f32_32x32x16_bf16 v[34:49], v[164:167], v[130:133], v[34:49]
	global_load_dwordx4 v[164:167], v[170:171], off offset:128
	s_nop 0
	global_load_dwordx4 v[168:171], v[176:177], off offset:128
	global_load_dwordx4 v[172:175], v[178:179], off offset:128
	s_nop 0
	global_load_dwordx4 v[176:179], v[180:181], off offset:128
	s_nop 0
	global_load_dwordx4 v[186:189], v[186:187], off offset:128
	s_nop 0
	global_load_dwordx4 v[190:193], v[190:191], off offset:128
	s_nop 0
	global_load_dwordx4 v[194:197], v[194:195], off offset:128
	s_waitcnt lgkmcnt(0)
	v_mfma_f32_32x32x16_bf16 v[18:33], v[134:137], v[152:155], v[18:33]
	global_load_dwordx4 v[152:155], v[198:199], off offset:128
	s_barrier
; #define MFMA32(a, b, c) __builtin_amdgcn_mfma_f32_32x32x16_bf16((a), (b), (c), 0, 0, 0)
; DI void gemm_mainloop_big(const bf16_t* __restrict__ A, int lda, const bf16_t* __restrict__ Bt, int ldb, int K, int m0, int n0,
;                           f32x16 (&acc)[4][2], char* smem) {
;     ...
; #pragma unroll
;     for (int ks = 0; ks < 4; ++ks) {
;       bf16x8 af[4], bfr[2];
; #pragma unroll
;       for (int f = 0; f < 4; ++f) af[f] = *(const bf16x8*)&sa[wm * 128 + f * 32 + r][ks * 16 + half * 8];
; #pragma unroll
;       for (int f = 0; f < 2; ++f) bfr[f] = *(const bf16x8*)&sb[wn * 64 + f * 32 + r][ks * 16 + half * 8];
; #pragma unroll
;       for (int mf = 0; mf < 4; ++mf)
; #pragma unroll
;         for (int nf = 0; nf < 2; ++nf) acc[mf][nf] = MFMA32(af[mf], bfr[nf], acc[mf][nf]);
;     }
;     __syncthreads();
;     if (kt + 1 < nk) {
; #pragma unroll
;       for (int i = 0; i < 8; ++i) *(u32x4*)&sa[(tid >> 3) + 32 * i][(tid & 7) * 8] = ra[i];
; #pragma unroll
;       for (int i = 0; i < 4; ++i) *(u32x4*)&sb[(tid >> 3) + 32 * i][(tid & 7) * 8] = rb[i];
;     }
;     __syncthreads();
	s_waitcnt vmcnt(11)
	ds_write_b128 v138, v[144:147] offset:36864
	s_waitcnt vmcnt(10)
	ds_write_b128 v138, v[148:151]
	s_waitcnt vmcnt(9)
	ds_write_b128 v138, v[156:159] offset:4608
	s_waitcnt vmcnt(8)
	ds_write_b128 v138, v[160:163] offset:9216
	s_waitcnt vmcnt(7)
	ds_write_b128 v138, v[164:167] offset:13824
	s_waitcnt vmcnt(6)
	ds_write_b128 v138, v[168:171] offset:18432
	s_waitcnt vmcnt(5)
	ds_write_b128 v138, v[172:175] offset:23040
	s_waitcnt vmcnt(4)
	ds_write_b128 v138, v[176:179] offset:27648
	s_waitcnt vmcnt(3)
	ds_write_b128 v138, v[186:189] offset:32256
	s_waitcnt vmcnt(2)
	ds_write_b128 v138, v[190:193] offset:41472
	s_waitcnt vmcnt(1)
	ds_write_b128 v138, v[194:197] offset:46080
	s_waitcnt vmcnt(0)
	ds_write_b128 v138, v[152:155] offset:50688
	v_mfma_f32_32x32x16_bf16 v[2:17], v[134:137], v[130:133], v[2:17]
	s_waitcnt lgkmcnt(0)
	s_barrier
	s_cbranch_scc1 .LBB0_333
	ds_read_b128 v[130:133], v0
	ds_read_b128 v[134:137], v139 offset:36864
	ds_read_b128 v[140:143], v139 offset:41472
	s_waitcnt lgkmcnt(1)
	v_mfma_f32_32x32x16_bf16 v[114:129], v[130:133], v[134:137], v[114:129]
	s_waitcnt lgkmcnt(0)
	v_mfma_f32_32x32x16_bf16 v[98:113], v[130:133], v[140:143], v[98:113]
	ds_read_b128 v[130:133], v0 offset:4608
	s_waitcnt lgkmcnt(0)
	v_mfma_f32_32x32x16_bf16 v[82:97], v[130:133], v[134:137], v[82:97]
	v_mfma_f32_32x32x16_bf16 v[66:81], v[130:133], v[140:143], v[66:81]
	ds_read_b128 v[130:133], v0 offset:9216
	s_waitcnt lgkmcnt(0)
	v_mfma_f32_32x32x16_bf16 v[50:65], v[130:133], v[134:137], v[50:65]
	v_mfma_f32_32x32x16_bf16 v[34:49], v[130:133], v[140:143], v[34:49]
	ds_read_b128 v[130:133], v0 offset:13824
	s_waitcnt lgkmcnt(0)
	v_mfma_f32_32x32x16_bf16 v[18:33], v[130:133], v[134:137], v[18:33]
	v_mfma_f32_32x32x16_bf16 v[2:17], v[130:133], v[140:143], v[2:17]
	ds_read_b128 v[130:133], v0 offset:32
	ds_read_b128 v[134:137], v139 offset:36896
	ds_read_b128 v[140:143], v139 offset:41504
	s_waitcnt lgkmcnt(1)
	v_mfma_f32_32x32x16_bf16 v[114:129], v[130:133], v[134:137], v[114:129]
	s_waitcnt lgkmcnt(0)
	v_mfma_f32_32x32x16_bf16 v[98:113], v[130:133], v[140:143], v[98:113]
	ds_read_b128 v[130:133], v0 offset:4640
	s_waitcnt lgkmcnt(0)
	v_mfma_f32_32x32x16_bf16 v[82:97], v[130:133], v[134:137], v[82:97]
	v_mfma_f32_32x32x16_bf16 v[66:81], v[130:133], v[140:143], v[66:81]
	ds_read_b128 v[130:133], v0 offset:9248
	s_waitcnt lgkmcnt(0)
	v_mfma_f32_32x32x16_bf16 v[50:65], v[130:133], v[134:137], v[50:65]
	v_mfma_f32_32x32x16_bf16 v[34:49], v[130:133], v[140:143], v[34:49]
	ds_read_b128 v[130:133], v0 offset:13856
	s_waitcnt lgkmcnt(0)
	v_mfma_f32_32x32x16_bf16 v[18:33], v[130:133], v[134:137], v[18:33]
	v_mfma_f32_32x32x16_bf16 v[2:17], v[130:133], v[140:143], v[2:17]
	ds_read_b128 v[130:133], v0 offset:64
	ds_read_b128 v[134:137], v139 offset:36928
	ds_read_b128 v[140:143], v139 offset:41536
	s_waitcnt lgkmcnt(1)
	v_mfma_f32_32x32x16_bf16 v[114:129], v[130:133], v[134:137], v[114:129]
	s_waitcnt lgkmcnt(0)
	v_mfma_f32_32x32x16_bf16 v[98:113], v[130:133], v[140:143], v[98:113]
	ds_read_b128 v[130:133], v0 offset:4672
	s_waitcnt lgkmcnt(0)
	v_mfma_f32_32x32x16_bf16 v[82:97], v[130:133], v[134:137], v[82:97]
	v_mfma_f32_32x32x16_bf16 v[66:81], v[130:133], v[140:143], v[66:81]
	ds_read_b128 v[130:133], v0 offset:9280
	s_waitcnt lgkmcnt(0)
	v_mfma_f32_32x32x16_bf16 v[50:65], v[130:133], v[134:137], v[50:65]
	v_mfma_f32_32x32x16_bf16 v[34:49], v[130:133], v[140:143], v[34:49]
	ds_read_b128 v[130:133], v0 offset:13888
	s_waitcnt lgkmcnt(0)
	v_mfma_f32_32x32x16_bf16 v[18:33], v[130:133], v[134:137], v[18:33]
	v_mfma_f32_32x32x16_bf16 v[2:17], v[130:133], v[140:143], v[2:17]
	ds_read_b128 v[130:133], v0 offset:96
	ds_read_b128 v[134:137], v139 offset:36960
	ds_read_b128 v[138:141], v139 offset:41568
	s_waitcnt lgkmcnt(1)
	v_mfma_f32_32x32x16_bf16 v[114:129], v[130:133], v[134:137], v[114:129]
	s_waitcnt lgkmcnt(0)
	v_mfma_f32_32x32x16_bf16 v[98:113], v[130:133], v[138:141], v[98:113]
	ds_read_b128 v[130:133], v0 offset:4704
	s_waitcnt lgkmcnt(0)
	v_mfma_f32_32x32x16_bf16 v[82:97], v[130:133], v[134:137], v[82:97]
	v_mfma_f32_32x32x16_bf16 v[66:81], v[130:133], v[138:141], v[66:81]
	ds_read_b128 v[130:133], v0 offset:9312
	s_waitcnt lgkmcnt(0)
	v_mfma_f32_32x32x16_bf16 v[50:65], v[130:133], v[134:137], v[50:65]
	v_mfma_f32_32x32x16_bf16 v[34:49], v[130:133], v[138:141], v[34:49]
	ds_read_b128 v[130:133], v0 offset:13920
	v_mov_b32_e32 v0, v216
	s_waitcnt lgkmcnt(0)
	s_barrier
	s_barrier
	v_mfma_f32_32x32x16_bf16 v[18:33], v[130:133], v[134:137], v[18:33]
	s_nop 0
	v_cmp_gt_u32_e32 vcc, s31, v0
	v_mfma_f32_32x32x16_bf16 v[2:17], v[130:133], v[138:141], v[2:17]
	s_and_saveexec_b64 s[26:27], vcc
	s_cbranch_execz .LBB0_336
; DI int crow(int i, int h) { return (i & 3) + 8 * (i >> 2) + 4 * h; }
; DI void stage_half(float* st, const f32x16 (&acc)[4][2], int h, int tid) {
;   const int lane = tid & 63, w = tid >> 6, wm = w >> 1, wn = w & 1, c = lane & 31, half = lane >> 5;
;   if (wm == h) {
; #pragma unroll
;     for (int mf = 0; mf < 4; ++mf)
; #pragma unroll
;       for (int nf = 0; nf < 2; ++nf)
; #pragma unroll
;         for (int i = 0; i < 16; ++i) st[(mf * 32 + crow(i, half)) * 132 + wn * 64 + nf * 32 + c] = acc[mf][nf][i];
;   }
	v_lshrrev_b32_e32 v130, 3, v0
	v_and_b32_e32 v130, 4, v130
	v_and_b32_e32 v0, 0x5f, v0
	v_mul_u32_u24_e32 v130, 0x210, v130
	v_lshl_add_u32 v0, v0, 2, v130
	v_add_u32_e32 v130, 0x400, v0
	ds_write2_b32 v0, v114, v98 offset1:32
	ds_write2_b32 v0, v115, v99 offset0:132 offset1:164
	ds_write2_b32 v130, v116, v100 offset0:8 offset1:40
	ds_write2_b32 v130, v117, v101 offset0:140 offset1:172
	v_add_u32_e32 v130, 0x1000, v0
	ds_write2_b32 v130, v118, v102 offset0:32 offset1:64
	ds_write2_b32 v130, v119, v103 offset0:164 offset1:196
	v_add_u32_e32 v130, 0x1400, v0
	ds_write2_b32 v130, v120, v104 offset0:40 offset1:72
	ds_write2_b32 v130, v121, v105 offset0:172 offset1:204
	v_add_u32_e32 v130, 0x2000, v0
	ds_write2_b32 v130, v122, v106 offset0:64 offset1:96
	ds_write2_b32 v130, v123, v107 offset0:196 offset1:228
	v_add_u32_e32 v130, 0x2400, v0
	ds_write2_b32 v130, v124, v108 offset0:72 offset1:104
	ds_write2_b32 v130, v125, v109 offset0:204 offset1:236
	v_add_u32_e32 v130, 0x3000, v0
	ds_write2_b32 v130, v126, v110 offset0:96 offset1:128
	v_add_u32_e32 v130, 0x3200, v0
	ds_write2_b32 v130, v127, v111 offset0:100 offset1:132
	v_add_u32_e32 v130, 0x3400, v0
	ds_write2_b32 v130, v128, v112 offset0:104 offset1:136
	v_add_u32_e32 v130, 0x3600, v0
	ds_write2_b32 v130, v129, v113 offset0:108 offset1:140
	v_add_u32_e32 v130, 0x4000, v0
	ds_write2_b32 v130, v82, v66 offset0:128 offset1:160
	v_add_u32_e32 v130, 0x4400, v0
	ds_write2_b32 v130, v83, v67 offset0:4 offset1:36
	ds_write2_b32 v130, v84, v68 offset0:136 offset1:168
	v_add_u32_e32 v130, 0x4800, v0
	ds_write2_b32 v130, v85, v69 offset0:12 offset1:44
	v_add_u32_e32 v130, 0x5000, v0
	ds_write2_b32 v130, v86, v70 offset0:160 offset1:192
	v_add_u32_e32 v130, 0x5400, v0
	ds_write2_b32 v130, v87, v71 offset0:36 offset1:68
	ds_write2_b32 v130, v88, v72 offset0:168 offset1:200
	v_add_u32_e32 v130, 0x5800, v0
	ds_write2_b32 v130, v89, v73 offset0:44 offset1:76
	v_add_u32_e32 v130, 0x6000, v0
	ds_write2_b32 v130, v90, v74 offset0:192 offset1:224
	v_add_u32_e32 v130, 0x6400, v0
	ds_write2_b32 v130, v91, v75 offset0:68 offset1:100
	ds_write2_b32 v130, v92, v76 offset0:200 offset1:232
	v_add_u32_e32 v130, 0x6800, v0
	ds_write2_b32 v130, v93, v77 offset0:76 offset1:108
	v_add_u32_e32 v130, 0x7200, v0
	ds_write2_b32 v130, v94, v78 offset0:96 offset1:128
	v_add_u32_e32 v130, 0x7400, v0
	ds_write2_b32 v130, v95, v79 offset0:100 offset1:132
	v_add_u32_e32 v130, 0x7600, v0
	ds_write2_b32 v130, v96, v80 offset0:104 offset1:136
	v_add_u32_e32 v130, 0x7800, v0
	ds_write2_b32 v130, v97, v81 offset0:108 offset1:140
	v_add_u32_e32 v130, 0x8400, v0
	ds_write2_b32 v130, v50, v34 offset1:32
	ds_write2_b32 v130, v51, v35 offset0:132 offset1:164
	v_add_u32_e32 v130, 0x8800, v0
	ds_write2_b32 v130, v52, v36 offset0:8 offset1:40
	ds_write2_b32 v130, v53, v37 offset0:140 offset1:172
	v_add_u32_e32 v130, 0x9400, v0
	ds_write2_b32 v130, v54, v38 offset0:32 offset1:64
	ds_write2_b32 v130, v55, v39 offset0:164 offset1:196
	v_add_u32_e32 v130, 0x9800, v0
	ds_write2_b32 v130, v56, v40 offset0:40 offset1:72
	ds_write2_b32 v130, v57, v41 offset0:172 offset1:204
	v_add_u32_e32 v130, 0xa400, v0
	ds_write2_b32 v130, v58, v42 offset0:64 offset1:96
	ds_write2_b32 v130, v59, v43 offset0:196 offset1:228
	v_add_u32_e32 v130, 0xa800, v0
	ds_write2_b32 v130, v60, v44 offset0:72 offset1:104
	ds_write2_b32 v130, v61, v45 offset0:204 offset1:236
	v_add_u32_e32 v130, 0xb400, v0
	ds_write2_b32 v130, v62, v46 offset0:96 offset1:128
	v_add_u32_e32 v130, 0xb600, v0
	ds_write2_b32 v130, v63, v47 offset0:100 offset1:132
	v_add_u32_e32 v130, 0xb800, v0
	ds_write2_b32 v130, v64, v48 offset0:104 offset1:136
	v_add_u32_e32 v130, 0xba00, v0
	ds_write2_b32 v130, v65, v49 offset0:108 offset1:140
	v_add_u32_e32 v130, 0xc400, v0
	ds_write2_b32 v130, v18, v2 offset0:128 offset1:160
	v_add_u32_e32 v130, 0xc800, v0
	ds_write2_b32 v130, v19, v3 offset0:4 offset1:36
	ds_write2_b32 v130, v20, v4 offset0:136 offset1:168
	v_add_u32_e32 v130, 0xcc00, v0
	ds_write2_b32 v130, v21, v5 offset0:12 offset1:44
	v_add_u32_e32 v130, 0xd400, v0
	ds_write2_b32 v130, v22, v6 offset0:160 offset1:192
	v_add_u32_e32 v130, 0xd800, v0
	ds_write2_b32 v130, v23, v7 offset0:36 offset1:68
	ds_write2_b32 v130, v24, v8 offset0:168 offset1:200
	v_add_u32_e32 v130, 0xdc00, v0
	ds_write2_b32 v130, v25, v9 offset0:44 offset1:76
	v_add_u32_e32 v130, 0xe400, v0
	ds_write2_b32 v130, v26, v10 offset0:192 offset1:224
	v_add_u32_e32 v130, 0xe800, v0
	ds_write2_b32 v130, v27, v11 offset0:68 offset1:100
	ds_write2_b32 v130, v28, v12 offset0:200 offset1:232
	v_add_u32_e32 v130, 0xec00, v0
	ds_write2_b32 v130, v29, v13 offset0:76 offset1:108
	v_add_u32_e32 v130, 0xf600, v0
	ds_write2_b32 v130, v30, v14 offset0:96 offset1:128
	v_add_u32_e32 v130, 0xf800, v0
	ds_write2_b32 v130, v31, v15 offset0:100 offset1:132
	v_add_u32_e32 v130, 0xfa00, v0
	v_add_u32_e32 v0, 0xfc00, v0
	ds_write2_b32 v130, v32, v16 offset0:104 offset1:136
	ds_write2_b32 v0, v33, v17 offset0:108 offset1:140

; #define MFMA32(a, b, c) __builtin_amdgcn_mfma_f32_32x32x16_bf16((a), (b), (c), 0, 0, 0)
; DI void gemm_mainloop_big(const bf16_t* __restrict__ A, int lda, const bf16_t* __restrict__ Bt, int ldb, int K, int m0, int n0,
;                           f32x16 (&acc)[4][2], char* smem) {
;     ...
;   for (int kt = 0; kt < nk; ++kt) {
;     if (kt + 1 < nk) {
; #pragma unroll
;       for (int i = 0; i < 8; ++i) ra[i] = *(const u32x4*)(ap + (size_t)(32 * i) * lda + (kt + 1) * 64);
; #pragma unroll
;       for (int i = 0; i < 4; ++i) rb[i] = *(const u32x4*)(bp + (size_t)(32 * i) * ldb + (kt + 1) * 64);
;     }
; #pragma unroll
;     for (int ks = 0; ks < 4; ++ks) {
;       bf16x8 af[4], bfr[2];
; #pragma unroll
;       for (int f = 0; f < 4; ++f) af[f] = *(const bf16x8*)&sa[wm * 128 + f * 32 + r][ks * 16 + half * 8];
; #pragma unroll
;       for (int f = 0; f < 2; ++f) bfr[f] = *(const bf16x8*)&sb[wn * 64 + f * 32 + r][ks * 16 + half * 8];
; #pragma unroll
;       for (int mf = 0; mf < 4; ++mf)
; #pragma unroll
;         for (int nf = 0; nf < 2; ++nf) acc[mf][nf] = MFMA32(af[mf], bfr[nf], acc[mf][nf]);
;     }
.LBB0_1118:
	ds_read_b128 v[130:133], v0
	ds_read_b128 v[134:137], v139 offset:36864
	ds_read_b128 v[144:147], v0 offset:32
	ds_read_b128 v[148:151], v139 offset:36896
	ds_read_b128 v[152:155], v139 offset:41472
	ds_read_b128 v[156:159], v139 offset:41504
	s_mov_b32 s44, 0xbc0000
	s_waitcnt lgkmcnt(4)
	v_mfma_f32_32x32x16_bf16 v[114:129], v[130:133], v[134:137], v[114:129]
	s_waitcnt lgkmcnt(1)
	v_mfma_f32_32x32x16_bf16 v[98:113], v[130:133], v[152:155], v[98:113]
	ds_read_b128 v[130:133], v0 offset:4608
	ds_read_b128 v[160:163], v0 offset:4640
	s_waitcnt lgkmcnt(1)
	v_mfma_f32_32x32x16_bf16 v[82:97], v[130:133], v[134:137], v[82:97]
	v_mfma_f32_32x32x16_bf16 v[66:81], v[130:133], v[152:155], v[66:81]
	ds_read_b128 v[130:133], v0 offset:9216
	ds_read_b128 v[164:167], v0 offset:9248
	s_waitcnt lgkmcnt(1)
	v_mfma_f32_32x32x16_bf16 v[50:65], v[130:133], v[134:137], v[50:65]
	v_mfma_f32_32x32x16_bf16 v[34:49], v[130:133], v[152:155], v[34:49]
	ds_read_b128 v[130:133], v0 offset:13824
	ds_read_b128 v[168:171], v0 offset:13856
	s_waitcnt lgkmcnt(1)
	v_mfma_f32_32x32x16_bf16 v[18:33], v[130:133], v[134:137], v[18:33]
	v_mfma_f32_32x32x16_bf16 v[2:17], v[130:133], v[152:155], v[2:17]
	v_mfma_f32_32x32x16_bf16 v[114:129], v[144:147], v[148:151], v[114:129]
	v_mfma_f32_32x32x16_bf16 v[98:113], v[144:147], v[156:159], v[98:113]
	v_mfma_f32_32x32x16_bf16 v[82:97], v[160:163], v[148:151], v[82:97]
	v_mfma_f32_32x32x16_bf16 v[66:81], v[160:163], v[156:159], v[66:81]
	v_mfma_f32_32x32x16_bf16 v[50:65], v[164:167], v[148:151], v[50:65]
	v_mfma_f32_32x32x16_bf16 v[34:49], v[164:167], v[156:159], v[34:49]
	s_waitcnt lgkmcnt(0)
	v_mfma_f32_32x32x16_bf16 v[18:33], v[168:171], v[148:151], v[18:33]
	ds_read_b128 v[134:137], v0 offset:64
	ds_read_b128 v[144:147], v139 offset:36928
	ds_read_b128 v[148:151], v0 offset:96
	ds_read_b128 v[152:155], v139 offset:36960
	v_mfma_f32_32x32x16_bf16 v[2:17], v[168:171], v[156:159], v[2:17]
	ds_read_b128 v[156:159], v139 offset:41536
	ds_read_b128 v[130:133], v139 offset:41568
	s_waitcnt lgkmcnt(4)
	v_mfma_f32_32x32x16_bf16 v[114:129], v[134:137], v[144:147], v[114:129]
	s_waitcnt lgkmcnt(1)
	v_mfma_f32_32x32x16_bf16 v[98:113], v[134:137], v[156:159], v[98:113]
	ds_read_b128 v[134:137], v0 offset:4672
	ds_read_b128 v[160:163], v0 offset:4704
	s_waitcnt lgkmcnt(1)
	v_mfma_f32_32x32x16_bf16 v[82:97], v[134:137], v[144:147], v[82:97]
	v_mfma_f32_32x32x16_bf16 v[66:81], v[134:137], v[156:159], v[66:81]
	ds_read_b128 v[134:137], v0 offset:9280
	ds_read_b128 v[164:167], v0 offset:9312
	s_waitcnt lgkmcnt(1)
	v_mfma_f32_32x32x16_bf16 v[50:65], v[134:137], v[144:147], v[50:65]
	v_mfma_f32_32x32x16_bf16 v[34:49], v[134:137], v[156:159], v[34:49]
	ds_read_b128 v[168:171], v0 offset:13888
	ds_read_b128 v[134:137], v0 offset:13920
	s_waitcnt lgkmcnt(1)
	v_mfma_f32_32x32x16_bf16 v[18:33], v[168:171], v[144:147], v[18:33]
	v_lshl_add_u64 v[144:145], v[140:141], 0, s[42:43]
	v_add_co_u32_e32 v172, vcc, s87, v144
	v_lshl_add_u64 v[146:147], v[142:143], 0, s[42:43]
	s_nop 0
	v_addc_co_u32_e32 v173, vcc, 0, v145, vcc
	s_add_u32 s42, s42, 0x80
	v_mfma_f32_32x32x16_bf16 v[2:17], v[168:171], v[156:159], v[2:17]
	v_add_co_u32_e32 v156, vcc, s2, v144
	s_addc_u32 s43, s43, 0
	s_nop 0
	v_addc_co_u32_e32 v157, vcc, 0, v145, vcc
	v_add_co_u32_e32 v158, vcc, s3, v144
	v_mfma_f32_32x32x16_bf16 v[114:129], v[148:151], v[152:155], v[114:129]
	s_nop 0
	v_addc_co_u32_e32 v159, vcc, 0, v145, vcc
	v_add_co_u32_e32 v168, vcc, s88, v144
	s_cmpk_lg_i32 s42, 0x780
	s_nop 0
	v_addc_co_u32_e32 v169, vcc, 0, v145, vcc
	v_add_co_u32_e32 v170, vcc, s89, v144
	v_mfma_f32_32x32x16_bf16 v[98:113], v[148:151], v[130:133], v[98:113]
	s_nop 0
	v_addc_co_u32_e32 v171, vcc, 0, v145, vcc
	v_add_co_u32_e32 v174, vcc, s4, v144
	s_nop 1
	v_addc_co_u32_e32 v175, vcc, 0, v145, vcc
	v_add_co_u32_e32 v176, vcc, s5, v144
	v_mfma_f32_32x32x16_bf16 v[82:97], v[160:163], v[152:155], v[82:97]
	s_nop 0
	v_addc_co_u32_e32 v177, vcc, 0, v145, vcc
	v_add_co_u32_e32 v178, vcc, s86, v144
	s_nop 1
	v_addc_co_u32_e32 v179, vcc, 0, v145, vcc
	v_add_co_u32_e32 v180, vcc, s44, v146
	s_mov_b32 s44, 0xbd0000
	s_nop 0
	v_addc_co_u32_e32 v181, vcc, 0, v147, vcc
	v_add_co_u32_e32 v190, vcc, s44, v146
	s_mov_b32 s44, 0xbe0000
	s_nop 0
	v_addc_co_u32_e32 v191, vcc, 0, v147, vcc
	v_add_co_u32_e32 v194, vcc, s44, v146
	s_mov_b32 s44, 0xbf0000
	s_nop 0
	v_addc_co_u32_e32 v195, vcc, 0, v147, vcc
	v_add_co_u32_e32 v198, vcc, s44, v146
	v_mfma_f32_32x32x16_bf16 v[66:81], v[160:163], v[130:133], v[66:81]
	s_nop 0
	v_addc_co_u32_e32 v199, vcc, 0, v147, vcc
	global_load_dwordx4 v[144:147], v[172:173], off offset:128
	global_load_dwordx4 v[148:151], v[156:157], off offset:128
	s_nop 0
	global_load_dwordx4 v[156:159], v[158:159], off offset:128
	s_nop 0
	global_load_dwordx4 v[160:163], v[168:169], off offset:128
	v_mfma_f32_32x32x16_bf16 v[50:65], v[164:167], v[152:155], v[50:65]
	v_mfma_f32_32x32x16_bf16 v[34:49], v[164:167], v[130:133], v[34:49]
	global_load_dwordx4 v[164:167], v[170:171], off offset:128
	s_nop 0
	global_load_dwordx4 v[168:171], v[174:175], off offset:128
	s_nop 0
	global_load_dwordx4 v[172:175], v[176:177], off offset:128
	s_nop 0
	global_load_dwordx4 v[176:179], v[178:179], off offset:128
	s_nop 0
	global_load_dwordx4 v[186:189], v[180:181], off offset:128
	s_nop 0
	global_load_dwordx4 v[190:193], v[190:191], off offset:128
	s_nop 0
	global_load_dwordx4 v[194:197], v[194:195], off offset:128
	s_waitcnt lgkmcnt(0)
	v_mfma_f32_32x32x16_bf16 v[18:33], v[134:137], v[152:155], v[18:33]
	global_load_dwordx4 v[152:155], v[198:199], off offset:128
	s_barrier
; #define MFMA32(a, b, c) __builtin_amdgcn_mfma_f32_32x32x16_bf16((a), (b), (c), 0, 0, 0)
; DI void gemm_mainloop_big(const bf16_t* __restrict__ A, int lda, const bf16_t* __restrict__ Bt, int ldb, int K, int m0, int n0,
;                           f32x16 (&acc)[4][2], char* smem) {
;     ...
; #pragma unroll
;     for (int ks = 0; ks < 4; ++ks) {
;       bf16x8 af[4], bfr[2];
; #pragma unroll
;       for (int f = 0; f < 4; ++f) af[f] = *(const bf16x8*)&sa[wm * 128 + f * 32 + r][ks * 16 + half * 8];
; #pragma unroll
;       for (int f = 0; f < 2; ++f) bfr[f] = *(const bf16x8*)&sb[wn * 64 + f * 32 + r][ks * 16 + half * 8];
; #pragma unroll
;       for (int mf = 0; mf < 4; ++mf)
; #pragma unroll
;         for (int nf = 0; nf < 2; ++nf) acc[mf][nf] = MFMA32(af[mf], bfr[nf], acc[mf][nf]);
;     }
;     __syncthreads();
;     if (kt + 1 < nk) {
; #pragma unroll
;       for (int i = 0; i < 8; ++i) *(u32x4*)&sa[(tid >> 3) + 32 * i][(tid & 7) * 8] = ra[i];
; #pragma unroll
;       for (int i = 0; i < 4; ++i) *(u32x4*)&sb[(tid >> 3) + 32 * i][(tid & 7) * 8] = rb[i];
;     }
;     __syncthreads();
	s_waitcnt vmcnt(11)
	ds_write_b128 v138, v[144:147]
	s_waitcnt vmcnt(10)
	ds_write_b128 v138, v[148:151] offset:4608
	s_waitcnt vmcnt(9)
	ds_write_b128 v138, v[156:159] offset:9216
	s_waitcnt vmcnt(8)
	ds_write_b128 v138, v[160:163] offset:13824
	s_waitcnt vmcnt(7)
	ds_write_b128 v138, v[164:167] offset:18432
	s_waitcnt vmcnt(6)
	ds_write_b128 v138, v[168:171] offset:23040
	s_waitcnt vmcnt(5)
	ds_write_b128 v138, v[172:175] offset:27648
	s_waitcnt vmcnt(4)
	ds_write_b128 v138, v[176:179] offset:32256
	s_waitcnt vmcnt(3)
	ds_write_b128 v138, v[186:189] offset:36864
	s_waitcnt vmcnt(2)
	ds_write_b128 v138, v[190:193] offset:41472
	s_waitcnt vmcnt(1)
	ds_write_b128 v138, v[194:197] offset:46080
	s_waitcnt vmcnt(0)
	ds_write_b128 v138, v[152:155] offset:50688
	v_mfma_f32_32x32x16_bf16 v[2:17], v[134:137], v[130:133], v[2:17]
	s_waitcnt lgkmcnt(0)
	s_barrier
	s_cbranch_scc1 .LBB0_1118
	ds_read_b128 v[130:133], v0
	ds_read_b128 v[134:137], v139 offset:36864
	ds_read_b128 v[140:143], v139 offset:41472
	s_waitcnt lgkmcnt(1)
	v_mfma_f32_32x32x16_bf16 v[114:129], v[130:133], v[134:137], v[114:129]
	s_waitcnt lgkmcnt(0)
	v_mfma_f32_32x32x16_bf16 v[98:113], v[130:133], v[140:143], v[98:113]
	ds_read_b128 v[130:133], v0 offset:4608
	s_waitcnt lgkmcnt(0)
	v_mfma_f32_32x32x16_bf16 v[82:97], v[130:133], v[134:137], v[82:97]
	v_mfma_f32_32x32x16_bf16 v[66:81], v[130:133], v[140:143], v[66:81]
	ds_read_b128 v[130:133], v0 offset:9216
	s_waitcnt lgkmcnt(0)
	v_mfma_f32_32x32x16_bf16 v[50:65], v[130:133], v[134:137], v[50:65]
	v_mfma_f32_32x32x16_bf16 v[34:49], v[130:133], v[140:143], v[34:49]
	ds_read_b128 v[130:133], v0 offset:13824
	s_waitcnt lgkmcnt(0)
	v_mfma_f32_32x32x16_bf16 v[18:33], v[130:133], v[134:137], v[18:33]
	v_mfma_f32_32x32x16_bf16 v[2:17], v[130:133], v[140:143], v[2:17]
	ds_read_b128 v[130:133], v0 offset:32
	ds_read_b128 v[134:137], v139 offset:36896
	ds_read_b128 v[140:143], v139 offset:41504
	s_waitcnt lgkmcnt(1)
	v_mfma_f32_32x32x16_bf16 v[114:129], v[130:133], v[134:137], v[114:129]
	s_waitcnt lgkmcnt(0)
	v_mfma_f32_32x32x16_bf16 v[98:113], v[130:133], v[140:143], v[98:113]
	ds_read_b128 v[130:133], v0 offset:4640
	s_waitcnt lgkmcnt(0)
	v_mfma_f32_32x32x16_bf16 v[82:97], v[130:133], v[134:137], v[82:97]
	v_mfma_f32_32x32x16_bf16 v[66:81], v[130:133], v[140:143], v[66:81]
	ds_read_b128 v[130:133], v0 offset:9248
	s_waitcnt lgkmcnt(0)
	v_mfma_f32_32x32x16_bf16 v[50:65], v[130:133], v[134:137], v[50:65]
	v_mfma_f32_32x32x16_bf16 v[34:49], v[130:133], v[140:143], v[34:49]
	ds_read_b128 v[130:133], v0 offset:13856
	s_waitcnt lgkmcnt(0)
	v_mfma_f32_32x32x16_bf16 v[18:33], v[130:133], v[134:137], v[18:33]
	v_mfma_f32_32x32x16_bf16 v[2:17], v[130:133], v[140:143], v[2:17]
	ds_read_b128 v[130:133], v0 offset:64
	ds_read_b128 v[134:137], v139 offset:36928
	ds_read_b128 v[140:143], v139 offset:41536
	s_waitcnt lgkmcnt(1)
	v_mfma_f32_32x32x16_bf16 v[114:129], v[130:133], v[134:137], v[114:129]
	s_waitcnt lgkmcnt(0)
	v_mfma_f32_32x32x16_bf16 v[98:113], v[130:133], v[140:143], v[98:113]
	ds_read_b128 v[130:133], v0 offset:4672
	s_waitcnt lgkmcnt(0)
	v_mfma_f32_32x32x16_bf16 v[82:97], v[130:133], v[134:137], v[82:97]
	v_mfma_f32_32x32x16_bf16 v[66:81], v[130:133], v[140:143], v[66:81]
	ds_read_b128 v[130:133], v0 offset:9280
	s_waitcnt lgkmcnt(0)
	v_mfma_f32_32x32x16_bf16 v[50:65], v[130:133], v[134:137], v[50:65]
	v_mfma_f32_32x32x16_bf16 v[34:49], v[130:133], v[140:143], v[34:49]
	ds_read_b128 v[130:133], v0 offset:13888
	s_waitcnt lgkmcnt(0)
	v_mfma_f32_32x32x16_bf16 v[18:33], v[130:133], v[134:137], v[18:33]
	v_mfma_f32_32x32x16_bf16 v[2:17], v[130:133], v[140:143], v[2:17]
	ds_read_b128 v[130:133], v0 offset:96
	ds_read_b128 v[134:137], v139 offset:36960
	ds_read_b128 v[138:141], v139 offset:41568
	s_waitcnt lgkmcnt(1)
	v_mfma_f32_32x32x16_bf16 v[114:129], v[130:133], v[134:137], v[114:129]
	s_waitcnt lgkmcnt(0)
	v_mfma_f32_32x32x16_bf16 v[98:113], v[130:133], v[138:141], v[98:113]
	ds_read_b128 v[130:133], v0 offset:4704
	s_waitcnt lgkmcnt(0)
	v_mfma_f32_32x32x16_bf16 v[82:97], v[130:133], v[134:137], v[82:97]
	v_mfma_f32_32x32x16_bf16 v[66:81], v[130:133], v[138:141], v[66:81]
	ds_read_b128 v[130:133], v0 offset:9312
	s_waitcnt lgkmcnt(0)
	v_mfma_f32_32x32x16_bf16 v[50:65], v[130:133], v[134:137], v[50:65]
	v_mfma_f32_32x32x16_bf16 v[34:49], v[130:133], v[138:141], v[34:49]
	ds_read_b128 v[130:133], v0 offset:13920
	s_waitcnt lgkmcnt(0)
	s_barrier
	s_barrier
	v_mfma_f32_32x32x16_bf16 v[18:33], v[130:133], v[134:137], v[18:33]
	v_mov_b32_e32 v134, v216
	s_nop 0
	v_cmp_gt_u32_e32 vcc, s31, v134
	v_mfma_f32_32x32x16_bf16 v[2:17], v[130:133], v[138:141], v[2:17]
	s_and_saveexec_b64 s[42:43], vcc
	s_cbranch_execz .LBB0_1121
; DI int crow(int i, int h) { return (i & 3) + 8 * (i >> 2) + 4 * h; }
; DI void stage_half(float* st, const f32x16 (&acc)[4][2], int h, int tid) {
;   const int lane = tid & 63, w = tid >> 6, wm = w >> 1, wn = w & 1, c = lane & 31, half = lane >> 5;
;   if (wm == h) {
; #pragma unroll
;     for (int mf = 0; mf < 4; ++mf)
; #pragma unroll
;       for (int nf = 0; nf < 2; ++nf)
; #pragma unroll
;         for (int i = 0; i < 16; ++i) st[(mf * 32 + crow(i, half)) * 132 + wn * 64 + nf * 32 + c] = acc[mf][nf][i];
;   }
	v_lshrrev_b32_e32 v0, 3, v134
	v_and_b32_e32 v0, 4, v0
	v_and_b32_e32 v130, 0x5f, v134
	v_mul_u32_u24_e32 v0, 0x210, v0
	v_lshl_add_u32 v0, v130, 2, v0
	v_add_u32_e32 v130, 0x400, v0
	ds_write2_b32 v0, v114, v98 offset1:32
	ds_write2_b32 v0, v115, v99 offset0:132 offset1:164
	ds_write2_b32 v130, v116, v100 offset0:8 offset1:40
	ds_write2_b32 v130, v117, v101 offset0:140 offset1:172
	v_add_u32_e32 v130, 0x1000, v0
	ds_write2_b32 v130, v118, v102 offset0:32 offset1:64
	ds_write2_b32 v130, v119, v103 offset0:164 offset1:196
	v_add_u32_e32 v130, 0x1400, v0
	ds_write2_b32 v130, v120, v104 offset0:40 offset1:72
	ds_write2_b32 v130, v121, v105 offset0:172 offset1:204
	v_add_u32_e32 v130, 0x2000, v0
	ds_write2_b32 v130, v122, v106 offset0:64 offset1:96
	ds_write2_b32 v130, v123, v107 offset0:196 offset1:228
	v_add_u32_e32 v130, 0x2400, v0
	ds_write2_b32 v130, v124, v108 offset0:72 offset1:104
	ds_write2_b32 v130, v125, v109 offset0:204 offset1:236
	v_add_u32_e32 v130, 0x3000, v0
	ds_write2_b32 v130, v126, v110 offset0:96 offset1:128
	v_add_u32_e32 v130, 0x3200, v0
	ds_write2_b32 v130, v127, v111 offset0:100 offset1:132
	v_add_u32_e32 v130, 0x3400, v0
	ds_write2_b32 v130, v128, v112 offset0:104 offset1:136
	v_add_u32_e32 v130, 0x3600, v0
	ds_write2_b32 v130, v129, v113 offset0:108 offset1:140
	v_add_u32_e32 v130, 0x4000, v0
	ds_write2_b32 v130, v82, v66 offset0:128 offset1:160
	v_add_u32_e32 v130, 0x4400, v0
	ds_write2_b32 v130, v83, v67 offset0:4 offset1:36
	ds_write2_b32 v130, v84, v68 offset0:136 offset1:168
	v_add_u32_e32 v130, 0x4800, v0
	ds_write2_b32 v130, v85, v69 offset0:12 offset1:44
	v_add_u32_e32 v130, 0x5000, v0
	ds_write2_b32 v130, v86, v70 offset0:160 offset1:192
	v_add_u32_e32 v130, 0x5400, v0
	ds_write2_b32 v130, v87, v71 offset0:36 offset1:68
	ds_write2_b32 v130, v88, v72 offset0:168 offset1:200
	v_add_u32_e32 v130, 0x5800, v0
	ds_write2_b32 v130, v89, v73 offset0:44 offset1:76
	v_add_u32_e32 v130, 0x6000, v0
	ds_write2_b32 v130, v90, v74 offset0:192 offset1:224
	v_add_u32_e32 v130, 0x6400, v0
	ds_write2_b32 v130, v91, v75 offset0:68 offset1:100
	ds_write2_b32 v130, v92, v76 offset0:200 offset1:232
	v_add_u32_e32 v130, 0x6800, v0
	ds_write2_b32 v130, v93, v77 offset0:76 offset1:108
	v_add_u32_e32 v130, 0x7200, v0
	ds_write2_b32 v130, v94, v78 offset0:96 offset1:128
	v_add_u32_e32 v130, 0x7400, v0
	ds_write2_b32 v130, v95, v79 offset0:100 offset1:132
	v_add_u32_e32 v130, 0x7600, v0
	ds_write2_b32 v130, v96, v80 offset0:104 offset1:136
	v_add_u32_e32 v130, 0x7800, v0
	ds_write2_b32 v130, v97, v81 offset0:108 offset1:140
	v_add_u32_e32 v130, 0x8400, v0
	ds_write2_b32 v130, v50, v34 offset1:32
	ds_write2_b32 v130, v51, v35 offset0:132 offset1:164
	v_add_u32_e32 v130, 0x8800, v0
	ds_write2_b32 v130, v52, v36 offset0:8 offset1:40
	ds_write2_b32 v130, v53, v37 offset0:140 offset1:172
	v_add_u32_e32 v130, 0x9400, v0
	ds_write2_b32 v130, v54, v38 offset0:32 offset1:64
	ds_write2_b32 v130, v55, v39 offset0:164 offset1:196
	v_add_u32_e32 v130, 0x9800, v0
	ds_write2_b32 v130, v56, v40 offset0:40 offset1:72
	ds_write2_b32 v130, v57, v41 offset0:172 offset1:204
	v_add_u32_e32 v130, 0xa400, v0
	ds_write2_b32 v130, v58, v42 offset0:64 offset1:96
	ds_write2_b32 v130, v59, v43 offset0:196 offset1:228
	v_add_u32_e32 v130, 0xa800, v0
	ds_write2_b32 v130, v60, v44 offset0:72 offset1:104
	ds_write2_b32 v130, v61, v45 offset0:204 offset1:236
	v_add_u32_e32 v130, 0xb400, v0
	ds_write2_b32 v130, v62, v46 offset0:96 offset1:128
	v_add_u32_e32 v130, 0xb600, v0
	ds_write2_b32 v130, v63, v47 offset0:100 offset1:132
	v_add_u32_e32 v130, 0xb800, v0
	ds_write2_b32 v130, v64, v48 offset0:104 offset1:136
	v_add_u32_e32 v130, 0xba00, v0
	ds_write2_b32 v130, v65, v49 offset0:108 offset1:140
	v_add_u32_e32 v130, 0xc400, v0
	ds_write2_b32 v130, v18, v2 offset0:128 offset1:160
	v_add_u32_e32 v130, 0xc800, v0
	ds_write2_b32 v130, v19, v3 offset0:4 offset1:36
	ds_write2_b32 v130, v20, v4 offset0:136 offset1:168
	v_add_u32_e32 v130, 0xcc00, v0
	ds_write2_b32 v130, v21, v5 offset0:12 offset1:44
	v_add_u32_e32 v130, 0xd400, v0
	ds_write2_b32 v130, v22, v6 offset0:160 offset1:192
	v_add_u32_e32 v130, 0xd800, v0
	ds_write2_b32 v130, v23, v7 offset0:36 offset1:68
	ds_write2_b32 v130, v24, v8 offset0:168 offset1:200
	v_add_u32_e32 v130, 0xdc00, v0
	ds_write2_b32 v130, v25, v9 offset0:44 offset1:76
	v_add_u32_e32 v130, 0xe400, v0
	ds_write2_b32 v130, v26, v10 offset0:192 offset1:224
	v_add_u32_e32 v130, 0xe800, v0
	ds_write2_b32 v130, v27, v11 offset0:68 offset1:100
	ds_write2_b32 v130, v28, v12 offset0:200 offset1:232
	v_add_u32_e32 v130, 0xec00, v0
	ds_write2_b32 v130, v29, v13 offset0:76 offset1:108
	v_add_u32_e32 v130, 0xf600, v0
	ds_write2_b32 v130, v30, v14 offset0:96 offset1:128
	v_add_u32_e32 v130, 0xf800, v0
	ds_write2_b32 v130, v31, v15 offset0:100 offset1:132
	v_add_u32_e32 v130, 0xfa00, v0
	v_add_u32_e32 v0, 0xfc00, v0
	ds_write2_b32 v130, v32, v16 offset0:104 offset1:136
	ds_write2_b32 v0, v33, v17 offset0:108 offset1:140

; DI int otid() { int t = threadIdx.x; asm volatile("" : "+v"(t)); return t; }
; DI void gemm_res_tile_big(const bf16_t* A, int lda, const bf16_t* Bt, int K, const float* __restrict__ xin, float* __restrict__ xout,
;                           const float* __restrict__ gate, int mt, int nt, char* smem) {
;     ...
;   for (int h = 0; h < 2; ++h) {
;     const int tid = otid();
;     stage_half(st, acc, h, tid);
;     __syncthreads();
;     const int r = tid >> 5, ch = tid & 31;
;     const float4 g = *(const float4*)(gate + (size_t)b * 6144 + n0 + ch * 4);
; #pragma unroll 4
;     for (int ps = 0; ps < 16; ++ps) {
;       const int row = ps * 8 + r;
;       const float4 a = *(const float4*)(st + row * 132 + ch * 4);
;       const size_t off = (size_t)(m0 + h * 128 + row) * 1024 + n0 + ch * 4;
;       const float4 xi = *(const float4*)(xin + off);
;       float4 o; o.x = xi.x + g.x * a.x; o.y = xi.y + g.y * a.y; o.z = xi.z + g.z * a.z; o.w = xi.w + g.w * a.w;
;       *(float4*)(xout + off) = o;
;     }
;     __syncthreads();
.LBB0_1122:
	v_lshrrev_b32_e32 v215, 5, v216
	v_mul_u32_u24_e32 v182, 0x210, v215
	v_and_b32_e32 v215, 31, v216
	v_lshl_add_u32 v182, v215, 4, v182
	v_lshlrev_b32_e32 v184, 10, v136
	v_add_u32_e32 v184, v184, v144
	v_lshlrev_b32_e32 v184, 2, v184
	v_mov_b32_e32 v214, v184
	global_load_dwordx4 v[158:161], v184, s[24:25]
	s_nop 0
	v_add_u32_e32 v184, 0x8000, v184
	global_load_dwordx4 v[162:165], v184, s[24:25]
	s_nop 0
	v_add_u32_e32 v184, 0x8000, v184
	global_load_dwordx4 v[166:169], v184, s[24:25]
	s_nop 0
	v_add_u32_e32 v184, 0x8000, v184
	global_load_dwordx4 v[170:173], v184, s[24:25]
	s_nop 0
	v_add_u32_e32 v184, 0x8000, v184
	global_load_dwordx4 v[174:177], v184, s[24:25]
	s_nop 0
	v_add_u32_e32 v184, 0x8000, v184
	global_load_dwordx4 v[178:181], v184, s[24:25]
	s_nop 0
	v_add_u32_e32 v184, 0x8000, v184
	global_load_dwordx4 v[186:189], v184, s[24:25]
	s_nop 0
	v_add_u32_e32 v184, 0x8000, v184
	global_load_dwordx4 v[190:193], v184, s[24:25]
	s_nop 0
	v_add_u32_e32 v184, 0x8000, v184
	ds_read_b128 v[194:197], v182 offset:0
	ds_read_b128 v[198:201], v182 offset:4224
	ds_read_b128 v[202:205], v182 offset:8448
	ds_read_b128 v[210:213], v182 offset:12672
	s_waitcnt vmcnt(7) lgkmcnt(3)
	v_fma_f32 v158, v154, v194, v158
	v_fma_f32 v159, v130, v195, v159
	v_fma_f32 v160, v156, v196, v160
	v_fma_f32 v161, v132, v197, v161
	global_store_dwordx4 v214, v[158:161], s[84:85]
	s_nop 1
	v_add_u32_e32 v214, 0x8000, v214
	s_waitcnt vmcnt(7) lgkmcnt(2)
	v_fma_f32 v162, v154, v198, v162
	v_fma_f32 v163, v130, v199, v163
	v_fma_f32 v164, v156, v200, v164
	v_fma_f32 v165, v132, v201, v165
	global_store_dwordx4 v214, v[162:165], s[84:85]
	s_nop 1
	v_add_u32_e32 v214, 0x8000, v214
	s_waitcnt vmcnt(7) lgkmcnt(1)
	v_fma_f32 v166, v154, v202, v166
	v_fma_f32 v167, v130, v203, v167
	v_fma_f32 v168, v156, v204, v168
	v_fma_f32 v169, v132, v205, v169
	global_store_dwordx4 v214, v[166:169], s[84:85]
	s_nop 1
	v_add_u32_e32 v214, 0x8000, v214
	s_waitcnt vmcnt(7) lgkmcnt(0)
	v_fma_f32 v170, v154, v210, v170
	v_fma_f32 v171, v130, v211, v171
	v_fma_f32 v172, v156, v212, v172
	v_fma_f32 v173, v132, v213, v173
	global_store_dwordx4 v214, v[170:173], s[84:85]
	s_nop 1
	v_add_u32_e32 v214, 0x8000, v214
	ds_read_b128 v[194:197], v182 offset:16896
	ds_read_b128 v[198:201], v182 offset:21120
	ds_read_b128 v[202:205], v182 offset:25344
	ds_read_b128 v[210:213], v182 offset:29568
	s_waitcnt vmcnt(7) lgkmcnt(3)
	v_fma_f32 v174, v154, v194, v174
	v_fma_f32 v175, v130, v195, v175
	v_fma_f32 v176, v156, v196, v176
	v_fma_f32 v177, v132, v197, v177
	global_store_dwordx4 v214, v[174:177], s[84:85]
	s_nop 1
	v_add_u32_e32 v214, 0x8000, v214
	s_waitcnt vmcnt(7) lgkmcnt(2)
	v_fma_f32 v178, v154, v198, v178
	v_fma_f32 v179, v130, v199, v179
	v_fma_f32 v180, v156, v200, v180
	v_fma_f32 v181, v132, v201, v181
	global_store_dwordx4 v214, v[178:181], s[84:85]
	s_nop 1
	v_add_u32_e32 v214, 0x8000, v214
	s_waitcnt vmcnt(7) lgkmcnt(1)
	v_fma_f32 v186, v154, v202, v186
	v_fma_f32 v187, v130, v203, v187
	v_fma_f32 v188, v156, v204, v188
	v_fma_f32 v189, v132, v205, v189
	global_store_dwordx4 v214, v[186:189], s[84:85]
	s_nop 1
	v_add_u32_e32 v214, 0x8000, v214
	s_waitcnt vmcnt(7) lgkmcnt(0)
	v_fma_f32 v190, v154, v210, v190
	v_fma_f32 v191, v130, v211, v191
	v_fma_f32 v192, v156, v212, v192
	v_fma_f32 v193, v132, v213, v193
	global_store_dwordx4 v214, v[190:193], s[84:85]
	s_nop 1
	v_add_u32_e32 v214, 0x8000, v214
	global_load_dwordx4 v[158:161], v184, s[24:25]
	s_nop 0
	v_add_u32_e32 v184, 0x8000, v184
	global_load_dwordx4 v[162:165], v184, s[24:25]
	s_nop 0
	v_add_u32_e32 v184, 0x8000, v184
	global_load_dwordx4 v[166:169], v184, s[24:25]
	s_nop 0
	v_add_u32_e32 v184, 0x8000, v184
	global_load_dwordx4 v[170:173], v184, s[24:25]
	s_nop 0
	v_add_u32_e32 v184, 0x8000, v184
	global_load_dwordx4 v[174:177], v184, s[24:25]
	s_nop 0
	v_add_u32_e32 v184, 0x8000, v184
	global_load_dwordx4 v[178:181], v184, s[24:25]
	s_nop 0
	v_add_u32_e32 v184, 0x8000, v184
	global_load_dwordx4 v[186:189], v184, s[24:25]
	s_nop 0
	v_add_u32_e32 v184, 0x8000, v184
	global_load_dwordx4 v[190:193], v184, s[24:25]
	s_nop 0
	v_add_u32_e32 v184, 0x8000, v184
	ds_read_b128 v[194:197], v182 offset:33792
	ds_read_b128 v[198:201], v182 offset:38016
	ds_read_b128 v[202:205], v182 offset:42240
	ds_read_b128 v[210:213], v182 offset:46464
	s_waitcnt vmcnt(7) lgkmcnt(3)
	v_fma_f32 v158, v154, v194, v158
	v_fma_f32 v159, v130, v195, v159
	v_fma_f32 v160, v156, v196, v160
	v_fma_f32 v161, v132, v197, v161
	global_store_dwordx4 v214, v[158:161], s[84:85]
	s_nop 1
	v_add_u32_e32 v214, 0x8000, v214
	s_waitcnt vmcnt(7) lgkmcnt(2)
	v_fma_f32 v162, v154, v198, v162
	v_fma_f32 v163, v130, v199, v163
	v_fma_f32 v164, v156, v200, v164
	v_fma_f32 v165, v132, v201, v165
	global_store_dwordx4 v214, v[162:165], s[84:85]
	s_nop 1
	v_add_u32_e32 v214, 0x8000, v214
	s_waitcnt vmcnt(7) lgkmcnt(1)
	v_fma_f32 v166, v154, v202, v166
	v_fma_f32 v167, v130, v203, v167
	v_fma_f32 v168, v156, v204, v168
	v_fma_f32 v169, v132, v205, v169
	global_store_dwordx4 v214, v[166:169], s[84:85]
	s_nop 1
	v_add_u32_e32 v214, 0x8000, v214
	s_waitcnt vmcnt(7) lgkmcnt(0)
	v_fma_f32 v170, v154, v210, v170
	v_fma_f32 v171, v130, v211, v171
	v_fma_f32 v172, v156, v212, v172
	v_fma_f32 v173, v132, v213, v173
	global_store_dwordx4 v214, v[170:173], s[84:85]
	s_nop 1
	v_add_u32_e32 v214, 0x8000, v214
	ds_read_b128 v[194:197], v182 offset:50688
	ds_read_b128 v[198:201], v182 offset:54912
	ds_read_b128 v[202:205], v182 offset:59136
	ds_read_b128 v[210:213], v182 offset:63360
	s_waitcnt vmcnt(7) lgkmcnt(3)
	v_fma_f32 v174, v154, v194, v174
	v_fma_f32 v175, v130, v195, v175
	v_fma_f32 v176, v156, v196, v176
	v_fma_f32 v177, v132, v197, v177
	global_store_dwordx4 v214, v[174:177], s[84:85]
	s_nop 1
	v_add_u32_e32 v214, 0x8000, v214
	s_waitcnt vmcnt(7) lgkmcnt(2)
	v_fma_f32 v178, v154, v198, v178
	v_fma_f32 v179, v130, v199, v179
	v_fma_f32 v180, v156, v200, v180
	v_fma_f32 v181, v132, v201, v181
	global_store_dwordx4 v214, v[178:181], s[84:85]
	s_nop 1
	v_add_u32_e32 v214, 0x8000, v214
	s_waitcnt vmcnt(7) lgkmcnt(1)
	v_fma_f32 v186, v154, v202, v186
	v_fma_f32 v187, v130, v203, v187
	v_fma_f32 v188, v156, v204, v188
	v_fma_f32 v189, v132, v205, v189
	global_store_dwordx4 v214, v[186:189], s[84:85]
	s_nop 1
	v_add_u32_e32 v214, 0x8000, v214
	s_waitcnt vmcnt(7) lgkmcnt(0)
	v_fma_f32 v190, v154, v210, v190
	v_fma_f32 v191, v130, v211, v191
	v_fma_f32 v192, v156, v212, v192
	v_fma_f32 v193, v132, v213, v193
	global_store_dwordx4 v214, v[190:193], s[84:85]
	s_nop 1
	v_add_u32_e32 v214, 0x8000, v214
	v_mov_b32_e32 v130, v216
	s_barrier
; DI int crow(int i, int h) { return (i & 3) + 8 * (i >> 2) + 4 * h; }
; DI void stage_half(float* st, const f32x16 (&acc)[4][2], int h, int tid) {
;   const int lane = tid & 63, w = tid >> 6, wm = w >> 1, wn = w & 1, c = lane & 31, half = lane >> 5;
;   if (wm == h) {
; #pragma unroll
;     for (int mf = 0; mf < 4; ++mf)
; #pragma unroll
;       for (int nf = 0; nf < 2; ++nf)
; #pragma unroll
;         for (int i = 0; i < 16; ++i) st[(mf * 32 + crow(i, half)) * 132 + wn * 64 + nf * 32 + c] = acc[mf][nf][i];
;   }
	s_nop 0
	v_and_b32_e32 v0, 0xffffff80, v130
	v_cmp_eq_u32_e32 vcc, s31, v0
	s_and_saveexec_b64 s[44:45], vcc
	s_cbranch_execz .LBB0_1125
	v_lshrrev_b32_e32 v0, 3, v130
	v_and_b32_e32 v0, 4, v0
	v_and_b32_e32 v131, 0x5f, v130
	v_mul_u32_u24_e32 v0, 0x210, v0
	v_lshl_add_u32 v0, v131, 2, v0
	ds_write2_b32 v0, v114, v98 offset1:32
	ds_write2_b32 v0, v115, v99 offset0:132 offset1:164
	v_add_u32_e32 v98, 0x400, v0
	ds_write2_b32 v98, v116, v100 offset0:8 offset1:40
	ds_write2_b32 v98, v117, v101 offset0:140 offset1:172
	v_add_u32_e32 v98, 0x1000, v0
	ds_write2_b32 v98, v118, v102 offset0:32 offset1:64
	ds_write2_b32 v98, v119, v103 offset0:164 offset1:196
	v_add_u32_e32 v98, 0x1400, v0
	ds_write2_b32 v98, v120, v104 offset0:40 offset1:72
	ds_write2_b32 v98, v121, v105 offset0:172 offset1:204
	v_add_u32_e32 v98, 0x2000, v0
	ds_write2_b32 v98, v122, v106 offset0:64 offset1:96
	ds_write2_b32 v98, v123, v107 offset0:196 offset1:228
	v_add_u32_e32 v98, 0x2400, v0
	ds_write2_b32 v98, v124, v108 offset0:72 offset1:104
	ds_write2_b32 v98, v125, v109 offset0:204 offset1:236
	v_add_u32_e32 v98, 0x3000, v0
	ds_write2_b32 v98, v126, v110 offset0:96 offset1:128
	v_add_u32_e32 v98, 0x3200, v0
	ds_write2_b32 v98, v127, v111 offset0:100 offset1:132
	v_add_u32_e32 v98, 0x3400, v0
	ds_write2_b32 v98, v128, v112 offset0:104 offset1:136
	v_add_u32_e32 v98, 0x3600, v0
	ds_write2_b32 v98, v129, v113 offset0:108 offset1:140
	v_add_u32_e32 v98, 0x4000, v0
	ds_write2_b32 v98, v82, v66 offset0:128 offset1:160
	v_add_u32_e32 v66, 0x4400, v0
	ds_write2_b32 v66, v83, v67 offset0:4 offset1:36
	ds_write2_b32 v66, v84, v68 offset0:136 offset1:168
	v_add_u32_e32 v66, 0x4800, v0
	ds_write2_b32 v66, v85, v69 offset0:12 offset1:44
	v_add_u32_e32 v66, 0x5000, v0
	ds_write2_b32 v66, v86, v70 offset0:160 offset1:192
	v_add_u32_e32 v66, 0x5400, v0
	ds_write2_b32 v66, v87, v71 offset0:36 offset1:68
	ds_write2_b32 v66, v88, v72 offset0:168 offset1:200
	v_add_u32_e32 v66, 0x5800, v0
	ds_write2_b32 v66, v89, v73 offset0:44 offset1:76
	v_add_u32_e32 v66, 0x6000, v0
	ds_write2_b32 v66, v90, v74 offset0:192 offset1:224
	v_add_u32_e32 v66, 0x6400, v0
	ds_write2_b32 v66, v91, v75 offset0:68 offset1:100
	ds_write2_b32 v66, v92, v76 offset0:200 offset1:232
	v_add_u32_e32 v66, 0x6800, v0
	ds_write2_b32 v66, v93, v77 offset0:76 offset1:108
	v_add_u32_e32 v66, 0x7200, v0
	ds_write2_b32 v66, v94, v78 offset0:96 offset1:128
	v_add_u32_e32 v66, 0x7400, v0
	ds_write2_b32 v66, v95, v79 offset0:100 offset1:132
	v_add_u32_e32 v66, 0x7600, v0
	ds_write2_b32 v66, v96, v80 offset0:104 offset1:136
	v_add_u32_e32 v66, 0x7800, v0
	ds_write2_b32 v66, v97, v81 offset0:108 offset1:140
	v_add_u32_e32 v66, 0x8400, v0
	ds_write2_b32 v66, v50, v34 offset1:32
	ds_write2_b32 v66, v51, v35 offset0:132 offset1:164
	v_add_u32_e32 v34, 0x8800, v0
	ds_write2_b32 v34, v52, v36 offset0:8 offset1:40
	ds_write2_b32 v34, v53, v37 offset0:140 offset1:172
	v_add_u32_e32 v34, 0x9400, v0
	ds_write2_b32 v34, v54, v38 offset0:32 offset1:64
	ds_write2_b32 v34, v55, v39 offset0:164 offset1:196
	v_add_u32_e32 v34, 0x9800, v0
	ds_write2_b32 v34, v56, v40 offset0:40 offset1:72
	ds_write2_b32 v34, v57, v41 offset0:172 offset1:204
	v_add_u32_e32 v34, 0xa400, v0
	ds_write2_b32 v34, v58, v42 offset0:64 offset1:96
	ds_write2_b32 v34, v59, v43 offset0:196 offset1:228
	v_add_u32_e32 v34, 0xa800, v0
	ds_write2_b32 v34, v60, v44 offset0:72 offset1:104
	ds_write2_b32 v34, v61, v45 offset0:204 offset1:236
	v_add_u32_e32 v34, 0xb400, v0
	ds_write2_b32 v34, v62, v46 offset0:96 offset1:128
	v_add_u32_e32 v34, 0xb600, v0
	ds_write2_b32 v34, v63, v47 offset0:100 offset1:132
	v_add_u32_e32 v34, 0xb800, v0
	ds_write2_b32 v34, v64, v48 offset0:104 offset1:136
	v_add_u32_e32 v34, 0xba00, v0
	ds_write2_b32 v34, v65, v49 offset0:108 offset1:140
	v_add_u32_e32 v34, 0xc400, v0
	ds_write2_b32 v34, v18, v2 offset0:128 offset1:160
	v_add_u32_e32 v2, 0xc800, v0
	ds_write2_b32 v2, v19, v3 offset0:4 offset1:36
	ds_write2_b32 v2, v20, v4 offset0:136 offset1:168
	v_add_u32_e32 v2, 0xcc00, v0
	ds_write2_b32 v2, v21, v5 offset0:12 offset1:44
	v_add_u32_e32 v2, 0xd400, v0
	ds_write2_b32 v2, v22, v6 offset0:160 offset1:192
	v_add_u32_e32 v2, 0xd800, v0
	ds_write2_b32 v2, v23, v7 offset0:36 offset1:68
	ds_write2_b32 v2, v24, v8 offset0:168 offset1:200
	v_add_u32_e32 v2, 0xdc00, v0
	ds_write2_b32 v2, v25, v9 offset0:44 offset1:76
	v_add_u32_e32 v2, 0xe400, v0
	ds_write2_b32 v2, v26, v10 offset0:192 offset1:224
	v_add_u32_e32 v2, 0xe800, v0
	ds_write2_b32 v2, v27, v11 offset0:68 offset1:100
	ds_write2_b32 v2, v28, v12 offset0:200 offset1:232
	v_add_u32_e32 v2, 0xec00, v0
	ds_write2_b32 v2, v29, v13 offset0:76 offset1:108
	v_add_u32_e32 v2, 0xf600, v0
	ds_write2_b32 v2, v30, v14 offset0:96 offset1:128
	v_add_u32_e32 v2, 0xf800, v0
	ds_write2_b32 v2, v31, v15 offset0:100 offset1:132
	v_add_u32_e32 v2, 0xfa00, v0
	v_add_u32_e32 v0, 0xfc00, v0
	ds_write2_b32 v2, v32, v16 offset0:104 offset1:136
	ds_write2_b32 v0, v33, v17 offset0:108 offset1:140

; DI int otid() { int t = threadIdx.x; asm volatile("" : "+v"(t)); return t; }
; DI void gemm_res_tile_big(const bf16_t* A, int lda, const bf16_t* Bt, int K, const float* __restrict__ xin, float* __restrict__ xout,
;                           const float* __restrict__ gate, int mt, int nt, char* smem) {
;     ...
;   for (int h = 0; h < 2; ++h) {
;     const int tid = otid();
;     stage_half(st, acc, h, tid);
;     __syncthreads();
;     const int r = tid >> 5, ch = tid & 31;
;     const float4 g = *(const float4*)(gate + (size_t)b * 6144 + n0 + ch * 4);
; #pragma unroll 4
;     for (int ps = 0; ps < 16; ++ps) {
;       const int row = ps * 8 + r;
;       const float4 a = *(const float4*)(st + row * 132 + ch * 4);
;       const size_t off = (size_t)(m0 + h * 128 + row) * 1024 + n0 + ch * 4;
;       const float4 xi = *(const float4*)(xin + off);
;       float4 o; o.x = xi.x + g.x * a.x; o.y = xi.y + g.y * a.y; o.z = xi.z + g.z * a.z; o.w = xi.w + g.w * a.w;
;       *(float4*)(xout + off) = o;
;     }
;     __syncthreads();
.LBB0_1126:
	v_lshrrev_b32_e32 v215, 5, v216
	v_mul_u32_u24_e32 v182, 0x210, v215
	v_and_b32_e32 v215, 31, v216
	v_lshl_add_u32 v182, v215, 4, v182
	v_lshlrev_b32_e32 v184, 10, v12
	v_add_u32_e32 v184, v184, v8
	v_lshlrev_b32_e32 v184, 2, v184
	v_mov_b32_e32 v214, v184
	global_load_dwordx4 v[158:161], v184, s[24:25]
	s_nop 0
	v_add_u32_e32 v184, 0x8000, v184
	global_load_dwordx4 v[162:165], v184, s[24:25]
	s_nop 0
	v_add_u32_e32 v184, 0x8000, v184
	global_load_dwordx4 v[166:169], v184, s[24:25]
	s_nop 0
	v_add_u32_e32 v184, 0x8000, v184
	global_load_dwordx4 v[170:173], v184, s[24:25]
	s_nop 0
	v_add_u32_e32 v184, 0x8000, v184
	global_load_dwordx4 v[174:177], v184, s[24:25]
	s_nop 0
	v_add_u32_e32 v184, 0x8000, v184
	global_load_dwordx4 v[178:181], v184, s[24:25]
	s_nop 0
	v_add_u32_e32 v184, 0x8000, v184
	global_load_dwordx4 v[186:189], v184, s[24:25]
	s_nop 0
	v_add_u32_e32 v184, 0x8000, v184
	global_load_dwordx4 v[190:193], v184, s[24:25]
	s_nop 0
	v_add_u32_e32 v184, 0x8000, v184
	ds_read_b128 v[194:197], v182 offset:0
	ds_read_b128 v[198:201], v182 offset:4224
	ds_read_b128 v[202:205], v182 offset:8448
	ds_read_b128 v[210:213], v182 offset:12672
	s_waitcnt vmcnt(7) lgkmcnt(3)
	v_fma_f32 v158, v26, v194, v158
	v_fma_f32 v159, v2, v195, v159
	v_fma_f32 v160, v28, v196, v160
	v_fma_f32 v161, v4, v197, v161
	global_store_dwordx4 v214, v[158:161], s[84:85]
	s_nop 1
	v_add_u32_e32 v214, 0x8000, v214
	s_waitcnt vmcnt(7) lgkmcnt(2)
	v_fma_f32 v162, v26, v198, v162
	v_fma_f32 v163, v2, v199, v163
	v_fma_f32 v164, v28, v200, v164
	v_fma_f32 v165, v4, v201, v165
	global_store_dwordx4 v214, v[162:165], s[84:85]
	s_nop 1
	v_add_u32_e32 v214, 0x8000, v214
	s_waitcnt vmcnt(7) lgkmcnt(1)
	v_fma_f32 v166, v26, v202, v166
	v_fma_f32 v167, v2, v203, v167
	v_fma_f32 v168, v28, v204, v168
	v_fma_f32 v169, v4, v205, v169
	global_store_dwordx4 v214, v[166:169], s[84:85]
	s_nop 1
	v_add_u32_e32 v214, 0x8000, v214
	s_waitcnt vmcnt(7) lgkmcnt(0)
	v_fma_f32 v170, v26, v210, v170
	v_fma_f32 v171, v2, v211, v171
	v_fma_f32 v172, v28, v212, v172
	v_fma_f32 v173, v4, v213, v173
	global_store_dwordx4 v214, v[170:173], s[84:85]
	s_nop 1
	v_add_u32_e32 v214, 0x8000, v214
	ds_read_b128 v[194:197], v182 offset:16896
	ds_read_b128 v[198:201], v182 offset:21120
	ds_read_b128 v[202:205], v182 offset:25344
	ds_read_b128 v[210:213], v182 offset:29568
	s_waitcnt vmcnt(7) lgkmcnt(3)
	v_fma_f32 v174, v26, v194, v174
	v_fma_f32 v175, v2, v195, v175
	v_fma_f32 v176, v28, v196, v176
	v_fma_f32 v177, v4, v197, v177
	global_store_dwordx4 v214, v[174:177], s[84:85]
	s_nop 1
	v_add_u32_e32 v214, 0x8000, v214
	s_waitcnt vmcnt(7) lgkmcnt(2)
	v_fma_f32 v178, v26, v198, v178
	v_fma_f32 v179, v2, v199, v179
	v_fma_f32 v180, v28, v200, v180
	v_fma_f32 v181, v4, v201, v181
	global_store_dwordx4 v214, v[178:181], s[84:85]
	s_nop 1
	v_add_u32_e32 v214, 0x8000, v214
	s_waitcnt vmcnt(7) lgkmcnt(1)
	v_fma_f32 v186, v26, v202, v186
	v_fma_f32 v187, v2, v203, v187
	v_fma_f32 v188, v28, v204, v188
	v_fma_f32 v189, v4, v205, v189
	global_store_dwordx4 v214, v[186:189], s[84:85]
	s_nop 1
	v_add_u32_e32 v214, 0x8000, v214
	s_waitcnt vmcnt(7) lgkmcnt(0)
	v_fma_f32 v190, v26, v210, v190
	v_fma_f32 v191, v2, v211, v191
	v_fma_f32 v192, v28, v212, v192
	v_fma_f32 v193, v4, v213, v193
	global_store_dwordx4 v214, v[190:193], s[84:85]
	s_nop 1
	v_add_u32_e32 v214, 0x8000, v214
	global_load_dwordx4 v[158:161], v184, s[24:25]
	s_nop 0
	v_add_u32_e32 v184, 0x8000, v184
	global_load_dwordx4 v[162:165], v184, s[24:25]
	s_nop 0
	v_add_u32_e32 v184, 0x8000, v184
	global_load_dwordx4 v[166:169], v184, s[24:25]
	s_nop 0
	v_add_u32_e32 v184, 0x8000, v184
	global_load_dwordx4 v[170:173], v184, s[24:25]
	s_nop 0
	v_add_u32_e32 v184, 0x8000, v184
	global_load_dwordx4 v[174:177], v184, s[24:25]
	s_nop 0
	v_add_u32_e32 v184, 0x8000, v184
	global_load_dwordx4 v[178:181], v184, s[24:25]
	s_nop 0
	v_add_u32_e32 v184, 0x8000, v184
	global_load_dwordx4 v[186:189], v184, s[24:25]
	s_nop 0
	v_add_u32_e32 v184, 0x8000, v184
	global_load_dwordx4 v[190:193], v184, s[24:25]
	s_nop 0
	v_add_u32_e32 v184, 0x8000, v184
	ds_read_b128 v[194:197], v182 offset:33792
	ds_read_b128 v[198:201], v182 offset:38016
	ds_read_b128 v[202:205], v182 offset:42240
	ds_read_b128 v[210:213], v182 offset:46464
	s_waitcnt vmcnt(7) lgkmcnt(3)
	v_fma_f32 v158, v26, v194, v158
	v_fma_f32 v159, v2, v195, v159
	v_fma_f32 v160, v28, v196, v160
	v_fma_f32 v161, v4, v197, v161
	global_store_dwordx4 v214, v[158:161], s[84:85]
	s_nop 1
	v_add_u32_e32 v214, 0x8000, v214
	s_waitcnt vmcnt(7) lgkmcnt(2)
	v_fma_f32 v162, v26, v198, v162
	v_fma_f32 v163, v2, v199, v163
	v_fma_f32 v164, v28, v200, v164
	v_fma_f32 v165, v4, v201, v165
	global_store_dwordx4 v214, v[162:165], s[84:85]
	s_nop 1
	v_add_u32_e32 v214, 0x8000, v214
	s_waitcnt vmcnt(7) lgkmcnt(1)
	v_fma_f32 v166, v26, v202, v166
	v_fma_f32 v167, v2, v203, v167
	v_fma_f32 v168, v28, v204, v168
	v_fma_f32 v169, v4, v205, v169
	global_store_dwordx4 v214, v[166:169], s[84:85]
	s_nop 1
	v_add_u32_e32 v214, 0x8000, v214
	s_waitcnt vmcnt(7) lgkmcnt(0)
	v_fma_f32 v170, v26, v210, v170
	v_fma_f32 v171, v2, v211, v171
	v_fma_f32 v172, v28, v212, v172
	v_fma_f32 v173, v4, v213, v173
	global_store_dwordx4 v214, v[170:173], s[84:85]
	s_nop 1
	v_add_u32_e32 v214, 0x8000, v214
	ds_read_b128 v[194:197], v182 offset:50688
	ds_read_b128 v[198:201], v182 offset:54912
	ds_read_b128 v[202:205], v182 offset:59136
	ds_read_b128 v[210:213], v182 offset:63360
	s_waitcnt vmcnt(7) lgkmcnt(3)
	v_fma_f32 v174, v26, v194, v174
	v_fma_f32 v175, v2, v195, v175
	v_fma_f32 v176, v28, v196, v176
	v_fma_f32 v177, v4, v197, v177
	global_store_dwordx4 v214, v[174:177], s[84:85]
	s_nop 1
	v_add_u32_e32 v214, 0x8000, v214
	s_waitcnt vmcnt(7) lgkmcnt(2)
	v_fma_f32 v178, v26, v198, v178
	v_fma_f32 v179, v2, v199, v179
	v_fma_f32 v180, v28, v200, v180
	v_fma_f32 v181, v4, v201, v181
	global_store_dwordx4 v214, v[178:181], s[84:85]
	s_nop 1
	v_add_u32_e32 v214, 0x8000, v214
	s_waitcnt vmcnt(7) lgkmcnt(1)
	v_fma_f32 v186, v26, v202, v186
	v_fma_f32 v187, v2, v203, v187
	v_fma_f32 v188, v28, v204, v188
	v_fma_f32 v189, v4, v205, v189
	global_store_dwordx4 v214, v[186:189], s[84:85]
	s_nop 1
	v_add_u32_e32 v214, 0x8000, v214
	s_waitcnt vmcnt(7) lgkmcnt(0)
	v_fma_f32 v190, v26, v210, v190
	v_fma_f32 v191, v2, v211, v191
	v_fma_f32 v192, v28, v212, v192
	v_fma_f32 v193, v4, v213, v193
	global_store_dwordx4 v214, v[190:193], s[84:85]
	s_nop 1
	v_add_u32_e32 v214, 0x8000, v214
	s_barrier
	s_branch .LBB0_1115

; #define MFMA32(a, b, c) __builtin_amdgcn_mfma_f32_32x32x16_bf16((a), (b), (c), 0, 0, 0)
; DI void gemm_mainloop_big(const bf16_t* __restrict__ A, int lda, const bf16_t* __restrict__ Bt, int ldb, int K, int m0, int n0,
;                           f32x16 (&acc)[4][2], char* smem) {
;     ...
;   for (int kt = 0; kt < nk; ++kt) {
;     if (kt + 1 < nk) {
; #pragma unroll
;       for (int i = 0; i < 8; ++i) ra[i] = *(const u32x4*)(ap + (size_t)(32 * i) * lda + (kt + 1) * 64);
; #pragma unroll
;       for (int i = 0; i < 4; ++i) rb[i] = *(const u32x4*)(bp + (size_t)(32 * i) * ldb + (kt + 1) * 64);
;     }
; #pragma unroll
;     for (int ks = 0; ks < 4; ++ks) {
;       bf16x8 af[4], bfr[2];
; #pragma unroll
;       for (int f = 0; f < 4; ++f) af[f] = *(const bf16x8*)&sa[wm * 128 + f * 32 + r][ks * 16 + half * 8];
; #pragma unroll
;       for (int f = 0; f < 2; ++f) bfr[f] = *(const bf16x8*)&sb[wn * 64 + f * 32 + r][ks * 16 + half * 8];
; #pragma unroll
;       for (int mf = 0; mf < 4; ++mf)
; #pragma unroll
;         for (int nf = 0; nf < 2; ++nf) acc[mf][nf] = MFMA32(af[mf], bfr[nf], acc[mf][nf]);
;     }
.LBB0_1240:
	ds_read_b128 v[130:133], v139
	ds_read_b128 v[134:137], v0 offset:36864
	ds_read_b128 v[144:147], v139 offset:32
	ds_read_b128 v[148:151], v0 offset:36896
	ds_read_b128 v[152:155], v0 offset:41472
	ds_read_b128 v[156:159], v0 offset:41504
	s_mov_b32 s9, 0xdc0000
	s_waitcnt lgkmcnt(4)
	v_mfma_f32_32x32x16_bf16 v[114:129], v[130:133], v[134:137], v[114:129]
	s_waitcnt lgkmcnt(1)
	v_mfma_f32_32x32x16_bf16 v[98:113], v[130:133], v[152:155], v[98:113]
	ds_read_b128 v[130:133], v139 offset:4608
	ds_read_b128 v[160:163], v139 offset:4640
	s_waitcnt lgkmcnt(1)
	v_mfma_f32_32x32x16_bf16 v[82:97], v[130:133], v[134:137], v[82:97]
	v_mfma_f32_32x32x16_bf16 v[66:81], v[130:133], v[152:155], v[66:81]
	ds_read_b128 v[130:133], v139 offset:9216
	ds_read_b128 v[164:167], v139 offset:9248
	s_waitcnt lgkmcnt(1)
	v_mfma_f32_32x32x16_bf16 v[50:65], v[130:133], v[134:137], v[50:65]
	v_mfma_f32_32x32x16_bf16 v[34:49], v[130:133], v[152:155], v[34:49]
	ds_read_b128 v[130:133], v139 offset:13824
	ds_read_b128 v[168:171], v139 offset:13856
	s_waitcnt lgkmcnt(1)
	v_mfma_f32_32x32x16_bf16 v[18:33], v[130:133], v[134:137], v[18:33]
	v_mfma_f32_32x32x16_bf16 v[2:17], v[130:133], v[152:155], v[2:17]
	v_mfma_f32_32x32x16_bf16 v[114:129], v[144:147], v[148:151], v[114:129]
	v_mfma_f32_32x32x16_bf16 v[98:113], v[144:147], v[156:159], v[98:113]
	v_mfma_f32_32x32x16_bf16 v[82:97], v[160:163], v[148:151], v[82:97]
	v_mfma_f32_32x32x16_bf16 v[66:81], v[160:163], v[156:159], v[66:81]
	v_mfma_f32_32x32x16_bf16 v[50:65], v[164:167], v[148:151], v[50:65]
	v_mfma_f32_32x32x16_bf16 v[34:49], v[164:167], v[156:159], v[34:49]
	s_waitcnt lgkmcnt(0)
	v_mfma_f32_32x32x16_bf16 v[18:33], v[168:171], v[148:151], v[18:33]
	ds_read_b128 v[134:137], v139 offset:64
	ds_read_b128 v[144:147], v0 offset:36928
	ds_read_b128 v[148:151], v139 offset:96
	ds_read_b128 v[152:155], v0 offset:36960
	v_mfma_f32_32x32x16_bf16 v[2:17], v[168:171], v[156:159], v[2:17]
	ds_read_b128 v[156:159], v0 offset:41536
	ds_read_b128 v[130:133], v0 offset:41568
	s_waitcnt lgkmcnt(4)
	v_mfma_f32_32x32x16_bf16 v[114:129], v[134:137], v[144:147], v[114:129]
	s_waitcnt lgkmcnt(1)
	v_mfma_f32_32x32x16_bf16 v[98:113], v[134:137], v[156:159], v[98:113]
	ds_read_b128 v[134:137], v139 offset:4672
	ds_read_b128 v[160:163], v139 offset:4704
	s_waitcnt lgkmcnt(1)
	v_mfma_f32_32x32x16_bf16 v[82:97], v[134:137], v[144:147], v[82:97]
	v_mfma_f32_32x32x16_bf16 v[66:81], v[134:137], v[156:159], v[66:81]
	ds_read_b128 v[134:137], v139 offset:9280
	ds_read_b128 v[164:167], v139 offset:9312
	s_waitcnt lgkmcnt(1)
	v_mfma_f32_32x32x16_bf16 v[50:65], v[134:137], v[144:147], v[50:65]
	v_mfma_f32_32x32x16_bf16 v[34:49], v[134:137], v[156:159], v[34:49]
	ds_read_b128 v[168:171], v139 offset:13888
	ds_read_b128 v[134:137], v139 offset:13920
	s_waitcnt lgkmcnt(1)
	v_mfma_f32_32x32x16_bf16 v[18:33], v[168:171], v[144:147], v[18:33]
	v_lshl_add_u64 v[144:145], v[140:141], 0, s[26:27]
	v_add_co_u32_e32 v172, vcc, s87, v144
	v_lshl_add_u64 v[146:147], v[142:143], 0, s[26:27]
	s_nop 0
	v_addc_co_u32_e32 v173, vcc, 0, v145, vcc
	s_add_u32 s26, s26, 0x80
	v_mfma_f32_32x32x16_bf16 v[2:17], v[168:171], v[156:159], v[2:17]
	v_add_co_u32_e32 v156, vcc, s2, v144
	s_addc_u32 s27, s27, 0
	s_nop 0
	v_addc_co_u32_e32 v157, vcc, 0, v145, vcc
	v_add_co_u32_e32 v158, vcc, s3, v144
	v_mfma_f32_32x32x16_bf16 v[114:129], v[148:151], v[152:155], v[114:129]
	s_nop 0
	v_addc_co_u32_e32 v159, vcc, 0, v145, vcc
	v_add_co_u32_e32 v168, vcc, s88, v144
	s_cmpk_lg_i32 s26, 0x780
	s_nop 0
	v_addc_co_u32_e32 v169, vcc, 0, v145, vcc
	v_add_co_u32_e32 v170, vcc, s89, v144
	v_mfma_f32_32x32x16_bf16 v[98:113], v[148:151], v[130:133], v[98:113]
	s_nop 0
	v_addc_co_u32_e32 v171, vcc, 0, v145, vcc
	v_add_co_u32_e32 v174, vcc, s4, v144
	s_nop 1
	v_addc_co_u32_e32 v175, vcc, 0, v145, vcc
	v_add_co_u32_e32 v176, vcc, s5, v144
	v_mfma_f32_32x32x16_bf16 v[82:97], v[160:163], v[152:155], v[82:97]
	s_nop 0
	v_addc_co_u32_e32 v177, vcc, 0, v145, vcc
	v_add_co_u32_e32 v178, vcc, s86, v144
	s_nop 1
	v_addc_co_u32_e32 v179, vcc, 0, v145, vcc
	v_add_co_u32_e32 v180, vcc, s9, v146
	s_mov_b32 s9, 0xdd0000
	s_nop 0
	v_addc_co_u32_e32 v181, vcc, 0, v147, vcc
	v_add_co_u32_e32 v190, vcc, s9, v146
	s_mov_b32 s9, 0xde0000
	s_nop 0
	v_addc_co_u32_e32 v191, vcc, 0, v147, vcc
	v_add_co_u32_e32 v194, vcc, s9, v146
	s_mov_b32 s9, 0xdf0000
	s_nop 0
	v_addc_co_u32_e32 v195, vcc, 0, v147, vcc
	v_add_co_u32_e32 v198, vcc, s9, v146
	v_mfma_f32_32x32x16_bf16 v[66:81], v[160:163], v[130:133], v[66:81]
	s_nop 0
	v_addc_co_u32_e32 v199, vcc, 0, v147, vcc
	global_load_dwordx4 v[144:147], v[172:173], off offset:128
	global_load_dwordx4 v[148:151], v[156:157], off offset:128
	s_nop 0
	global_load_dwordx4 v[156:159], v[158:159], off offset:128
	s_nop 0
	global_load_dwordx4 v[160:163], v[168:169], off offset:128
	v_mfma_f32_32x32x16_bf16 v[50:65], v[164:167], v[152:155], v[50:65]
	v_mfma_f32_32x32x16_bf16 v[34:49], v[164:167], v[130:133], v[34:49]
	global_load_dwordx4 v[164:167], v[170:171], off offset:128
	s_nop 0
	global_load_dwordx4 v[168:171], v[174:175], off offset:128
	s_nop 0
	global_load_dwordx4 v[172:175], v[176:177], off offset:128
	s_nop 0
	global_load_dwordx4 v[176:179], v[178:179], off offset:128
	s_nop 0
	global_load_dwordx4 v[186:189], v[180:181], off offset:128
	s_nop 0
	global_load_dwordx4 v[190:193], v[190:191], off offset:128
	s_nop 0
	global_load_dwordx4 v[194:197], v[194:195], off offset:128
	s_waitcnt lgkmcnt(0)
	v_mfma_f32_32x32x16_bf16 v[18:33], v[134:137], v[152:155], v[18:33]
	global_load_dwordx4 v[152:155], v[198:199], off offset:128
	s_barrier
; DI unsigned pk2(float a, float b) { f32x2 v = {a, b}; bf2_t r = __builtin_convertvector(v, bf2_t); return __builtin_bit_cast(unsigned, r); }
; DI int crow(int i, int h) { return (i & 3) + 8 * (i >> 2) + 4 * h; }
; DI void gemm_mainloop_big(const bf16_t* __restrict__ A, int lda, const bf16_t* __restrict__ Bt, int ldb, int K, int m0, int n0,
;                           f32x16 (&acc)[4][2], char* smem) {
;     ...
;     __syncthreads();
;     if (kt + 1 < nk) {
; #pragma unroll
;       for (int i = 0; i < 8; ++i) *(u32x4*)&sa[(tid >> 3) + 32 * i][(tid & 7) * 8] = ra[i];
; #pragma unroll
;       for (int i = 0; i < 4; ++i) *(u32x4*)&sb[(tid >> 3) + 32 * i][(tid & 7) * 8] = rb[i];
;     }
;     __syncthreads();
; DI void gemm_ffi_tile_big(const Params& p, int l, int mt, int nt, char* smem) {
;     ...
; #pragma unroll
;   for (int mf = 0; mf < 4; ++mf)
; #pragma unroll
;     for (int i = 0; i < 16; ++i) {
;       const float g = acc[mf][0][i], u = acc[mf][1][i];
;       const float a = g * __builtin_amdgcn_rcpf(1.f + __expf(-g)) * u;
;       sbt[wm * 128 + mf * 32 + crow(i, half)][wn * 32 + c] = (bf16_t)(pk2(a, 0.f) & 0xffff);
	s_waitcnt vmcnt(11)
	ds_write_b128 v138, v[144:147]
	s_waitcnt vmcnt(10)
	ds_write_b128 v138, v[148:151] offset:4608
	s_waitcnt vmcnt(9)
	ds_write_b128 v138, v[156:159] offset:9216
	s_waitcnt vmcnt(8)
	ds_write_b128 v138, v[160:163] offset:13824
	s_waitcnt vmcnt(7)
	ds_write_b128 v138, v[164:167] offset:18432
	s_waitcnt vmcnt(6)
	ds_write_b128 v138, v[168:171] offset:23040
	s_waitcnt vmcnt(5)
	ds_write_b128 v138, v[172:175] offset:27648
	s_waitcnt vmcnt(4)
	ds_write_b128 v138, v[176:179] offset:32256
	s_waitcnt vmcnt(3)
	ds_write_b128 v138, v[186:189] offset:36864
	s_waitcnt vmcnt(2)
	ds_write_b128 v138, v[190:193] offset:41472
	s_waitcnt vmcnt(1)
	ds_write_b128 v138, v[194:197] offset:46080
	s_waitcnt vmcnt(0)
	ds_write_b128 v138, v[152:155] offset:50688
	v_mfma_f32_32x32x16_bf16 v[2:17], v[134:137], v[130:133], v[2:17]
	s_waitcnt lgkmcnt(0)
	s_barrier
	s_cbranch_scc1 .LBB0_1240
	ds_read_b128 v[130:133], v139 offset:4608
	ds_read_b128 v[134:137], v139 offset:9216
	ds_read_b128 v[140:143], v139 offset:13824
	ds_read_b128 v[144:147], v0 offset:41472
	ds_read_b128 v[148:151], v139
	ds_read_b128 v[152:155], v139 offset:32
	ds_read_b128 v[156:159], v0 offset:36864
	ds_read_b128 v[160:163], v0 offset:36896
	s_waitcnt lgkmcnt(4)
	v_mfma_f32_32x32x16_bf16 v[66:81], v[130:133], v[144:147], v[66:81]
	s_movk_i32 s9, 0x90
	s_lshl_b32 s26, s43, 6
	s_ashr_i32 s27, s26, 31
	s_lshl_b64 s[26:27], s[26:27], 1
	v_readlane_b32 s44, v244, 24
	v_readlane_b32 s45, v244, 25
	s_add_u32 s26, s44, s26
	s_waitcnt lgkmcnt(1)
	v_mfma_f32_32x32x16_bf16 v[114:129], v[148:151], v[156:159], v[114:129]
	s_addc_u32 s27, s45, s27
	v_mfma_f32_32x32x16_bf16 v[98:113], v[148:151], v[144:147], v[98:113]
	v_mfma_f32_32x32x16_bf16 v[82:97], v[130:133], v[156:159], v[82:97]
	v_mfma_f32_32x32x16_bf16 v[50:65], v[134:137], v[156:159], v[50:65]
	v_mfma_f32_32x32x16_bf16 v[34:49], v[134:137], v[144:147], v[34:49]
	v_mfma_f32_32x32x16_bf16 v[18:33], v[140:143], v[156:159], v[18:33]
	v_mfma_f32_32x32x16_bf16 v[2:17], v[140:143], v[144:147], v[2:17]
	ds_read_b128 v[130:133], v139 offset:4640
	ds_read_b128 v[134:137], v139 offset:9248
	ds_read_b128 v[140:143], v139 offset:13856
	ds_read_b128 v[144:147], v0 offset:41504
	s_waitcnt lgkmcnt(4)
	v_mfma_f32_32x32x16_bf16 v[114:129], v[152:155], v[160:163], v[114:129]
	s_waitcnt lgkmcnt(0)
	v_mfma_f32_32x32x16_bf16 v[98:113], v[152:155], v[144:147], v[98:113]
	v_mfma_f32_32x32x16_bf16 v[82:97], v[130:133], v[160:163], v[82:97]
	v_mfma_f32_32x32x16_bf16 v[66:81], v[130:133], v[144:147], v[66:81]
	v_mfma_f32_32x32x16_bf16 v[50:65], v[134:137], v[160:163], v[50:65]
	v_mfma_f32_32x32x16_bf16 v[34:49], v[134:137], v[144:147], v[34:49]
	v_mfma_f32_32x32x16_bf16 v[18:33], v[140:143], v[160:163], v[18:33]
	v_mfma_f32_32x32x16_bf16 v[2:17], v[140:143], v[144:147], v[2:17]
	ds_read_b128 v[130:133], v139 offset:64
	ds_read_b128 v[134:137], v139 offset:4672
	ds_read_b128 v[140:143], v139 offset:9280
	ds_read_b128 v[144:147], v139 offset:13888
	ds_read_b128 v[148:151], v0 offset:36928
	ds_read_b128 v[152:155], v0 offset:41536
	s_waitcnt lgkmcnt(1)
	v_mfma_f32_32x32x16_bf16 v[114:129], v[130:133], v[148:151], v[114:129]
	s_waitcnt lgkmcnt(0)
	v_mfma_f32_32x32x16_bf16 v[98:113], v[130:133], v[152:155], v[98:113]
	v_mfma_f32_32x32x16_bf16 v[82:97], v[134:137], v[148:151], v[82:97]
	v_mfma_f32_32x32x16_bf16 v[66:81], v[134:137], v[152:155], v[66:81]
	v_mfma_f32_32x32x16_bf16 v[50:65], v[140:143], v[148:151], v[50:65]
	v_mfma_f32_32x32x16_bf16 v[34:49], v[140:143], v[152:155], v[34:49]
	v_mfma_f32_32x32x16_bf16 v[18:33], v[144:147], v[148:151], v[18:33]
	v_mfma_f32_32x32x16_bf16 v[2:17], v[144:147], v[152:155], v[2:17]
	ds_read_b128 v[130:133], v139 offset:96
	ds_read_b128 v[134:137], v139 offset:4704
	ds_read_b128 v[140:143], v139 offset:9312
	ds_read_b128 v[144:147], v139 offset:13920
	ds_read_b128 v[148:151], v0 offset:36960
	ds_read_b128 v[152:155], v0 offset:41568
	v_mov_b32_e32 v0, v216
	s_waitcnt lgkmcnt(0)
	s_barrier
	s_barrier
	v_mfma_f32_32x32x16_bf16 v[114:129], v[130:133], v[148:151], v[114:129]
	v_mfma_f32_32x32x16_bf16 v[98:113], v[130:133], v[152:155], v[98:113]
	s_nop 10
	v_mul_f32_e32 v133, 0xbfb8aa3b, v114
	v_exp_f32_e32 v133, v133
	v_lshrrev_b32_e32 v132, 3, v0
	v_and_b32_e32 v131, 0xfffff80, v0
	v_and_b32_e32 v132, 4, v132
	v_add_f32_e32 v133, 1.0, v133
	v_rcp_f32_e32 v133, v133
	v_mul_lo_u32 v131, v131, s9
	v_and_b32_e32 v130, 31, v0
	v_mfma_f32_32x32x16_bf16 v[82:97], v[134:137], v[148:151], v[82:97]
	v_mul_f32_e32 v114, v114, v133
	v_mul_f32_e32 v98, v98, v114
	v_cvt_pk_bf16_f32 v114, v98, s0
	v_mul_u32_u24_e32 v98, 0x90, v132
	v_or_b32_e32 v98, v131, v98
	v_and_b32_e32 v131, 64, v0
	v_add_u32_e32 v98, v98, v131
	v_lshl_or_b32 v98, v130, 1, v98
	ds_write_b16 v98, v114
	v_mul_f32_e32 v114, 0xbfb8aa3b, v115
	v_exp_f32_e32 v114, v114
	v_mfma_f32_32x32x16_bf16 v[66:81], v[134:137], v[152:155], v[66:81]
	v_add_f32_e32 v114, 1.0, v114
	v_rcp_f32_e32 v114, v114
	s_nop 0
	v_mul_f32_e32 v114, v115, v114
	v_mul_f32_e32 v99, v99, v114
	v_cvt_pk_bf16_f32 v99, v99, s0
	ds_write_b16 v98, v99 offset:144
	v_mul_f32_e32 v99, 0xbfb8aa3b, v116
	v_exp_f32_e32 v99, v99
	v_mfma_f32_32x32x16_bf16 v[50:65], v[140:143], v[148:151], v[50:65]
	v_add_f32_e32 v99, 1.0, v99
	v_rcp_f32_e32 v99, v99
	s_nop 0
	v_mul_f32_e32 v99, v116, v99
	v_mul_f32_e32 v99, v100, v99
	v_cvt_pk_bf16_f32 v99, v99, s0
	ds_write_b16 v98, v99 offset:288
	v_mul_f32_e32 v99, 0xbfb8aa3b, v117
	v_exp_f32_e32 v99, v99
	v_mfma_f32_32x32x16_bf16 v[34:49], v[140:143], v[152:155], v[34:49]
	v_add_f32_e32 v99, 1.0, v99
	v_rcp_f32_e32 v99, v99
	s_nop 0
	v_mul_f32_e32 v99, v117, v99
	v_mul_f32_e32 v99, v101, v99
; DI unsigned pk2(float a, float b) { f32x2 v = {a, b}; bf2_t r = __builtin_convertvector(v, bf2_t); return __builtin_bit_cast(unsigned, r); }
; DI int crow(int i, int h) { return (i & 3) + 8 * (i >> 2) + 4 * h; }
; DI void gemm_ffi_tile_big(const Params& p, int l, int mt, int nt, char* smem) {
;     ...
; #pragma unroll
;   for (int mf = 0; mf < 4; ++mf)
; #pragma unroll
;     for (int i = 0; i < 16; ++i) {
;       const float g = acc[mf][0][i], u = acc[mf][1][i];
;       const float a = g * __builtin_amdgcn_rcpf(1.f + __expf(-g)) * u;
;       sbt[wm * 128 + mf * 32 + crow(i, half)][wn * 32 + c] = (bf16_t)(pk2(a, 0.f) & 0xffff);
	v_cvt_pk_bf16_f32 v99, v99, s0
	ds_write_b16 v98, v99 offset:432
	v_mul_f32_e32 v99, 0xbfb8aa3b, v118
	v_exp_f32_e32 v99, v99
	v_mfma_f32_32x32x16_bf16 v[18:33], v[144:147], v[148:151], v[18:33]
	v_add_f32_e32 v99, 1.0, v99
	v_rcp_f32_e32 v99, v99
	s_nop 0
	v_mul_f32_e32 v99, v118, v99
	v_mul_f32_e32 v99, v102, v99
	v_cvt_pk_bf16_f32 v99, v99, s0
	ds_write_b16 v98, v99 offset:1152
	v_mul_f32_e32 v99, 0xbfb8aa3b, v119
	v_exp_f32_e32 v99, v99
	v_mfma_f32_32x32x16_bf16 v[2:17], v[144:147], v[152:155], v[2:17]
	v_add_f32_e32 v99, 1.0, v99
	v_rcp_f32_e32 v99, v99
	s_nop 0
	v_mul_f32_e32 v99, v119, v99
	v_mul_f32_e32 v99, v103, v99
	v_cvt_pk_bf16_f32 v99, v99, s0
	ds_write_b16 v98, v99 offset:1296
	v_mul_f32_e32 v99, 0xbfb8aa3b, v120
	v_exp_f32_e32 v99, v99
	s_nop 0
	v_add_f32_e32 v99, 1.0, v99
	v_rcp_f32_e32 v99, v99
	s_nop 0
	v_mul_f32_e32 v99, v120, v99
	v_mul_f32_e32 v99, v104, v99
	v_cvt_pk_bf16_f32 v99, v99, s0
	ds_write_b16 v98, v99 offset:1440
	v_mul_f32_e32 v99, 0xbfb8aa3b, v121
	v_exp_f32_e32 v99, v99
	s_nop 0
	v_add_f32_e32 v99, 1.0, v99
	v_rcp_f32_e32 v99, v99
	s_nop 0
	v_mul_f32_e32 v99, v121, v99
	v_mul_f32_e32 v99, v105, v99
	v_cvt_pk_bf16_f32 v99, v99, s0
	ds_write_b16 v98, v99 offset:1584
	v_mul_f32_e32 v99, 0xbfb8aa3b, v122
	v_exp_f32_e32 v99, v99
	s_nop 0
	v_add_f32_e32 v99, 1.0, v99
	v_rcp_f32_e32 v99, v99
	s_nop 0
	v_mul_f32_e32 v99, v122, v99
	v_mul_f32_e32 v99, v106, v99
	v_cvt_pk_bf16_f32 v99, v99, s0
	ds_write_b16 v98, v99 offset:2304
	v_mul_f32_e32 v99, 0xbfb8aa3b, v123
	v_exp_f32_e32 v99, v99
	s_nop 0
	v_add_f32_e32 v99, 1.0, v99
	v_rcp_f32_e32 v99, v99
	s_nop 0
	v_mul_f32_e32 v99, v123, v99
	v_mul_f32_e32 v99, v107, v99
	v_cvt_pk_bf16_f32 v99, v99, s0
	ds_write_b16 v98, v99 offset:2448
	v_mul_f32_e32 v99, 0xbfb8aa3b, v124
	v_exp_f32_e32 v99, v99
	s_nop 0
	v_add_f32_e32 v99, 1.0, v99
	v_rcp_f32_e32 v99, v99
	s_nop 0
	v_mul_f32_e32 v99, v124, v99
	v_mul_f32_e32 v99, v108, v99
	v_cvt_pk_bf16_f32 v99, v99, s0
	ds_write_b16 v98, v99 offset:2592
	v_mul_f32_e32 v99, 0xbfb8aa3b, v125
	v_exp_f32_e32 v99, v99
	s_nop 0
	v_add_f32_e32 v99, 1.0, v99
	v_rcp_f32_e32 v99, v99
	s_nop 0
	v_mul_f32_e32 v99, v125, v99
	v_mul_f32_e32 v99, v109, v99
	v_cvt_pk_bf16_f32 v99, v99, s0
	ds_write_b16 v98, v99 offset:2736
	v_mul_f32_e32 v99, 0xbfb8aa3b, v126
	v_exp_f32_e32 v99, v99
	s_nop 0
	v_add_f32_e32 v99, 1.0, v99
	v_rcp_f32_e32 v99, v99
	s_nop 0
	v_mul_f32_e32 v99, v126, v99
	v_mul_f32_e32 v99, v110, v99
	v_cvt_pk_bf16_f32 v99, v99, s0
	ds_write_b16 v98, v99 offset:3456
	v_mul_f32_e32 v99, 0xbfb8aa3b, v127
	v_exp_f32_e32 v99, v99
	s_nop 0
	v_add_f32_e32 v99, 1.0, v99
	v_rcp_f32_e32 v99, v99
	s_nop 0
	v_mul_f32_e32 v99, v127, v99
	v_mul_f32_e32 v99, v111, v99
	v_cvt_pk_bf16_f32 v99, v99, s0
	ds_write_b16 v98, v99 offset:3600
	v_mul_f32_e32 v99, 0xbfb8aa3b, v128
	v_exp_f32_e32 v99, v99
	s_nop 0
	v_add_f32_e32 v99, 1.0, v99
	v_rcp_f32_e32 v99, v99
	s_nop 0
	v_mul_f32_e32 v99, v128, v99
	v_mul_f32_e32 v99, v112, v99
	v_cvt_pk_bf16_f32 v99, v99, s0
	ds_write_b16 v98, v99 offset:3744
	v_mul_f32_e32 v99, 0xbfb8aa3b, v129
	v_exp_f32_e32 v99, v99
	s_nop 0
	v_add_f32_e32 v99, 1.0, v99
	v_rcp_f32_e32 v99, v99
	s_nop 0
	v_mul_f32_e32 v99, v129, v99
	v_mul_f32_e32 v99, v113, v99
	v_cvt_pk_bf16_f32 v99, v99, s0
	ds_write_b16 v98, v99 offset:3888
	v_mul_f32_e32 v99, 0xbfb8aa3b, v82
	v_exp_f32_e32 v99, v99
	s_nop 0
	v_add_f32_e32 v99, 1.0, v99
	v_rcp_f32_e32 v99, v99
	s_nop 0
	v_mul_f32_e32 v82, v82, v99
	v_mul_f32_e32 v66, v66, v82
	v_cvt_pk_bf16_f32 v66, v66, s0
	ds_write_b16 v98, v66 offset:4608
	v_mul_f32_e32 v66, 0xbfb8aa3b, v83
	v_exp_f32_e32 v66, v66
	s_nop 0
	v_add_f32_e32 v66, 1.0, v66
	v_rcp_f32_e32 v66, v66
	s_nop 0
	v_mul_f32_e32 v66, v83, v66
	v_mul_f32_e32 v66, v67, v66
	v_cvt_pk_bf16_f32 v66, v66, s0
	ds_write_b16 v98, v66 offset:4752
	v_mul_f32_e32 v66, 0xbfb8aa3b, v84
	v_exp_f32_e32 v66, v66
	s_nop 0
	v_add_f32_e32 v66, 1.0, v66
	v_rcp_f32_e32 v66, v66
	s_nop 0
	v_mul_f32_e32 v66, v84, v66
	v_mul_f32_e32 v66, v68, v66
	v_cvt_pk_bf16_f32 v66, v66, s0
	ds_write_b16 v98, v66 offset:4896
	v_mul_f32_e32 v66, 0xbfb8aa3b, v85
	v_exp_f32_e32 v66, v66
	s_nop 0
	v_add_f32_e32 v66, 1.0, v66
	v_rcp_f32_e32 v66, v66
	s_nop 0
	v_mul_f32_e32 v66, v85, v66
	v_mul_f32_e32 v66, v69, v66
	v_cvt_pk_bf16_f32 v66, v66, s0
	ds_write_b16 v98, v66 offset:5040
	v_mul_f32_e32 v66, 0xbfb8aa3b, v86
	v_exp_f32_e32 v66, v66
	s_nop 0
	v_add_f32_e32 v66, 1.0, v66
	v_rcp_f32_e32 v66, v66
	s_nop 0
	v_mul_f32_e32 v66, v86, v66
	v_mul_f32_e32 v66, v70, v66
	v_cvt_pk_bf16_f32 v66, v66, s0
	ds_write_b16 v98, v66 offset:5760
	v_mul_f32_e32 v66, 0xbfb8aa3b, v87
	v_exp_f32_e32 v66, v66
	s_nop 0
	v_add_f32_e32 v66, 1.0, v66
	v_rcp_f32_e32 v66, v66
	s_nop 0
	v_mul_f32_e32 v66, v87, v66
	v_mul_f32_e32 v66, v71, v66
	v_cvt_pk_bf16_f32 v66, v66, s0
	ds_write_b16 v98, v66 offset:5904
	v_mul_f32_e32 v66, 0xbfb8aa3b, v88
	v_exp_f32_e32 v66, v66
	s_nop 0
	v_add_f32_e32 v66, 1.0, v66
	v_rcp_f32_e32 v66, v66
	s_nop 0
	v_mul_f32_e32 v66, v88, v66
	v_mul_f32_e32 v66, v72, v66
	v_cvt_pk_bf16_f32 v66, v66, s0
	ds_write_b16 v98, v66 offset:6048
	v_mul_f32_e32 v66, 0xbfb8aa3b, v89
	v_exp_f32_e32 v66, v66
	s_nop 0
	v_add_f32_e32 v66, 1.0, v66
	v_rcp_f32_e32 v66, v66
	s_nop 0
	v_mul_f32_e32 v66, v89, v66
	v_mul_f32_e32 v66, v73, v66
	v_cvt_pk_bf16_f32 v66, v66, s0
	ds_write_b16 v98, v66 offset:6192
	v_mul_f32_e32 v66, 0xbfb8aa3b, v90
	v_exp_f32_e32 v66, v66
	s_nop 0
	v_add_f32_e32 v66, 1.0, v66
	v_rcp_f32_e32 v66, v66
	s_nop 0
	v_mul_f32_e32 v66, v90, v66
	v_mul_f32_e32 v66, v74, v66
	v_cvt_pk_bf16_f32 v66, v66, s0
	ds_write_b16 v98, v66 offset:6912
	v_mul_f32_e32 v66, 0xbfb8aa3b, v91
; DI unsigned pk2(float a, float b) { f32x2 v = {a, b}; bf2_t r = __builtin_convertvector(v, bf2_t); return __builtin_bit_cast(unsigned, r); }
; DI int crow(int i, int h) { return (i & 3) + 8 * (i >> 2) + 4 * h; }
; DI void gemm_ffi_tile_big(const Params& p, int l, int mt, int nt, char* smem) {
;     ...
; #pragma unroll
;   for (int mf = 0; mf < 4; ++mf)
; #pragma unroll
;     for (int i = 0; i < 16; ++i) {
;       const float g = acc[mf][0][i], u = acc[mf][1][i];
;       const float a = g * __builtin_amdgcn_rcpf(1.f + __expf(-g)) * u;
;       sbt[wm * 128 + mf * 32 + crow(i, half)][wn * 32 + c] = (bf16_t)(pk2(a, 0.f) & 0xffff);
	v_exp_f32_e32 v66, v66
	s_nop 0
	v_add_f32_e32 v66, 1.0, v66
	v_rcp_f32_e32 v66, v66
	s_nop 0
	v_mul_f32_e32 v66, v91, v66
	v_mul_f32_e32 v66, v75, v66
	v_cvt_pk_bf16_f32 v66, v66, s0
	ds_write_b16 v98, v66 offset:7056
	v_mul_f32_e32 v66, 0xbfb8aa3b, v92
	v_exp_f32_e32 v66, v66
	s_nop 0
	v_add_f32_e32 v66, 1.0, v66
	v_rcp_f32_e32 v66, v66
	s_nop 0
	v_mul_f32_e32 v66, v92, v66
	v_mul_f32_e32 v66, v76, v66
	v_cvt_pk_bf16_f32 v66, v66, s0
	ds_write_b16 v98, v66 offset:7200
	v_mul_f32_e32 v66, 0xbfb8aa3b, v93
	v_exp_f32_e32 v66, v66
	s_nop 0
	v_add_f32_e32 v66, 1.0, v66
	v_rcp_f32_e32 v66, v66
	s_nop 0
	v_mul_f32_e32 v66, v93, v66
	v_mul_f32_e32 v66, v77, v66
	v_cvt_pk_bf16_f32 v66, v66, s0
	ds_write_b16 v98, v66 offset:7344
	v_mul_f32_e32 v66, 0xbfb8aa3b, v94
	v_exp_f32_e32 v66, v66
	s_nop 0
	v_add_f32_e32 v66, 1.0, v66
	v_rcp_f32_e32 v66, v66
	s_nop 0
	v_mul_f32_e32 v66, v94, v66
	v_mul_f32_e32 v66, v78, v66
	v_cvt_pk_bf16_f32 v66, v66, s0
	ds_write_b16 v98, v66 offset:8064
	v_mul_f32_e32 v66, 0xbfb8aa3b, v95
	v_exp_f32_e32 v66, v66
	s_nop 0
	v_add_f32_e32 v66, 1.0, v66
	v_rcp_f32_e32 v66, v66
	s_nop 0
	v_mul_f32_e32 v66, v95, v66
	v_mul_f32_e32 v66, v79, v66
	v_cvt_pk_bf16_f32 v66, v66, s0
	ds_write_b16 v98, v66 offset:8208
	v_mul_f32_e32 v66, 0xbfb8aa3b, v96
	v_exp_f32_e32 v66, v66
	s_nop 0
	v_add_f32_e32 v66, 1.0, v66
	v_rcp_f32_e32 v66, v66
	s_nop 0
	v_mul_f32_e32 v66, v96, v66
	v_mul_f32_e32 v66, v80, v66
	v_cvt_pk_bf16_f32 v66, v66, s0
	ds_write_b16 v98, v66 offset:8352
	v_mul_f32_e32 v66, 0xbfb8aa3b, v97
	v_exp_f32_e32 v66, v66
	s_nop 0
	v_add_f32_e32 v66, 1.0, v66
	v_rcp_f32_e32 v66, v66
	s_nop 0
	v_mul_f32_e32 v66, v97, v66
	v_mul_f32_e32 v66, v81, v66
	v_cvt_pk_bf16_f32 v66, v66, s0
	ds_write_b16 v98, v66 offset:8496
	v_mul_f32_e32 v66, 0xbfb8aa3b, v50
	v_exp_f32_e32 v66, v66
	s_nop 0
	v_add_f32_e32 v66, 1.0, v66
	v_rcp_f32_e32 v66, v66
	s_nop 0
	v_mul_f32_e32 v50, v50, v66
	v_mul_f32_e32 v34, v34, v50
	v_cvt_pk_bf16_f32 v34, v34, s0
	ds_write_b16 v98, v34 offset:9216
	v_mul_f32_e32 v34, 0xbfb8aa3b, v51
	v_exp_f32_e32 v34, v34
	s_nop 0
	v_add_f32_e32 v34, 1.0, v34
	v_rcp_f32_e32 v34, v34
	s_nop 0
	v_mul_f32_e32 v34, v51, v34
	v_mul_f32_e32 v34, v35, v34
	v_cvt_pk_bf16_f32 v34, v34, s0
	ds_write_b16 v98, v34 offset:9360
	v_mul_f32_e32 v34, 0xbfb8aa3b, v52
	v_exp_f32_e32 v34, v34
	s_nop 0
	v_add_f32_e32 v34, 1.0, v34
	v_rcp_f32_e32 v34, v34
	s_nop 0
	v_mul_f32_e32 v34, v52, v34
	v_mul_f32_e32 v34, v36, v34
	v_cvt_pk_bf16_f32 v34, v34, s0
	ds_write_b16 v98, v34 offset:9504
	v_mul_f32_e32 v34, 0xbfb8aa3b, v53
	v_exp_f32_e32 v34, v34
	s_nop 0
	v_add_f32_e32 v34, 1.0, v34
	v_rcp_f32_e32 v34, v34
	s_nop 0
	v_mul_f32_e32 v34, v53, v34
	v_mul_f32_e32 v34, v37, v34
	v_cvt_pk_bf16_f32 v34, v34, s0
	ds_write_b16 v98, v34 offset:9648
	v_mul_f32_e32 v34, 0xbfb8aa3b, v54
	v_exp_f32_e32 v34, v34
	s_nop 0
	v_add_f32_e32 v34, 1.0, v34
	v_rcp_f32_e32 v34, v34
	s_nop 0
	v_mul_f32_e32 v34, v54, v34
	v_mul_f32_e32 v34, v38, v34
	v_cvt_pk_bf16_f32 v34, v34, s0
	ds_write_b16 v98, v34 offset:10368
	v_mul_f32_e32 v34, 0xbfb8aa3b, v55
	v_exp_f32_e32 v34, v34
	s_nop 0
	v_add_f32_e32 v34, 1.0, v34
	v_rcp_f32_e32 v34, v34
	s_nop 0
	v_mul_f32_e32 v34, v55, v34
	v_mul_f32_e32 v34, v39, v34
	v_cvt_pk_bf16_f32 v34, v34, s0
	ds_write_b16 v98, v34 offset:10512
	v_mul_f32_e32 v34, 0xbfb8aa3b, v56
	v_exp_f32_e32 v34, v34
	s_nop 0
	v_add_f32_e32 v34, 1.0, v34
	v_rcp_f32_e32 v34, v34
	s_nop 0
	v_mul_f32_e32 v34, v56, v34
	v_mul_f32_e32 v34, v40, v34
	v_cvt_pk_bf16_f32 v34, v34, s0
	ds_write_b16 v98, v34 offset:10656
	v_mul_f32_e32 v34, 0xbfb8aa3b, v57
	v_exp_f32_e32 v34, v34
	s_nop 0
	v_add_f32_e32 v34, 1.0, v34
	v_rcp_f32_e32 v34, v34
	s_nop 0
	v_mul_f32_e32 v34, v57, v34
	v_mul_f32_e32 v34, v41, v34
	v_cvt_pk_bf16_f32 v34, v34, s0
	ds_write_b16 v98, v34 offset:10800
	v_mul_f32_e32 v34, 0xbfb8aa3b, v58
	v_exp_f32_e32 v34, v34
	s_nop 0
	v_add_f32_e32 v34, 1.0, v34
	v_rcp_f32_e32 v34, v34
	s_nop 0
	v_mul_f32_e32 v34, v58, v34
	v_mul_f32_e32 v34, v42, v34
	v_cvt_pk_bf16_f32 v34, v34, s0
	ds_write_b16 v98, v34 offset:11520
	v_mul_f32_e32 v34, 0xbfb8aa3b, v59
	v_exp_f32_e32 v34, v34
	s_nop 0
	v_add_f32_e32 v34, 1.0, v34
	v_rcp_f32_e32 v34, v34
	s_nop 0
	v_mul_f32_e32 v34, v59, v34
	v_mul_f32_e32 v34, v43, v34
	v_cvt_pk_bf16_f32 v34, v34, s0
	ds_write_b16 v98, v34 offset:11664
	v_mul_f32_e32 v34, 0xbfb8aa3b, v60
	v_exp_f32_e32 v34, v34
	s_nop 0
	v_add_f32_e32 v34, 1.0, v34
	v_rcp_f32_e32 v34, v34
	s_nop 0
	v_mul_f32_e32 v34, v60, v34
	v_mul_f32_e32 v34, v44, v34
	v_cvt_pk_bf16_f32 v34, v34, s0
	ds_write_b16 v98, v34 offset:11808
	v_mul_f32_e32 v34, 0xbfb8aa3b, v61
	v_exp_f32_e32 v34, v34
	s_nop 0
	v_add_f32_e32 v34, 1.0, v34
	v_rcp_f32_e32 v34, v34
	s_nop 0
	v_mul_f32_e32 v34, v61, v34
	v_mul_f32_e32 v34, v45, v34
	v_cvt_pk_bf16_f32 v34, v34, s0
	ds_write_b16 v98, v34 offset:11952
	v_mul_f32_e32 v34, 0xbfb8aa3b, v62
	v_exp_f32_e32 v34, v34
	s_nop 0
	v_add_f32_e32 v34, 1.0, v34
	v_rcp_f32_e32 v34, v34
	s_nop 0
	v_mul_f32_e32 v34, v62, v34
	v_mul_f32_e32 v34, v46, v34
	v_cvt_pk_bf16_f32 v34, v34, s0
	ds_write_b16 v98, v34 offset:12672
	v_mul_f32_e32 v34, 0xbfb8aa3b, v63
	v_exp_f32_e32 v34, v34
	s_nop 0
	v_add_f32_e32 v34, 1.0, v34
	v_rcp_f32_e32 v34, v34
	s_nop 0
	v_mul_f32_e32 v34, v63, v34
	v_mul_f32_e32 v34, v47, v34
	v_cvt_pk_bf16_f32 v34, v34, s0
	ds_write_b16 v98, v34 offset:12816
	v_mul_f32_e32 v34, 0xbfb8aa3b, v64
	v_exp_f32_e32 v34, v34
	s_nop 0
	v_add_f32_e32 v34, 1.0, v34
	v_rcp_f32_e32 v34, v34
	s_nop 0
	v_mul_f32_e32 v34, v64, v34
	v_mul_f32_e32 v34, v48, v34
	v_cvt_pk_bf16_f32 v34, v34, s0
	ds_write_b16 v98, v34 offset:12960
	v_mul_f32_e32 v34, 0xbfb8aa3b, v65
; DI unsigned pk2(float a, float b) { f32x2 v = {a, b}; bf2_t r = __builtin_convertvector(v, bf2_t); return __builtin_bit_cast(unsigned, r); }
; DI int crow(int i, int h) { return (i & 3) + 8 * (i >> 2) + 4 * h; }
; DI void gemm_ffi_tile_big(const Params& p, int l, int mt, int nt, char* smem) {
;     ...
; #pragma unroll
;   for (int mf = 0; mf < 4; ++mf)
; #pragma unroll
;     for (int i = 0; i < 16; ++i) {
;       const float g = acc[mf][0][i], u = acc[mf][1][i];
;       const float a = g * __builtin_amdgcn_rcpf(1.f + __expf(-g)) * u;
;       sbt[wm * 128 + mf * 32 + crow(i, half)][wn * 32 + c] = (bf16_t)(pk2(a, 0.f) & 0xffff);
;     }
;   __syncthreads();
;   const int r = tid >> 3, ch = tid & 7;
; #pragma unroll
;   for (int ps = 0; ps < 8; ++ps) {
;     const int row = ps * 32 + r;
;     *(u32x4*)(ACT + (size_t)(m0 + row) * DFF + nt * 64 + ch * 8) = *(const u32x4*)&sbt[row][ch * 8];
;   }
;   __syncthreads();
	v_exp_f32_e32 v34, v34
	s_nop 0
	v_add_f32_e32 v34, 1.0, v34
	v_rcp_f32_e32 v34, v34
	s_nop 0
	v_mul_f32_e32 v34, v65, v34
	v_mul_f32_e32 v34, v49, v34
	v_cvt_pk_bf16_f32 v34, v34, s0
	ds_write_b16 v98, v34 offset:13104
	v_mul_f32_e32 v34, 0xbfb8aa3b, v18
	v_exp_f32_e32 v34, v34
	s_nop 0
	v_add_f32_e32 v34, 1.0, v34
	v_rcp_f32_e32 v34, v34
	s_nop 0
	v_mul_f32_e32 v18, v18, v34
	v_mul_f32_e32 v2, v2, v18
	v_cvt_pk_bf16_f32 v2, v2, s0
	ds_write_b16 v98, v2 offset:13824
	v_mul_f32_e32 v2, 0xbfb8aa3b, v19
	v_exp_f32_e32 v2, v2
	s_nop 0
	v_add_f32_e32 v2, 1.0, v2
	v_rcp_f32_e32 v2, v2
	s_nop 0
	v_mul_f32_e32 v2, v19, v2
	v_mul_f32_e32 v2, v3, v2
	v_cvt_pk_bf16_f32 v2, v2, s0
	ds_write_b16 v98, v2 offset:13968
	v_mul_f32_e32 v2, 0xbfb8aa3b, v20
	v_exp_f32_e32 v2, v2
	s_nop 0
	v_add_f32_e32 v2, 1.0, v2
	v_rcp_f32_e32 v2, v2
	s_nop 0
	v_mul_f32_e32 v2, v20, v2
	v_mul_f32_e32 v2, v4, v2
	v_cvt_pk_bf16_f32 v2, v2, s0
	ds_write_b16 v98, v2 offset:14112
	v_mul_f32_e32 v2, 0xbfb8aa3b, v21
	v_exp_f32_e32 v2, v2
	s_nop 0
	v_add_f32_e32 v2, 1.0, v2
	v_rcp_f32_e32 v2, v2
	s_nop 0
	v_mul_f32_e32 v2, v21, v2
	v_mul_f32_e32 v2, v5, v2
	v_cvt_pk_bf16_f32 v2, v2, s0
	ds_write_b16 v98, v2 offset:14256
	v_mul_f32_e32 v2, 0xbfb8aa3b, v22
	v_exp_f32_e32 v2, v2
	s_nop 0
	v_add_f32_e32 v2, 1.0, v2
	v_rcp_f32_e32 v2, v2
	s_nop 0
	v_mul_f32_e32 v2, v22, v2
	v_mul_f32_e32 v2, v6, v2
	v_cvt_pk_bf16_f32 v2, v2, s0
	ds_write_b16 v98, v2 offset:14976
	v_mul_f32_e32 v2, 0xbfb8aa3b, v23
	v_exp_f32_e32 v2, v2
	s_nop 0
	v_add_f32_e32 v2, 1.0, v2
	v_rcp_f32_e32 v2, v2
	s_nop 0
	v_mul_f32_e32 v2, v23, v2
	v_mul_f32_e32 v2, v7, v2
	v_cvt_pk_bf16_f32 v2, v2, s0
	ds_write_b16 v98, v2 offset:15120
	v_mul_f32_e32 v2, 0xbfb8aa3b, v24
	v_exp_f32_e32 v2, v2
	s_nop 0
	v_add_f32_e32 v2, 1.0, v2
	v_rcp_f32_e32 v2, v2
	s_nop 0
	v_mul_f32_e32 v2, v24, v2
	v_mul_f32_e32 v2, v8, v2
	v_cvt_pk_bf16_f32 v2, v2, s0
	ds_write_b16 v98, v2 offset:15264
	v_mul_f32_e32 v2, 0xbfb8aa3b, v25
	v_exp_f32_e32 v2, v2
	s_nop 0
	v_add_f32_e32 v2, 1.0, v2
	v_rcp_f32_e32 v2, v2
	s_nop 0
	v_mul_f32_e32 v2, v25, v2
	v_mul_f32_e32 v2, v9, v2
	v_cvt_pk_bf16_f32 v2, v2, s0
	ds_write_b16 v98, v2 offset:15408
	v_mul_f32_e32 v2, 0xbfb8aa3b, v26
	v_exp_f32_e32 v2, v2
	s_nop 0
	v_add_f32_e32 v2, 1.0, v2
	v_rcp_f32_e32 v2, v2
	s_nop 0
	v_mul_f32_e32 v2, v26, v2
	v_mul_f32_e32 v2, v10, v2
	v_cvt_pk_bf16_f32 v2, v2, s0
	ds_write_b16 v98, v2 offset:16128
	v_mul_f32_e32 v2, 0xbfb8aa3b, v27
	v_exp_f32_e32 v2, v2
	v_ashrrev_i32_e32 v10, 3, v0
	v_lshlrev_b32_e32 v0, 4, v0
	v_and_b32_e32 v0, 0x70, v0
	v_add_f32_e32 v2, 1.0, v2
	v_rcp_f32_e32 v2, v2
	v_lshl_add_u64 v[6:7], s[26:27], 0, v[0:1]
	v_mad_u64_u32 v[8:9], s[26:27], v10, s9, v[0:1]
	v_mul_f32_e32 v2, v27, v2
	v_mul_f32_e32 v2, v11, v2
	v_cvt_pk_bf16_f32 v2, v2, s0
	ds_write_b16 v98, v2 offset:16272
	v_mul_f32_e32 v2, 0xbfb8aa3b, v28
	v_exp_f32_e32 v2, v2
	v_add_u32_e32 v0, s42, v10
	s_movk_i32 s9, 0x1600
	v_mad_i64_i32 v[10:11], s[26:27], v0, s9, v[6:7]
	v_add_f32_e32 v2, 1.0, v2
	v_rcp_f32_e32 v2, v2
	v_add_u32_e32 v9, 32, v0
	v_mul_f32_e32 v2, v28, v2
	v_mul_f32_e32 v2, v12, v2
	v_cvt_pk_bf16_f32 v2, v2, s0
	ds_write_b16 v98, v2 offset:16416
	v_mul_f32_e32 v2, 0xbfb8aa3b, v29
	v_exp_f32_e32 v2, v2
	s_nop 0
	v_add_f32_e32 v2, 1.0, v2
	v_rcp_f32_e32 v2, v2
	s_nop 0
	v_mul_f32_e32 v2, v29, v2
	v_mul_f32_e32 v2, v13, v2
	v_cvt_pk_bf16_f32 v2, v2, s0
	ds_write_b16 v98, v2 offset:16560
	v_mul_f32_e32 v2, 0xbfb8aa3b, v30
	v_exp_f32_e32 v2, v2
	s_nop 0
	v_add_f32_e32 v2, 1.0, v2
	v_rcp_f32_e32 v2, v2
	s_nop 0
	v_mul_f32_e32 v2, v30, v2
	v_mul_f32_e32 v2, v14, v2
	v_cvt_pk_bf16_f32 v2, v2, s0
	ds_write_b16 v98, v2 offset:17280
	v_mul_f32_e32 v2, 0xbfb8aa3b, v31
	v_exp_f32_e32 v2, v2
	s_nop 0
	v_add_f32_e32 v2, 1.0, v2
	v_rcp_f32_e32 v2, v2
	s_nop 0
	v_mul_f32_e32 v2, v31, v2
	v_mul_f32_e32 v2, v15, v2
	v_cvt_pk_bf16_f32 v2, v2, s0
	ds_write_b16 v98, v2 offset:17424
	v_mul_f32_e32 v2, 0xbfb8aa3b, v32
	v_exp_f32_e32 v2, v2
	s_nop 0
	v_add_f32_e32 v2, 1.0, v2
	v_rcp_f32_e32 v2, v2
	s_nop 0
	v_mul_f32_e32 v2, v32, v2
	v_mul_f32_e32 v2, v16, v2
	v_cvt_pk_bf16_f32 v2, v2, s0
	ds_write_b16 v98, v2 offset:17568
	v_mul_f32_e32 v2, 0xbfb8aa3b, v33
	v_exp_f32_e32 v2, v2
	s_nop 0
	v_add_f32_e32 v2, 1.0, v2
	v_rcp_f32_e32 v2, v2
	s_nop 0
	v_mul_f32_e32 v2, v33, v2
	v_mul_f32_e32 v2, v17, v2
	v_cvt_pk_bf16_f32 v2, v2, s0
	ds_write_b16 v98, v2 offset:17712
	s_waitcnt lgkmcnt(0)
	s_barrier
	ds_read_b128 v[2:5], v8
	s_waitcnt lgkmcnt(0)
	global_store_dwordx4 v[10:11], v[2:5], off
	ds_read_b128 v[2:5], v8 offset:4608
	v_mad_i64_i32 v[10:11], s[26:27], v9, s9, v[6:7]
	v_add_u32_e32 v9, 64, v0
	s_waitcnt lgkmcnt(0)
	global_store_dwordx4 v[10:11], v[2:5], off
	ds_read_b128 v[2:5], v8 offset:9216
	v_mad_i64_i32 v[10:11], s[26:27], v9, s9, v[6:7]
	v_add_u32_e32 v9, 0x60, v0
	s_waitcnt lgkmcnt(0)
	global_store_dwordx4 v[10:11], v[2:5], off
	ds_read_b128 v[2:5], v8 offset:13824
	v_mad_i64_i32 v[10:11], s[26:27], v9, s9, v[6:7]
	v_add_u32_e32 v9, 0x80, v0
	s_waitcnt lgkmcnt(0)
	global_store_dwordx4 v[10:11], v[2:5], off
	ds_read_b128 v[2:5], v8 offset:18432
	v_mad_i64_i32 v[10:11], s[26:27], v9, s9, v[6:7]
	v_add_u32_e32 v9, 0xa0, v0
	s_waitcnt lgkmcnt(0)
	global_store_dwordx4 v[10:11], v[2:5], off
	ds_read_b128 v[2:5], v8 offset:23040
	v_mad_i64_i32 v[10:11], s[26:27], v9, s9, v[6:7]
	v_add_u32_e32 v9, 0xc0, v0
	v_add_u32_e32 v0, 0xe0, v0
	s_waitcnt lgkmcnt(0)
	global_store_dwordx4 v[10:11], v[2:5], off
	ds_read_b128 v[2:5], v8 offset:27648
	v_mad_i64_i32 v[10:11], s[26:27], v9, s9, v[6:7]
	v_mad_i64_i32 v[6:7], s[26:27], v0, s9, v[6:7]
	s_waitcnt lgkmcnt(0)
	global_store_dwordx4 v[10:11], v[2:5], off
	ds_read_b128 v[2:5], v8 offset:32256
	s_waitcnt lgkmcnt(0)
	global_store_dwordx4 v[6:7], v[2:5], off
	s_barrier
	s_branch .LBB0_1237

; #define MFMA32(a, b, c) __builtin_amdgcn_mfma_f32_32x32x16_bf16((a), (b), (c), 0, 0, 0)
; DI void gemm_mainloop_big(const bf16_t* __restrict__ A, int lda, const bf16_t* __restrict__ Bt, int ldb, int K, int m0, int n0,
;                           f32x16 (&acc)[4][2], char* smem) {
;     ...
;   for (int kt = 0; kt < nk; ++kt) {
;     if (kt + 1 < nk) {
; #pragma unroll
;       for (int i = 0; i < 8; ++i) ra[i] = *(const u32x4*)(ap + (size_t)(32 * i) * lda + (kt + 1) * 64);
; #pragma unroll
;       for (int i = 0; i < 4; ++i) rb[i] = *(const u32x4*)(bp + (size_t)(32 * i) * ldb + (kt + 1) * 64);
;     }
; #pragma unroll
;     for (int ks = 0; ks < 4; ++ks) {
;       bf16x8 af[4], bfr[2];
; #pragma unroll
;       for (int f = 0; f < 4; ++f) af[f] = *(const bf16x8*)&sa[wm * 128 + f * 32 + r][ks * 16 + half * 8];
; #pragma unroll
;       for (int f = 0; f < 2; ++f) bfr[f] = *(const bf16x8*)&sb[wn * 64 + f * 32 + r][ks * 16 + half * 8];
; #pragma unroll
;       for (int mf = 0; mf < 4; ++mf)
; #pragma unroll
;         for (int nf = 0; nf < 2; ++nf) acc[mf][nf] = MFMA32(af[mf], bfr[nf], acc[mf][nf]);
;     }
.LBB0_1299:
	ds_read_b128 v[130:133], v0
	ds_read_b128 v[134:137], v139 offset:36864
	ds_read_b128 v[144:147], v0 offset:32
	ds_read_b128 v[148:151], v139 offset:36896
	ds_read_b128 v[152:155], v139 offset:41472
	ds_read_b128 v[156:159], v139 offset:41504
	s_mov_b32 s42, 0x8378000
	s_waitcnt lgkmcnt(4)
	v_mfma_f32_32x32x16_bf16 v[114:129], v[130:133], v[134:137], v[114:129]
	s_waitcnt lgkmcnt(1)
	v_mfma_f32_32x32x16_bf16 v[98:113], v[130:133], v[152:155], v[98:113]
	ds_read_b128 v[130:133], v0 offset:4608
	ds_read_b128 v[160:163], v0 offset:4640
	s_waitcnt lgkmcnt(1)
	v_mfma_f32_32x32x16_bf16 v[82:97], v[130:133], v[134:137], v[82:97]
	v_mfma_f32_32x32x16_bf16 v[66:81], v[130:133], v[152:155], v[66:81]
	ds_read_b128 v[130:133], v0 offset:9216
	ds_read_b128 v[164:167], v0 offset:9248
	s_waitcnt lgkmcnt(1)
	v_mfma_f32_32x32x16_bf16 v[50:65], v[130:133], v[134:137], v[50:65]
	v_mfma_f32_32x32x16_bf16 v[34:49], v[130:133], v[152:155], v[34:49]
	ds_read_b128 v[130:133], v0 offset:13824
	ds_read_b128 v[168:171], v0 offset:13856
	s_waitcnt lgkmcnt(1)
	v_mfma_f32_32x32x16_bf16 v[18:33], v[130:133], v[134:137], v[18:33]
	v_mfma_f32_32x32x16_bf16 v[2:17], v[130:133], v[152:155], v[2:17]
	v_mfma_f32_32x32x16_bf16 v[114:129], v[144:147], v[148:151], v[114:129]
	v_mfma_f32_32x32x16_bf16 v[98:113], v[144:147], v[156:159], v[98:113]
	v_mfma_f32_32x32x16_bf16 v[82:97], v[160:163], v[148:151], v[82:97]
	v_mfma_f32_32x32x16_bf16 v[66:81], v[160:163], v[156:159], v[66:81]
	v_mfma_f32_32x32x16_bf16 v[50:65], v[164:167], v[148:151], v[50:65]
	v_mfma_f32_32x32x16_bf16 v[34:49], v[164:167], v[156:159], v[34:49]
	s_waitcnt lgkmcnt(0)
	v_mfma_f32_32x32x16_bf16 v[18:33], v[168:171], v[148:151], v[18:33]
	ds_read_b128 v[134:137], v0 offset:64
	ds_read_b128 v[144:147], v139 offset:36928
	ds_read_b128 v[148:151], v0 offset:96
	ds_read_b128 v[152:155], v139 offset:36960
	v_mfma_f32_32x32x16_bf16 v[2:17], v[168:171], v[156:159], v[2:17]
	ds_read_b128 v[156:159], v139 offset:41536
	ds_read_b128 v[130:133], v139 offset:41568
	s_waitcnt lgkmcnt(4)
	v_mfma_f32_32x32x16_bf16 v[114:129], v[134:137], v[144:147], v[114:129]
	s_waitcnt lgkmcnt(1)
	v_mfma_f32_32x32x16_bf16 v[98:113], v[134:137], v[156:159], v[98:113]
	ds_read_b128 v[134:137], v0 offset:4672
	ds_read_b128 v[160:163], v0 offset:4704
	s_waitcnt lgkmcnt(1)
	v_mfma_f32_32x32x16_bf16 v[82:97], v[134:137], v[144:147], v[82:97]
	v_mfma_f32_32x32x16_bf16 v[66:81], v[134:137], v[156:159], v[66:81]
	ds_read_b128 v[134:137], v0 offset:9280
	ds_read_b128 v[164:167], v0 offset:9312
	s_waitcnt lgkmcnt(1)
	v_mfma_f32_32x32x16_bf16 v[50:65], v[134:137], v[144:147], v[50:65]
	v_mfma_f32_32x32x16_bf16 v[34:49], v[134:137], v[156:159], v[34:49]
	ds_read_b128 v[168:171], v0 offset:13888
	ds_read_b128 v[134:137], v0 offset:13920
	s_waitcnt lgkmcnt(1)
	v_mfma_f32_32x32x16_bf16 v[18:33], v[168:171], v[144:147], v[18:33]
	v_lshl_add_u64 v[144:145], v[140:141], 0, s[36:37]
	v_add_co_u32_e32 v172, vcc, s42, v144
	s_mov_b32 s42, 0x83a4000
	s_nop 0
	v_addc_co_u32_e32 v173, vcc, 0, v145, vcc
	v_lshl_add_u64 v[146:147], v[142:143], 0, s[36:37]
	v_mfma_f32_32x32x16_bf16 v[2:17], v[168:171], v[156:159], v[2:17]
	v_add_co_u32_e32 v156, vcc, s42, v144
	s_mov_b32 s42, 0x83d0000
	s_nop 0
	v_addc_co_u32_e32 v157, vcc, 0, v145, vcc
	v_add_co_u32_e32 v158, vcc, s42, v144
	s_mov_b32 s42, 0x83fc000
	s_nop 0
	v_addc_co_u32_e32 v159, vcc, 0, v145, vcc
	v_add_co_u32_e32 v168, vcc, s42, v144
	s_mov_b32 s42, 0x8428000
	s_nop 0
	v_addc_co_u32_e32 v169, vcc, 0, v145, vcc
	v_add_co_u32_e32 v170, vcc, s42, v144
	s_mov_b32 s42, 0x8454000
	s_nop 0
	v_addc_co_u32_e32 v171, vcc, 0, v145, vcc
	v_add_co_u32_e32 v174, vcc, s42, v144
	s_mov_b32 s42, 0x8480000
	s_nop 0
	v_addc_co_u32_e32 v175, vcc, 0, v145, vcc
	v_add_co_u32_e32 v176, vcc, s42, v144
	s_mov_b32 s42, 0x84ac000
	s_nop 0
	v_addc_co_u32_e32 v177, vcc, 0, v145, vcc
	v_add_co_u32_e32 v178, vcc, s42, v144
	s_mov_b32 s42, 0x18c0000
	s_nop 0
	v_addc_co_u32_e32 v179, vcc, 0, v145, vcc
	v_add_co_u32_e32 v180, vcc, s42, v146
	s_mov_b32 s42, 0x18ec000
	s_nop 0
	v_addc_co_u32_e32 v181, vcc, 0, v147, vcc
	v_add_co_u32_e32 v190, vcc, s42, v146
	s_mov_b32 s42, 0x1918000
	s_nop 0
	v_addc_co_u32_e32 v191, vcc, 0, v147, vcc
	v_add_co_u32_e32 v194, vcc, s42, v146
	s_mov_b32 s42, 0x1944000
	s_nop 0
	v_addc_co_u32_e32 v195, vcc, 0, v147, vcc
	v_add_co_u32_e32 v198, vcc, s42, v146
	v_mfma_f32_32x32x16_bf16 v[114:129], v[148:151], v[152:155], v[114:129]
	s_nop 0
	v_addc_co_u32_e32 v199, vcc, 0, v147, vcc
	s_add_u32 s36, s36, 0x80
	s_addc_u32 s37, s37, 0
	s_cmpk_lg_i32 s36, 0x1580
	v_mfma_f32_32x32x16_bf16 v[98:113], v[148:151], v[130:133], v[98:113]
	v_mfma_f32_32x32x16_bf16 v[82:97], v[160:163], v[152:155], v[82:97]
	v_mfma_f32_32x32x16_bf16 v[66:81], v[160:163], v[130:133], v[66:81]
	global_load_dwordx4 v[144:147], v[172:173], off offset:128
	global_load_dwordx4 v[148:151], v[156:157], off offset:128
	s_nop 0
	global_load_dwordx4 v[156:159], v[158:159], off offset:128
	s_nop 0
	global_load_dwordx4 v[160:163], v[168:169], off offset:128
	v_mfma_f32_32x32x16_bf16 v[50:65], v[164:167], v[152:155], v[50:65]
	v_mfma_f32_32x32x16_bf16 v[34:49], v[164:167], v[130:133], v[34:49]
	global_load_dwordx4 v[164:167], v[170:171], off offset:128
	s_nop 0
	global_load_dwordx4 v[168:171], v[174:175], off offset:128
	s_nop 0
	global_load_dwordx4 v[172:175], v[176:177], off offset:128
	s_nop 0
	global_load_dwordx4 v[176:179], v[178:179], off offset:128
	s_nop 0
	global_load_dwordx4 v[186:189], v[180:181], off offset:128
	s_nop 0
	global_load_dwordx4 v[190:193], v[190:191], off offset:128
	s_nop 0
	global_load_dwordx4 v[194:197], v[194:195], off offset:128
	s_waitcnt lgkmcnt(0)
	v_mfma_f32_32x32x16_bf16 v[18:33], v[134:137], v[152:155], v[18:33]
	global_load_dwordx4 v[152:155], v[198:199], off offset:128
	s_barrier
; #define MFMA32(a, b, c) __builtin_amdgcn_mfma_f32_32x32x16_bf16((a), (b), (c), 0, 0, 0)
; DI void gemm_mainloop_big(const bf16_t* __restrict__ A, int lda, const bf16_t* __restrict__ Bt, int ldb, int K, int m0, int n0,
;                           f32x16 (&acc)[4][2], char* smem) {
;     ...
; #pragma unroll
;     for (int ks = 0; ks < 4; ++ks) {
;       bf16x8 af[4], bfr[2];
; #pragma unroll
;       for (int f = 0; f < 4; ++f) af[f] = *(const bf16x8*)&sa[wm * 128 + f * 32 + r][ks * 16 + half * 8];
; #pragma unroll
;       for (int f = 0; f < 2; ++f) bfr[f] = *(const bf16x8*)&sb[wn * 64 + f * 32 + r][ks * 16 + half * 8];
; #pragma unroll
;       for (int mf = 0; mf < 4; ++mf)
; #pragma unroll
;         for (int nf = 0; nf < 2; ++nf) acc[mf][nf] = MFMA32(af[mf], bfr[nf], acc[mf][nf]);
;     }
;     __syncthreads();
;     if (kt + 1 < nk) {
; #pragma unroll
;       for (int i = 0; i < 8; ++i) *(u32x4*)&sa[(tid >> 3) + 32 * i][(tid & 7) * 8] = ra[i];
; #pragma unroll
;       for (int i = 0; i < 4; ++i) *(u32x4*)&sb[(tid >> 3) + 32 * i][(tid & 7) * 8] = rb[i];
;     }
;     __syncthreads();
	s_waitcnt vmcnt(11)
	ds_write_b128 v138, v[144:147]
	s_waitcnt vmcnt(10)
	ds_write_b128 v138, v[148:151] offset:4608
	s_waitcnt vmcnt(9)
	ds_write_b128 v138, v[156:159] offset:9216
	s_waitcnt vmcnt(8)
	ds_write_b128 v138, v[160:163] offset:13824
	s_waitcnt vmcnt(7)
	ds_write_b128 v138, v[164:167] offset:18432
	s_waitcnt vmcnt(6)
	ds_write_b128 v138, v[168:171] offset:23040
	s_waitcnt vmcnt(5)
	ds_write_b128 v138, v[172:175] offset:27648
	s_waitcnt vmcnt(4)
	ds_write_b128 v138, v[176:179] offset:32256
	s_waitcnt vmcnt(3)
	ds_write_b128 v138, v[186:189] offset:36864
	s_waitcnt vmcnt(2)
	ds_write_b128 v138, v[190:193] offset:41472
	s_waitcnt vmcnt(1)
	ds_write_b128 v138, v[194:197] offset:46080
	s_waitcnt vmcnt(0)
	ds_write_b128 v138, v[152:155] offset:50688
	v_mfma_f32_32x32x16_bf16 v[2:17], v[134:137], v[130:133], v[2:17]
	s_waitcnt lgkmcnt(0)
	s_barrier
	s_cbranch_scc1 .LBB0_1299
	ds_read_b128 v[130:133], v0
	ds_read_b128 v[134:137], v139 offset:36864
	ds_read_b128 v[140:143], v139 offset:41472
	s_waitcnt lgkmcnt(1)
	v_mfma_f32_32x32x16_bf16 v[114:129], v[130:133], v[134:137], v[114:129]
	s_waitcnt lgkmcnt(0)
	v_mfma_f32_32x32x16_bf16 v[98:113], v[130:133], v[140:143], v[98:113]
	ds_read_b128 v[130:133], v0 offset:4608
	s_waitcnt lgkmcnt(0)
	v_mfma_f32_32x32x16_bf16 v[82:97], v[130:133], v[134:137], v[82:97]
	v_mfma_f32_32x32x16_bf16 v[66:81], v[130:133], v[140:143], v[66:81]
	ds_read_b128 v[130:133], v0 offset:9216
	s_waitcnt lgkmcnt(0)
	v_mfma_f32_32x32x16_bf16 v[50:65], v[130:133], v[134:137], v[50:65]
	v_mfma_f32_32x32x16_bf16 v[34:49], v[130:133], v[140:143], v[34:49]
	ds_read_b128 v[130:133], v0 offset:13824
	s_waitcnt lgkmcnt(0)
	v_mfma_f32_32x32x16_bf16 v[18:33], v[130:133], v[134:137], v[18:33]
	v_mfma_f32_32x32x16_bf16 v[2:17], v[130:133], v[140:143], v[2:17]
	ds_read_b128 v[130:133], v0 offset:32
	ds_read_b128 v[134:137], v139 offset:36896
	ds_read_b128 v[140:143], v139 offset:41504
	s_waitcnt lgkmcnt(1)
	v_mfma_f32_32x32x16_bf16 v[114:129], v[130:133], v[134:137], v[114:129]
	s_waitcnt lgkmcnt(0)
	v_mfma_f32_32x32x16_bf16 v[98:113], v[130:133], v[140:143], v[98:113]
	ds_read_b128 v[130:133], v0 offset:4640
	s_waitcnt lgkmcnt(0)
	v_mfma_f32_32x32x16_bf16 v[82:97], v[130:133], v[134:137], v[82:97]
	v_mfma_f32_32x32x16_bf16 v[66:81], v[130:133], v[140:143], v[66:81]
	ds_read_b128 v[130:133], v0 offset:9248
	s_waitcnt lgkmcnt(0)
	v_mfma_f32_32x32x16_bf16 v[50:65], v[130:133], v[134:137], v[50:65]
	v_mfma_f32_32x32x16_bf16 v[34:49], v[130:133], v[140:143], v[34:49]
	ds_read_b128 v[130:133], v0 offset:13856
	s_waitcnt lgkmcnt(0)
	v_mfma_f32_32x32x16_bf16 v[18:33], v[130:133], v[134:137], v[18:33]
	v_mfma_f32_32x32x16_bf16 v[2:17], v[130:133], v[140:143], v[2:17]
	ds_read_b128 v[130:133], v0 offset:64
	ds_read_b128 v[134:137], v139 offset:36928
	ds_read_b128 v[140:143], v139 offset:41536
	s_waitcnt lgkmcnt(1)
	v_mfma_f32_32x32x16_bf16 v[114:129], v[130:133], v[134:137], v[114:129]
	s_waitcnt lgkmcnt(0)
	v_mfma_f32_32x32x16_bf16 v[98:113], v[130:133], v[140:143], v[98:113]
	ds_read_b128 v[130:133], v0 offset:4672
	s_waitcnt lgkmcnt(0)
	v_mfma_f32_32x32x16_bf16 v[82:97], v[130:133], v[134:137], v[82:97]
	v_mfma_f32_32x32x16_bf16 v[66:81], v[130:133], v[140:143], v[66:81]
	ds_read_b128 v[130:133], v0 offset:9280
	s_waitcnt lgkmcnt(0)
	v_mfma_f32_32x32x16_bf16 v[50:65], v[130:133], v[134:137], v[50:65]
	v_mfma_f32_32x32x16_bf16 v[34:49], v[130:133], v[140:143], v[34:49]
	ds_read_b128 v[130:133], v0 offset:13888
	s_waitcnt lgkmcnt(0)
	v_mfma_f32_32x32x16_bf16 v[18:33], v[130:133], v[134:137], v[18:33]
	v_mfma_f32_32x32x16_bf16 v[2:17], v[130:133], v[140:143], v[2:17]
	ds_read_b128 v[130:133], v0 offset:96
	ds_read_b128 v[134:137], v139 offset:36960
	ds_read_b128 v[138:141], v139 offset:41568
	s_waitcnt lgkmcnt(1)
	v_mfma_f32_32x32x16_bf16 v[114:129], v[130:133], v[134:137], v[114:129]
	s_waitcnt lgkmcnt(0)
	v_mfma_f32_32x32x16_bf16 v[98:113], v[130:133], v[138:141], v[98:113]
	ds_read_b128 v[130:133], v0 offset:4704
	s_waitcnt lgkmcnt(0)
	v_mfma_f32_32x32x16_bf16 v[82:97], v[130:133], v[134:137], v[82:97]
	v_mfma_f32_32x32x16_bf16 v[66:81], v[130:133], v[138:141], v[66:81]
	ds_read_b128 v[130:133], v0 offset:9312
	s_waitcnt lgkmcnt(0)
	v_mfma_f32_32x32x16_bf16 v[50:65], v[130:133], v[134:137], v[50:65]
	v_mfma_f32_32x32x16_bf16 v[34:49], v[130:133], v[138:141], v[34:49]
	ds_read_b128 v[130:133], v0 offset:13920
	s_waitcnt lgkmcnt(0)
	s_barrier
	s_barrier
	v_mfma_f32_32x32x16_bf16 v[18:33], v[130:133], v[134:137], v[18:33]
	v_mov_b32_e32 v134, v216
	s_nop 0
	v_cmp_gt_u32_e32 vcc, s31, v134
	v_mfma_f32_32x32x16_bf16 v[2:17], v[130:133], v[138:141], v[2:17]
	s_and_saveexec_b64 s[36:37], vcc
	s_cbranch_execz .LBB0_1302
; DI int crow(int i, int h) { return (i & 3) + 8 * (i >> 2) + 4 * h; }
; DI void stage_half(float* st, const f32x16 (&acc)[4][2], int h, int tid) {
;   const int lane = tid & 63, w = tid >> 6, wm = w >> 1, wn = w & 1, c = lane & 31, half = lane >> 5;
;   if (wm == h) {
; #pragma unroll
;     for (int mf = 0; mf < 4; ++mf)
; #pragma unroll
;       for (int nf = 0; nf < 2; ++nf)
; #pragma unroll
;         for (int i = 0; i < 16; ++i) st[(mf * 32 + crow(i, half)) * 132 + wn * 64 + nf * 32 + c] = acc[mf][nf][i];
;   }
	v_lshrrev_b32_e32 v0, 3, v134
	v_and_b32_e32 v0, 4, v0
	v_and_b32_e32 v130, 0x5f, v134
	v_mul_u32_u24_e32 v0, 0x210, v0
	v_lshl_add_u32 v0, v130, 2, v0
	v_add_u32_e32 v130, 0x400, v0
	ds_write2_b32 v0, v114, v98 offset1:32
	ds_write2_b32 v0, v115, v99 offset0:132 offset1:164
	ds_write2_b32 v130, v116, v100 offset0:8 offset1:40
	ds_write2_b32 v130, v117, v101 offset0:140 offset1:172
	v_add_u32_e32 v130, 0x1000, v0
	ds_write2_b32 v130, v118, v102 offset0:32 offset1:64
	ds_write2_b32 v130, v119, v103 offset0:164 offset1:196
	v_add_u32_e32 v130, 0x1400, v0
	ds_write2_b32 v130, v120, v104 offset0:40 offset1:72
	ds_write2_b32 v130, v121, v105 offset0:172 offset1:204
	v_add_u32_e32 v130, 0x2000, v0
	ds_write2_b32 v130, v122, v106 offset0:64 offset1:96
	ds_write2_b32 v130, v123, v107 offset0:196 offset1:228
	v_add_u32_e32 v130, 0x2400, v0
	ds_write2_b32 v130, v124, v108 offset0:72 offset1:104
	ds_write2_b32 v130, v125, v109 offset0:204 offset1:236
	v_add_u32_e32 v130, 0x3000, v0
	ds_write2_b32 v130, v126, v110 offset0:96 offset1:128
	v_add_u32_e32 v130, 0x3200, v0
	ds_write2_b32 v130, v127, v111 offset0:100 offset1:132
	v_add_u32_e32 v130, 0x3400, v0
	ds_write2_b32 v130, v128, v112 offset0:104 offset1:136
	v_add_u32_e32 v130, 0x3600, v0
	ds_write2_b32 v130, v129, v113 offset0:108 offset1:140
	v_add_u32_e32 v130, 0x4000, v0
	ds_write2_b32 v130, v82, v66 offset0:128 offset1:160
	v_add_u32_e32 v130, 0x4400, v0
	ds_write2_b32 v130, v83, v67 offset0:4 offset1:36
	ds_write2_b32 v130, v84, v68 offset0:136 offset1:168
	v_add_u32_e32 v130, 0x4800, v0
	ds_write2_b32 v130, v85, v69 offset0:12 offset1:44
	v_add_u32_e32 v130, 0x5000, v0
	ds_write2_b32 v130, v86, v70 offset0:160 offset1:192
	v_add_u32_e32 v130, 0x5400, v0
	ds_write2_b32 v130, v87, v71 offset0:36 offset1:68
	ds_write2_b32 v130, v88, v72 offset0:168 offset1:200
	v_add_u32_e32 v130, 0x5800, v0
	ds_write2_b32 v130, v89, v73 offset0:44 offset1:76
	v_add_u32_e32 v130, 0x6000, v0
	ds_write2_b32 v130, v90, v74 offset0:192 offset1:224
	v_add_u32_e32 v130, 0x6400, v0
	ds_write2_b32 v130, v91, v75 offset0:68 offset1:100
	ds_write2_b32 v130, v92, v76 offset0:200 offset1:232
	v_add_u32_e32 v130, 0x6800, v0
	ds_write2_b32 v130, v93, v77 offset0:76 offset1:108
	v_add_u32_e32 v130, 0x7200, v0
	ds_write2_b32 v130, v94, v78 offset0:96 offset1:128
	v_add_u32_e32 v130, 0x7400, v0
	ds_write2_b32 v130, v95, v79 offset0:100 offset1:132
	v_add_u32_e32 v130, 0x7600, v0
	ds_write2_b32 v130, v96, v80 offset0:104 offset1:136
	v_add_u32_e32 v130, 0x7800, v0
	ds_write2_b32 v130, v97, v81 offset0:108 offset1:140
	v_add_u32_e32 v130, 0x8400, v0
	ds_write2_b32 v130, v50, v34 offset1:32
	ds_write2_b32 v130, v51, v35 offset0:132 offset1:164
	v_add_u32_e32 v130, 0x8800, v0
	ds_write2_b32 v130, v52, v36 offset0:8 offset1:40
	ds_write2_b32 v130, v53, v37 offset0:140 offset1:172
	v_add_u32_e32 v130, 0x9400, v0
	ds_write2_b32 v130, v54, v38 offset0:32 offset1:64
	ds_write2_b32 v130, v55, v39 offset0:164 offset1:196
	v_add_u32_e32 v130, 0x9800, v0
	ds_write2_b32 v130, v56, v40 offset0:40 offset1:72
	ds_write2_b32 v130, v57, v41 offset0:172 offset1:204
	v_add_u32_e32 v130, 0xa400, v0
	ds_write2_b32 v130, v58, v42 offset0:64 offset1:96
	ds_write2_b32 v130, v59, v43 offset0:196 offset1:228
	v_add_u32_e32 v130, 0xa800, v0
	ds_write2_b32 v130, v60, v44 offset0:72 offset1:104
	ds_write2_b32 v130, v61, v45 offset0:204 offset1:236
	v_add_u32_e32 v130, 0xb400, v0
	ds_write2_b32 v130, v62, v46 offset0:96 offset1:128
	v_add_u32_e32 v130, 0xb600, v0
	ds_write2_b32 v130, v63, v47 offset0:100 offset1:132
	v_add_u32_e32 v130, 0xb800, v0
	ds_write2_b32 v130, v64, v48 offset0:104 offset1:136
	v_add_u32_e32 v130, 0xba00, v0
	ds_write2_b32 v130, v65, v49 offset0:108 offset1:140
	v_add_u32_e32 v130, 0xc400, v0
	ds_write2_b32 v130, v18, v2 offset0:128 offset1:160
	v_add_u32_e32 v130, 0xc800, v0
	ds_write2_b32 v130, v19, v3 offset0:4 offset1:36
	ds_write2_b32 v130, v20, v4 offset0:136 offset1:168
	v_add_u32_e32 v130, 0xcc00, v0
	ds_write2_b32 v130, v21, v5 offset0:12 offset1:44
	v_add_u32_e32 v130, 0xd400, v0
	ds_write2_b32 v130, v22, v6 offset0:160 offset1:192
	v_add_u32_e32 v130, 0xd800, v0
	ds_write2_b32 v130, v23, v7 offset0:36 offset1:68
	ds_write2_b32 v130, v24, v8 offset0:168 offset1:200
	v_add_u32_e32 v130, 0xdc00, v0
	ds_write2_b32 v130, v25, v9 offset0:44 offset1:76
	v_add_u32_e32 v130, 0xe400, v0
	ds_write2_b32 v130, v26, v10 offset0:192 offset1:224
	v_add_u32_e32 v130, 0xe800, v0
	ds_write2_b32 v130, v27, v11 offset0:68 offset1:100
	ds_write2_b32 v130, v28, v12 offset0:200 offset1:232
	v_add_u32_e32 v130, 0xec00, v0
	ds_write2_b32 v130, v29, v13 offset0:76 offset1:108
	v_add_u32_e32 v130, 0xf600, v0
	ds_write2_b32 v130, v30, v14 offset0:96 offset1:128
	v_add_u32_e32 v130, 0xf800, v0
	ds_write2_b32 v130, v31, v15 offset0:100 offset1:132
	v_add_u32_e32 v130, 0xfa00, v0
	v_add_u32_e32 v0, 0xfc00, v0
	ds_write2_b32 v130, v32, v16 offset0:104 offset1:136
	ds_write2_b32 v0, v33, v17 offset0:108 offset1:140

; DI int otid() { int t = threadIdx.x; asm volatile("" : "+v"(t)); return t; }
; DI void gemm_res_tile_big(const bf16_t* A, int lda, const bf16_t* Bt, int K, const float* __restrict__ xin, float* __restrict__ xout,
;                           const float* __restrict__ gate, int mt, int nt, char* smem) {
;     ...
;     const int tid = otid();
;     stage_half(st, acc, h, tid);
;     __syncthreads();
;     const int r = tid >> 5, ch = tid & 31;
;     const float4 g = *(const float4*)(gate + (size_t)b * 6144 + n0 + ch * 4);
; #pragma unroll 4
;     for (int ps = 0; ps < 16; ++ps) {
;       const int row = ps * 8 + r;
;       const float4 a = *(const float4*)(st + row * 132 + ch * 4);
;       const size_t off = (size_t)(m0 + h * 128 + row) * 1024 + n0 + ch * 4;
;       const float4 xi = *(const float4*)(xin + off);
;       float4 o; o.x = xi.x + g.x * a.x; o.y = xi.y + g.y * a.y; o.z = xi.z + g.z * a.z; o.w = xi.w + g.w * a.w;
;       *(float4*)(xout + off) = o;
;     }
.LBB0_1303:
	v_lshrrev_b32_e32 v215, 5, v216
	v_mul_u32_u24_e32 v182, 0x210, v215
	v_and_b32_e32 v215, 31, v216
	v_lshl_add_u32 v182, v215, 4, v182
	v_lshlrev_b32_e32 v184, 10, v136
	v_add_u32_e32 v184, v184, v144
	v_lshlrev_b32_e32 v184, 2, v184
	v_mov_b32_e32 v214, v184
	global_load_dwordx4 v[158:161], v184, s[84:85]
	s_nop 0
	v_add_u32_e32 v184, 0x8000, v184
	global_load_dwordx4 v[162:165], v184, s[84:85]
	s_nop 0
	v_add_u32_e32 v184, 0x8000, v184
	global_load_dwordx4 v[166:169], v184, s[84:85]
	s_nop 0
	v_add_u32_e32 v184, 0x8000, v184
	global_load_dwordx4 v[170:173], v184, s[84:85]
	s_nop 0
	v_add_u32_e32 v184, 0x8000, v184
	global_load_dwordx4 v[174:177], v184, s[84:85]
	s_nop 0
	v_add_u32_e32 v184, 0x8000, v184
	global_load_dwordx4 v[178:181], v184, s[84:85]
	s_nop 0
	v_add_u32_e32 v184, 0x8000, v184
	global_load_dwordx4 v[186:189], v184, s[84:85]
	s_nop 0
	v_add_u32_e32 v184, 0x8000, v184
	global_load_dwordx4 v[190:193], v184, s[84:85]
	s_nop 0
	v_add_u32_e32 v184, 0x8000, v184
	ds_read_b128 v[194:197], v182 offset:0
	ds_read_b128 v[198:201], v182 offset:4224
	ds_read_b128 v[202:205], v182 offset:8448
	ds_read_b128 v[210:213], v182 offset:12672
	s_waitcnt vmcnt(7) lgkmcnt(3)
	v_fma_f32 v158, v154, v194, v158
	v_fma_f32 v159, v130, v195, v159
	v_fma_f32 v160, v156, v196, v160
	v_fma_f32 v161, v132, v197, v161
	global_store_dwordx4 v214, v[158:161], s[0:1]
	s_nop 1
	v_add_u32_e32 v214, 0x8000, v214
	s_waitcnt vmcnt(7) lgkmcnt(2)
	v_fma_f32 v162, v154, v198, v162
	v_fma_f32 v163, v130, v199, v163
	v_fma_f32 v164, v156, v200, v164
	v_fma_f32 v165, v132, v201, v165
	global_store_dwordx4 v214, v[162:165], s[0:1]
	s_nop 1
	v_add_u32_e32 v214, 0x8000, v214
	s_waitcnt vmcnt(7) lgkmcnt(1)
	v_fma_f32 v166, v154, v202, v166
	v_fma_f32 v167, v130, v203, v167
	v_fma_f32 v168, v156, v204, v168
	v_fma_f32 v169, v132, v205, v169
	global_store_dwordx4 v214, v[166:169], s[0:1]
	s_nop 1
	v_add_u32_e32 v214, 0x8000, v214
	s_waitcnt vmcnt(7) lgkmcnt(0)
	v_fma_f32 v170, v154, v210, v170
	v_fma_f32 v171, v130, v211, v171
	v_fma_f32 v172, v156, v212, v172
	v_fma_f32 v173, v132, v213, v173
	global_store_dwordx4 v214, v[170:173], s[0:1]
	s_nop 1
	v_add_u32_e32 v214, 0x8000, v214
	ds_read_b128 v[194:197], v182 offset:16896
	ds_read_b128 v[198:201], v182 offset:21120
	ds_read_b128 v[202:205], v182 offset:25344
	ds_read_b128 v[210:213], v182 offset:29568
	s_waitcnt vmcnt(7) lgkmcnt(3)
	v_fma_f32 v174, v154, v194, v174
	v_fma_f32 v175, v130, v195, v175
	v_fma_f32 v176, v156, v196, v176
	v_fma_f32 v177, v132, v197, v177
	global_store_dwordx4 v214, v[174:177], s[0:1]
	s_nop 1
	v_add_u32_e32 v214, 0x8000, v214
	s_waitcnt vmcnt(7) lgkmcnt(2)
	v_fma_f32 v178, v154, v198, v178
	v_fma_f32 v179, v130, v199, v179
	v_fma_f32 v180, v156, v200, v180
	v_fma_f32 v181, v132, v201, v181
	global_store_dwordx4 v214, v[178:181], s[0:1]
	s_nop 1
	v_add_u32_e32 v214, 0x8000, v214
	s_waitcnt vmcnt(7) lgkmcnt(1)
	v_fma_f32 v186, v154, v202, v186
	v_fma_f32 v187, v130, v203, v187
	v_fma_f32 v188, v156, v204, v188
	v_fma_f32 v189, v132, v205, v189
	global_store_dwordx4 v214, v[186:189], s[0:1]
	s_nop 1
	v_add_u32_e32 v214, 0x8000, v214
	s_waitcnt vmcnt(7) lgkmcnt(0)
	v_fma_f32 v190, v154, v210, v190
	v_fma_f32 v191, v130, v211, v191
	v_fma_f32 v192, v156, v212, v192
	v_fma_f32 v193, v132, v213, v193
	global_store_dwordx4 v214, v[190:193], s[0:1]
	s_nop 1
	v_add_u32_e32 v214, 0x8000, v214
	global_load_dwordx4 v[158:161], v184, s[84:85]
	s_nop 0
	v_add_u32_e32 v184, 0x8000, v184
	global_load_dwordx4 v[162:165], v184, s[84:85]
	s_nop 0
	v_add_u32_e32 v184, 0x8000, v184
	global_load_dwordx4 v[166:169], v184, s[84:85]
	s_nop 0
	v_add_u32_e32 v184, 0x8000, v184
	global_load_dwordx4 v[170:173], v184, s[84:85]
	s_nop 0
	v_add_u32_e32 v184, 0x8000, v184
	global_load_dwordx4 v[174:177], v184, s[84:85]
	s_nop 0
	v_add_u32_e32 v184, 0x8000, v184
	global_load_dwordx4 v[178:181], v184, s[84:85]
	s_nop 0
	v_add_u32_e32 v184, 0x8000, v184
	global_load_dwordx4 v[186:189], v184, s[84:85]
	s_nop 0
	v_add_u32_e32 v184, 0x8000, v184
	global_load_dwordx4 v[190:193], v184, s[84:85]
	s_nop 0
	v_add_u32_e32 v184, 0x8000, v184
	ds_read_b128 v[194:197], v182 offset:33792
	ds_read_b128 v[198:201], v182 offset:38016
	ds_read_b128 v[202:205], v182 offset:42240
	ds_read_b128 v[210:213], v182 offset:46464
	s_waitcnt vmcnt(7) lgkmcnt(3)
	v_fma_f32 v158, v154, v194, v158
	v_fma_f32 v159, v130, v195, v159
	v_fma_f32 v160, v156, v196, v160
	v_fma_f32 v161, v132, v197, v161
	global_store_dwordx4 v214, v[158:161], s[0:1]
	s_nop 1
	v_add_u32_e32 v214, 0x8000, v214
	s_waitcnt vmcnt(7) lgkmcnt(2)
	v_fma_f32 v162, v154, v198, v162
	v_fma_f32 v163, v130, v199, v163
	v_fma_f32 v164, v156, v200, v164
	v_fma_f32 v165, v132, v201, v165
	global_store_dwordx4 v214, v[162:165], s[0:1]
	s_nop 1
	v_add_u32_e32 v214, 0x8000, v214
	s_waitcnt vmcnt(7) lgkmcnt(1)
	v_fma_f32 v166, v154, v202, v166
	v_fma_f32 v167, v130, v203, v167
	v_fma_f32 v168, v156, v204, v168
	v_fma_f32 v169, v132, v205, v169
	global_store_dwordx4 v214, v[166:169], s[0:1]
	s_nop 1
	v_add_u32_e32 v214, 0x8000, v214
	s_waitcnt vmcnt(7) lgkmcnt(0)
	v_fma_f32 v170, v154, v210, v170
	v_fma_f32 v171, v130, v211, v171
	v_fma_f32 v172, v156, v212, v172
	v_fma_f32 v173, v132, v213, v173
	global_store_dwordx4 v214, v[170:173], s[0:1]
	s_nop 1
	v_add_u32_e32 v214, 0x8000, v214
	ds_read_b128 v[194:197], v182 offset:50688
	ds_read_b128 v[198:201], v182 offset:54912
	ds_read_b128 v[202:205], v182 offset:59136
	ds_read_b128 v[210:213], v182 offset:63360
	s_waitcnt vmcnt(7) lgkmcnt(3)
	v_fma_f32 v174, v154, v194, v174
	v_fma_f32 v175, v130, v195, v175
	v_fma_f32 v176, v156, v196, v176
	v_fma_f32 v177, v132, v197, v177
	global_store_dwordx4 v214, v[174:177], s[0:1]
	s_nop 1
	v_add_u32_e32 v214, 0x8000, v214
	s_waitcnt vmcnt(7) lgkmcnt(2)
	v_fma_f32 v178, v154, v198, v178
	v_fma_f32 v179, v130, v199, v179
	v_fma_f32 v180, v156, v200, v180
	v_fma_f32 v181, v132, v201, v181
	global_store_dwordx4 v214, v[178:181], s[0:1]
	s_nop 1
	v_add_u32_e32 v214, 0x8000, v214
	s_waitcnt vmcnt(7) lgkmcnt(1)
	v_fma_f32 v186, v154, v202, v186
	v_fma_f32 v187, v130, v203, v187
	v_fma_f32 v188, v156, v204, v188
	v_fma_f32 v189, v132, v205, v189
	global_store_dwordx4 v214, v[186:189], s[0:1]
	s_nop 1
	v_add_u32_e32 v214, 0x8000, v214
	s_waitcnt vmcnt(7) lgkmcnt(0)
	v_fma_f32 v190, v154, v210, v190
	v_fma_f32 v191, v130, v211, v191
	v_fma_f32 v192, v156, v212, v192
	v_fma_f32 v193, v132, v213, v193
	global_store_dwordx4 v214, v[190:193], s[0:1]
	s_nop 1
	v_add_u32_e32 v214, 0x8000, v214
	v_mov_b32_e32 v130, v216
	s_barrier
; DI int crow(int i, int h) { return (i & 3) + 8 * (i >> 2) + 4 * h; }
; DI void stage_half(float* st, const f32x16 (&acc)[4][2], int h, int tid) {
;   const int lane = tid & 63, w = tid >> 6, wm = w >> 1, wn = w & 1, c = lane & 31, half = lane >> 5;
;   if (wm == h) {
; #pragma unroll
;     for (int mf = 0; mf < 4; ++mf)
; #pragma unroll
;       for (int nf = 0; nf < 2; ++nf)
; #pragma unroll
;         for (int i = 0; i < 16; ++i) st[(mf * 32 + crow(i, half)) * 132 + wn * 64 + nf * 32 + c] = acc[mf][nf][i];
;   }
; }
	s_nop 0
	v_and_b32_e32 v0, 0xffffff80, v130
	v_cmp_eq_u32_e32 vcc, s31, v0
	s_and_saveexec_b64 s[42:43], vcc
	s_cbranch_execz .LBB0_1306
	v_lshrrev_b32_e32 v0, 3, v130
	v_and_b32_e32 v0, 4, v0
	v_and_b32_e32 v131, 0x5f, v130
	v_mul_u32_u24_e32 v0, 0x210, v0
	v_lshl_add_u32 v0, v131, 2, v0
	ds_write2_b32 v0, v114, v98 offset1:32
	ds_write2_b32 v0, v115, v99 offset0:132 offset1:164
	v_add_u32_e32 v98, 0x400, v0
	ds_write2_b32 v98, v116, v100 offset0:8 offset1:40
	ds_write2_b32 v98, v117, v101 offset0:140 offset1:172
	v_add_u32_e32 v98, 0x1000, v0
	ds_write2_b32 v98, v118, v102 offset0:32 offset1:64
	ds_write2_b32 v98, v119, v103 offset0:164 offset1:196
	v_add_u32_e32 v98, 0x1400, v0
	ds_write2_b32 v98, v120, v104 offset0:40 offset1:72
	ds_write2_b32 v98, v121, v105 offset0:172 offset1:204
	v_add_u32_e32 v98, 0x2000, v0
	ds_write2_b32 v98, v122, v106 offset0:64 offset1:96
	ds_write2_b32 v98, v123, v107 offset0:196 offset1:228
	v_add_u32_e32 v98, 0x2400, v0
	ds_write2_b32 v98, v124, v108 offset0:72 offset1:104
	ds_write2_b32 v98, v125, v109 offset0:204 offset1:236
	v_add_u32_e32 v98, 0x3000, v0
	ds_write2_b32 v98, v126, v110 offset0:96 offset1:128
	v_add_u32_e32 v98, 0x3200, v0
	ds_write2_b32 v98, v127, v111 offset0:100 offset1:132
	v_add_u32_e32 v98, 0x3400, v0
	ds_write2_b32 v98, v128, v112 offset0:104 offset1:136
	v_add_u32_e32 v98, 0x3600, v0
	ds_write2_b32 v98, v129, v113 offset0:108 offset1:140
	v_add_u32_e32 v98, 0x4000, v0
	ds_write2_b32 v98, v82, v66 offset0:128 offset1:160
	v_add_u32_e32 v66, 0x4400, v0
	ds_write2_b32 v66, v83, v67 offset0:4 offset1:36
	ds_write2_b32 v66, v84, v68 offset0:136 offset1:168
	v_add_u32_e32 v66, 0x4800, v0
	ds_write2_b32 v66, v85, v69 offset0:12 offset1:44
	v_add_u32_e32 v66, 0x5000, v0
	ds_write2_b32 v66, v86, v70 offset0:160 offset1:192
	v_add_u32_e32 v66, 0x5400, v0
	ds_write2_b32 v66, v87, v71 offset0:36 offset1:68
	ds_write2_b32 v66, v88, v72 offset0:168 offset1:200
	v_add_u32_e32 v66, 0x5800, v0
	ds_write2_b32 v66, v89, v73 offset0:44 offset1:76
	v_add_u32_e32 v66, 0x6000, v0
	ds_write2_b32 v66, v90, v74 offset0:192 offset1:224
	v_add_u32_e32 v66, 0x6400, v0
	ds_write2_b32 v66, v91, v75 offset0:68 offset1:100
	ds_write2_b32 v66, v92, v76 offset0:200 offset1:232
	v_add_u32_e32 v66, 0x6800, v0
	ds_write2_b32 v66, v93, v77 offset0:76 offset1:108
	v_add_u32_e32 v66, 0x7200, v0
	ds_write2_b32 v66, v94, v78 offset0:96 offset1:128
	v_add_u32_e32 v66, 0x7400, v0
	ds_write2_b32 v66, v95, v79 offset0:100 offset1:132
	v_add_u32_e32 v66, 0x7600, v0
	ds_write2_b32 v66, v96, v80 offset0:104 offset1:136
	v_add_u32_e32 v66, 0x7800, v0
	ds_write2_b32 v66, v97, v81 offset0:108 offset1:140
	v_add_u32_e32 v66, 0x8400, v0
	ds_write2_b32 v66, v50, v34 offset1:32
	ds_write2_b32 v66, v51, v35 offset0:132 offset1:164
	v_add_u32_e32 v34, 0x8800, v0
	ds_write2_b32 v34, v52, v36 offset0:8 offset1:40
	ds_write2_b32 v34, v53, v37 offset0:140 offset1:172
	v_add_u32_e32 v34, 0x9400, v0
	ds_write2_b32 v34, v54, v38 offset0:32 offset1:64
	ds_write2_b32 v34, v55, v39 offset0:164 offset1:196
	v_add_u32_e32 v34, 0x9800, v0
	ds_write2_b32 v34, v56, v40 offset0:40 offset1:72
	ds_write2_b32 v34, v57, v41 offset0:172 offset1:204
	v_add_u32_e32 v34, 0xa400, v0
	ds_write2_b32 v34, v58, v42 offset0:64 offset1:96
	ds_write2_b32 v34, v59, v43 offset0:196 offset1:228
	v_add_u32_e32 v34, 0xa800, v0
	ds_write2_b32 v34, v60, v44 offset0:72 offset1:104
	ds_write2_b32 v34, v61, v45 offset0:204 offset1:236
	v_add_u32_e32 v34, 0xb400, v0
	ds_write2_b32 v34, v62, v46 offset0:96 offset1:128
	v_add_u32_e32 v34, 0xb600, v0
	ds_write2_b32 v34, v63, v47 offset0:100 offset1:132
	v_add_u32_e32 v34, 0xb800, v0
	ds_write2_b32 v34, v64, v48 offset0:104 offset1:136
	v_add_u32_e32 v34, 0xba00, v0
	ds_write2_b32 v34, v65, v49 offset0:108 offset1:140
	v_add_u32_e32 v34, 0xc400, v0
	ds_write2_b32 v34, v18, v2 offset0:128 offset1:160
	v_add_u32_e32 v2, 0xc800, v0
	ds_write2_b32 v2, v19, v3 offset0:4 offset1:36
	ds_write2_b32 v2, v20, v4 offset0:136 offset1:168
	v_add_u32_e32 v2, 0xcc00, v0
	ds_write2_b32 v2, v21, v5 offset0:12 offset1:44
	v_add_u32_e32 v2, 0xd400, v0
	ds_write2_b32 v2, v22, v6 offset0:160 offset1:192
	v_add_u32_e32 v2, 0xd800, v0
	ds_write2_b32 v2, v23, v7 offset0:36 offset1:68
	ds_write2_b32 v2, v24, v8 offset0:168 offset1:200
	v_add_u32_e32 v2, 0xdc00, v0
	ds_write2_b32 v2, v25, v9 offset0:44 offset1:76
	v_add_u32_e32 v2, 0xe400, v0
	ds_write2_b32 v2, v26, v10 offset0:192 offset1:224
	v_add_u32_e32 v2, 0xe800, v0
	ds_write2_b32 v2, v27, v11 offset0:68 offset1:100
	ds_write2_b32 v2, v28, v12 offset0:200 offset1:232
	v_add_u32_e32 v2, 0xec00, v0
	ds_write2_b32 v2, v29, v13 offset0:76 offset1:108
	v_add_u32_e32 v2, 0xf600, v0
	ds_write2_b32 v2, v30, v14 offset0:96 offset1:128
	v_add_u32_e32 v2, 0xf800, v0
	ds_write2_b32 v2, v31, v15 offset0:100 offset1:132
	v_add_u32_e32 v2, 0xfa00, v0
	v_add_u32_e32 v0, 0xfc00, v0
	ds_write2_b32 v2, v32, v16 offset0:104 offset1:136
	ds_write2_b32 v0, v33, v17 offset0:108 offset1:140

; DI int otid() { int t = threadIdx.x; asm volatile("" : "+v"(t)); return t; }
; DI void gemm_res_tile_big(const bf16_t* A, int lda, const bf16_t* Bt, int K, const float* __restrict__ xin, float* __restrict__ xout,
;                           const float* __restrict__ gate, int mt, int nt, char* smem) {
;     ...
;     const int tid = otid();
;     stage_half(st, acc, h, tid);
;     __syncthreads();
;     const int r = tid >> 5, ch = tid & 31;
;     const float4 g = *(const float4*)(gate + (size_t)b * 6144 + n0 + ch * 4);
; #pragma unroll 4
;     for (int ps = 0; ps < 16; ++ps) {
;       const int row = ps * 8 + r;
;       const float4 a = *(const float4*)(st + row * 132 + ch * 4);
;       const size_t off = (size_t)(m0 + h * 128 + row) * 1024 + n0 + ch * 4;
;       const float4 xi = *(const float4*)(xin + off);
;       float4 o; o.x = xi.x + g.x * a.x; o.y = xi.y + g.y * a.y; o.z = xi.z + g.z * a.z; o.w = xi.w + g.w * a.w;
;       *(float4*)(xout + off) = o;
;     }
;     __syncthreads();
.LBB0_1307:
	v_lshrrev_b32_e32 v215, 5, v216
	v_mul_u32_u24_e32 v182, 0x210, v215
	v_and_b32_e32 v215, 31, v216
	v_lshl_add_u32 v182, v215, 4, v182
	v_lshlrev_b32_e32 v184, 10, v12
	v_add_u32_e32 v184, v184, v8
	v_lshlrev_b32_e32 v184, 2, v184
	v_mov_b32_e32 v214, v184
	global_load_dwordx4 v[158:161], v184, s[84:85]
	s_nop 0
	v_add_u32_e32 v184, 0x8000, v184
	global_load_dwordx4 v[162:165], v184, s[84:85]
	s_nop 0
	v_add_u32_e32 v184, 0x8000, v184
	global_load_dwordx4 v[166:169], v184, s[84:85]
	s_nop 0
	v_add_u32_e32 v184, 0x8000, v184
	global_load_dwordx4 v[170:173], v184, s[84:85]
	s_nop 0
	v_add_u32_e32 v184, 0x8000, v184
	global_load_dwordx4 v[174:177], v184, s[84:85]
	s_nop 0
	v_add_u32_e32 v184, 0x8000, v184
	global_load_dwordx4 v[178:181], v184, s[84:85]
	s_nop 0
	v_add_u32_e32 v184, 0x8000, v184
	global_load_dwordx4 v[186:189], v184, s[84:85]
	s_nop 0
	v_add_u32_e32 v184, 0x8000, v184
	global_load_dwordx4 v[190:193], v184, s[84:85]
	s_nop 0
	v_add_u32_e32 v184, 0x8000, v184
	ds_read_b128 v[194:197], v182 offset:0
	ds_read_b128 v[198:201], v182 offset:4224
	ds_read_b128 v[202:205], v182 offset:8448
	ds_read_b128 v[210:213], v182 offset:12672
	s_waitcnt vmcnt(7) lgkmcnt(3)
	v_fma_f32 v158, v26, v194, v158
	v_fma_f32 v159, v2, v195, v159
	v_fma_f32 v160, v28, v196, v160
	v_fma_f32 v161, v4, v197, v161
	global_store_dwordx4 v214, v[158:161], s[0:1]
	s_nop 1
	v_add_u32_e32 v214, 0x8000, v214
	s_waitcnt vmcnt(7) lgkmcnt(2)
	v_fma_f32 v162, v26, v198, v162
	v_fma_f32 v163, v2, v199, v163
	v_fma_f32 v164, v28, v200, v164
	v_fma_f32 v165, v4, v201, v165
	global_store_dwordx4 v214, v[162:165], s[0:1]
	s_nop 1
	v_add_u32_e32 v214, 0x8000, v214
	s_waitcnt vmcnt(7) lgkmcnt(1)
	v_fma_f32 v166, v26, v202, v166
	v_fma_f32 v167, v2, v203, v167
	v_fma_f32 v168, v28, v204, v168
	v_fma_f32 v169, v4, v205, v169
	global_store_dwordx4 v214, v[166:169], s[0:1]
	s_nop 1
	v_add_u32_e32 v214, 0x8000, v214
	s_waitcnt vmcnt(7) lgkmcnt(0)
	v_fma_f32 v170, v26, v210, v170
	v_fma_f32 v171, v2, v211, v171
	v_fma_f32 v172, v28, v212, v172
	v_fma_f32 v173, v4, v213, v173
	global_store_dwordx4 v214, v[170:173], s[0:1]
	s_nop 1
	v_add_u32_e32 v214, 0x8000, v214
	ds_read_b128 v[194:197], v182 offset:16896
	ds_read_b128 v[198:201], v182 offset:21120
	ds_read_b128 v[202:205], v182 offset:25344
	ds_read_b128 v[210:213], v182 offset:29568
	s_waitcnt vmcnt(7) lgkmcnt(3)
	v_fma_f32 v174, v26, v194, v174
	v_fma_f32 v175, v2, v195, v175
	v_fma_f32 v176, v28, v196, v176
	v_fma_f32 v177, v4, v197, v177
	global_store_dwordx4 v214, v[174:177], s[0:1]
	s_nop 1
	v_add_u32_e32 v214, 0x8000, v214
	s_waitcnt vmcnt(7) lgkmcnt(2)
	v_fma_f32 v178, v26, v198, v178
	v_fma_f32 v179, v2, v199, v179
	v_fma_f32 v180, v28, v200, v180
	v_fma_f32 v181, v4, v201, v181
	global_store_dwordx4 v214, v[178:181], s[0:1]
	s_nop 1
	v_add_u32_e32 v214, 0x8000, v214
	s_waitcnt vmcnt(7) lgkmcnt(1)
	v_fma_f32 v186, v26, v202, v186
	v_fma_f32 v187, v2, v203, v187
	v_fma_f32 v188, v28, v204, v188
	v_fma_f32 v189, v4, v205, v189
	global_store_dwordx4 v214, v[186:189], s[0:1]
	s_nop 1
	v_add_u32_e32 v214, 0x8000, v214
	s_waitcnt vmcnt(7) lgkmcnt(0)
	v_fma_f32 v190, v26, v210, v190
	v_fma_f32 v191, v2, v211, v191
	v_fma_f32 v192, v28, v212, v192
	v_fma_f32 v193, v4, v213, v193
	global_store_dwordx4 v214, v[190:193], s[0:1]
	s_nop 1
	v_add_u32_e32 v214, 0x8000, v214
	global_load_dwordx4 v[158:161], v184, s[84:85]
	s_nop 0
	v_add_u32_e32 v184, 0x8000, v184
	global_load_dwordx4 v[162:165], v184, s[84:85]
	s_nop 0
	v_add_u32_e32 v184, 0x8000, v184
	global_load_dwordx4 v[166:169], v184, s[84:85]
	s_nop 0
	v_add_u32_e32 v184, 0x8000, v184
	global_load_dwordx4 v[170:173], v184, s[84:85]
	s_nop 0
	v_add_u32_e32 v184, 0x8000, v184
	global_load_dwordx4 v[174:177], v184, s[84:85]
	s_nop 0
	v_add_u32_e32 v184, 0x8000, v184
	global_load_dwordx4 v[178:181], v184, s[84:85]
	s_nop 0
	v_add_u32_e32 v184, 0x8000, v184
	global_load_dwordx4 v[186:189], v184, s[84:85]
	s_nop 0
	v_add_u32_e32 v184, 0x8000, v184
	global_load_dwordx4 v[190:193], v184, s[84:85]
	s_nop 0
	v_add_u32_e32 v184, 0x8000, v184
	ds_read_b128 v[194:197], v182 offset:33792
	ds_read_b128 v[198:201], v182 offset:38016
	ds_read_b128 v[202:205], v182 offset:42240
	ds_read_b128 v[210:213], v182 offset:46464
	s_waitcnt vmcnt(7) lgkmcnt(3)
	v_fma_f32 v158, v26, v194, v158
	v_fma_f32 v159, v2, v195, v159
	v_fma_f32 v160, v28, v196, v160
	v_fma_f32 v161, v4, v197, v161
	global_store_dwordx4 v214, v[158:161], s[0:1]
	s_nop 1
	v_add_u32_e32 v214, 0x8000, v214
	s_waitcnt vmcnt(7) lgkmcnt(2)
	v_fma_f32 v162, v26, v198, v162
	v_fma_f32 v163, v2, v199, v163
	v_fma_f32 v164, v28, v200, v164
	v_fma_f32 v165, v4, v201, v165
	global_store_dwordx4 v214, v[162:165], s[0:1]
	s_nop 1
	v_add_u32_e32 v214, 0x8000, v214
	s_waitcnt vmcnt(7) lgkmcnt(1)
	v_fma_f32 v166, v26, v202, v166
	v_fma_f32 v167, v2, v203, v167
	v_fma_f32 v168, v28, v204, v168
	v_fma_f32 v169, v4, v205, v169
	global_store_dwordx4 v214, v[166:169], s[0:1]
	s_nop 1
	v_add_u32_e32 v214, 0x8000, v214
	s_waitcnt vmcnt(7) lgkmcnt(0)
	v_fma_f32 v170, v26, v210, v170
	v_fma_f32 v171, v2, v211, v171
	v_fma_f32 v172, v28, v212, v172
	v_fma_f32 v173, v4, v213, v173
	global_store_dwordx4 v214, v[170:173], s[0:1]
	s_nop 1
	v_add_u32_e32 v214, 0x8000, v214
	ds_read_b128 v[194:197], v182 offset:50688
	ds_read_b128 v[198:201], v182 offset:54912
	ds_read_b128 v[202:205], v182 offset:59136
	ds_read_b128 v[210:213], v182 offset:63360
	s_waitcnt vmcnt(7) lgkmcnt(3)
	v_fma_f32 v174, v26, v194, v174
	v_fma_f32 v175, v2, v195, v175
	v_fma_f32 v176, v28, v196, v176
	v_fma_f32 v177, v4, v197, v177
	global_store_dwordx4 v214, v[174:177], s[0:1]
	s_nop 1
	v_add_u32_e32 v214, 0x8000, v214
	s_waitcnt vmcnt(7) lgkmcnt(2)
	v_fma_f32 v178, v26, v198, v178
	v_fma_f32 v179, v2, v199, v179
	v_fma_f32 v180, v28, v200, v180
	v_fma_f32 v181, v4, v201, v181
	global_store_dwordx4 v214, v[178:181], s[0:1]
	s_nop 1
	v_add_u32_e32 v214, 0x8000, v214
	s_waitcnt vmcnt(7) lgkmcnt(1)
	v_fma_f32 v186, v26, v202, v186
	v_fma_f32 v187, v2, v203, v187
	v_fma_f32 v188, v28, v204, v188
	v_fma_f32 v189, v4, v205, v189
	global_store_dwordx4 v214, v[186:189], s[0:1]
	s_nop 1
	v_add_u32_e32 v214, 0x8000, v214
	s_waitcnt vmcnt(7) lgkmcnt(0)
	v_fma_f32 v190, v26, v210, v190
	v_fma_f32 v191, v2, v211, v191
	v_fma_f32 v192, v28, v212, v192
	v_fma_f32 v193, v4, v213, v193
	global_store_dwordx4 v214, v[190:193], s[0:1]
	s_nop 1
	v_add_u32_e32 v214, 0x8000, v214
	s_barrier
	s_branch .LBB0_1296

; __global__ void __launch_bounds__(256, 2) fwd_megakernel(Params p) {
;   __shared__ __attribute__((aligned(16))) char smem[SMEM_BYTES];
	.amdhsa_kernel _Z14fwd_megakernel6Params
		.amdhsa_group_segment_fixed_size 73748
		.amdhsa_private_segment_fixed_size 0
		.amdhsa_kernarg_size 448
		.amdhsa_user_sgpr_count 2
		.amdhsa_user_sgpr_dispatch_ptr 0
		.amdhsa_user_sgpr_queue_ptr 0
		.amdhsa_user_sgpr_kernarg_segment_ptr 1
		.amdhsa_user_sgpr_dispatch_id 0
		.amdhsa_user_sgpr_kernarg_preload_length 0
		.amdhsa_user_sgpr_kernarg_preload_offset 0
		.amdhsa_user_sgpr_private_segment_size 0
		.amdhsa_uses_dynamic_stack 0
		.amdhsa_enable_private_segment 0
		.amdhsa_system_sgpr_workgroup_id_x 1
		.amdhsa_system_sgpr_workgroup_id_y 0
		.amdhsa_system_sgpr_workgroup_id_z 0
		.amdhsa_system_sgpr_workgroup_info 0
		.amdhsa_system_vgpr_workitem_id 2
		.amdhsa_next_free_vgpr 247
		.amdhsa_next_free_sgpr 100
		.amdhsa_accum_offset 248
		.amdhsa_reserve_vcc 1
		.amdhsa_float_round_mode_32 0
		.amdhsa_float_round_mode_16_64 0
		.amdhsa_float_denorm_mode_32 3
		.amdhsa_float_denorm_mode_16_64 3
		.amdhsa_dx10_clamp 1
		.amdhsa_ieee_mode 1
		.amdhsa_fp16_overflow 0
		.amdhsa_tg_split 0
		.amdhsa_exception_fp_ieee_invalid_op 0
		.amdhsa_exception_fp_denorm_src 0
		.amdhsa_exception_fp_ieee_div_zero 0
		.amdhsa_exception_fp_ieee_overflow 0
		.amdhsa_exception_fp_ieee_underflow 0
		.amdhsa_exception_fp_ieee_inexact 0
		.amdhsa_exception_int_div_zero 0
	.end_amdhsa_kernel

; __global__ void __launch_bounds__(256, 2) fwd_megakernel(Params p) {
.Lfunc_end0:
	.size	_Z14fwd_megakernel6Params, .Lfunc_end0-_Z14fwd_megakernel6Params
	.set _Z14fwd_megakernel6Params.num_vgpr, 247
	.set _Z14fwd_megakernel6Params.num_agpr, 0
	.set _Z14fwd_megakernel6Params.numbered_sgpr, 100
	.set _Z14fwd_megakernel6Params.num_named_barrier, 0
	.set _Z14fwd_megakernel6Params.private_seg_size, 0
	.set _Z14fwd_megakernel6Params.uses_vcc, 1
	.set _Z14fwd_megakernel6Params.uses_flat_scratch, 0
	.set _Z14fwd_megakernel6Params.has_dyn_sized_stack, 0
	.set _Z14fwd_megakernel6Params.has_recursion, 0
	.set _Z14fwd_megakernel6Params.has_indirect_call, 0

; __global__ void __launch_bounds__(256, 2) fwd_megakernel(Params p) {
;   __shared__ __attribute__((aligned(16))) char smem[SMEM_BYTES];
amdhsa.kernels:
  - .agpr_count:     0
    .args:
      - .offset:         0
        .size:           192
        .value_kind:     by_value
      - .offset:         192
        .size:           4
        .value_kind:     hidden_block_count_x
      - .offset:         196
        .size:           4
        .value_kind:     hidden_block_count_y
      - .offset:         200
        .size:           4
        .value_kind:     hidden_block_count_z
      - .offset:         204
        .size:           2
        .value_kind:     hidden_group_size_x
      - .offset:         206
        .size:           2
        .value_kind:     hidden_group_size_y
      - .offset:         208
        .size:           2
        .value_kind:     hidden_group_size_z
      - .offset:         210
        .size:           2
        .value_kind:     hidden_remainder_x
      - .offset:         212
        .size:           2
        .value_kind:     hidden_remainder_y
      - .offset:         214
        .size:           2
        .value_kind:     hidden_remainder_z
      - .offset:         232
        .size:           8
        .value_kind:     hidden_global_offset_x
      - .offset:         240
        .size:           8
        .value_kind:     hidden_global_offset_y
      - .offset:         248
        .size:           8
        .value_kind:     hidden_global_offset_z
      - .offset:         256
        .size:           2
        .value_kind:     hidden_grid_dims
      - .offset:         280
        .size:           8
        .value_kind:     hidden_multigrid_sync_arg
    .group_segment_fixed_size: 73748
    .kernarg_segment_align: 8
    .kernarg_segment_size: 448
    .language:       OpenCL C
    .language_version:
      - 2
      - 0
    .max_flat_workgroup_size: 256
    .name:           _Z14fwd_megakernel6Params
    .private_segment_fixed_size: 0
    .sgpr_count:     106
    .sgpr_spill_count: 305
    .symbol:         _Z14fwd_megakernel6Params.kd
    .uniform_work_group_size: 1
    .uses_dynamic_stack: false
    .vgpr_count:     247
    .vgpr_spill_count: 0
    .wavefront_size: 64
